# c5 + static s_setprio 1 for waves 4-7 around GEMM main loops
# baseline (speedup 1.0000x reference)
; #define PG8_STAGE(bufoff, gbase, voff) do { _Pragma("unroll") for (int _i = 0; _i < 2; ++_i) \
;         __builtin_amdgcn_global_load_lds((const unsigned*)((const char*)(gbase) + (voff)[_i]), (LAS unsigned*)(lds + (bufoff) + ldsw + _i * 8192), 16, 0, 0); } while (0)
; #define PG8_LDA(dst, b, h) do { _Pragma("unroll") for (int m = 0; m < 4; ++m) _Pragma("unroll") for (int k = 0; k < 2; ++k) dst[m][k] = *(const LAS bf16x8*)(lds + PG8_SA(b, h) + aoff + m * 2048 + k * 1024); } while (0)
; #define PG8_LDB(dst, b, h) do { _Pragma("unroll") for (int n = 0; n < 2; ++n) _Pragma("unroll") for (int k = 0; k < 2; ++k) dst[n][k] = *(const LAS bf16x8*)(lds + PG8_SB(b, h) + boff + n * 2048 + k * 1024); } while (0)
; #define PG8_MMA(ai, bj, At, Bt) do { __builtin_amdgcn_s_setprio(1); _Pragma("unroll") for (int m = 0; m < 4; ++m) _Pragma("unroll") for (int n = 0; n < 2; ++n) _Pragma("unroll") for (int k = 0; k < 2; ++k) \
;         acc[ai][bj][m][n] = __builtin_amdgcn_mfma_f32_16x16x32_bf16(Bt[n][k], At[m][k], acc[ai][bj][m][n], 0, 0, 0); __builtin_amdgcn_s_setprio(0); } while (0)
; #define PG8_WAIT_V(n) asm volatile("s_waitcnt vmcnt(" #n ")" ::: "memory")
; #define PG8_WAIT_L(n) asm volatile("s_waitcnt lgkmcnt(" #n ")" ::: "memory")
; #define PG8_BAR __builtin_amdgcn_s_barrier()
; template <class Epi, class Sched>
; __device__ __forceinline__ void gemm_phase(LAS unsigned char* lds, const Gemm g, const Sched& S, const Epi& E, const int tid) {
;     ...
;         for (int t = 0; t < nt; t += 2) {
;             const bool last = (t == nt - 2);
;             const char* a1 = cA + (size_t)(t + 1) * kstep;
;             const char* a2 = last ? nA : cA + (size_t)(t + 2) * kstep; const char* b2 = last ? nB : cB + (size_t)(t + 2) * kstep;
;             const char* a3 = a2 + kstep; const char* b3 = b2 + kstep;
;             PG8_LDB(B0, 0, 0); PG8_LDB(B1, 0, 1); PG8_SCHED; PG8_LDA(At, 0, 0); PG8_STAGE(PG8_SA(1, 1), a1 + hstepA, voffA);
;             PG8_WAIT_V(8); PG8_WAIT_L(0); PG8_BAR; PG8_MMA(0, 0, At, B0); PG8_MMA(0, 1, At, B1); PG8_BAR; PG8_SCHED;
;     ...
; #pragma unroll
;         for (int a = 0; a < 2; ++a)
; #pragma unroll
;             for (int b = 0; b < 2; ++b)
; #pragma unroll
;                 for (int m = 0; m < 4; ++m)
; #pragma unroll
;                     for (int n = 0; n < 2; ++n) acc[a][b][m][n] = (f32x4){0.f, 0.f, 0.f, 0.f};
;         cur = nxt; cA = nA; cB = nB; ++ui;
.LBB0_181:
	s_add_u32 s16, s86, 0x100
	v_mov_b32_e32 v4, 0
	s_addc_u32 s17, s87, 0
	s_mov_b32 s12, -2
	v_mov_b32_e32 v5, v4
	v_mov_b32_e32 v6, v4
	v_mov_b32_e32 v7, v4
	v_mov_b32_e32 v36, v4
	v_mov_b32_e32 v37, v4
	v_mov_b32_e32 v38, v4
	v_mov_b32_e32 v39, v4
	v_mov_b32_e32 v8, v4
	v_mov_b32_e32 v9, v4
	v_mov_b32_e32 v10, v4
	v_mov_b32_e32 v11, v4
	v_mov_b32_e32 v40, v4
	v_mov_b32_e32 v41, v4
	v_mov_b32_e32 v42, v4
	v_mov_b32_e32 v43, v4
	v_mov_b32_e32 v12, v4
	v_mov_b32_e32 v13, v4
	v_mov_b32_e32 v14, v4
	v_mov_b32_e32 v15, v4
	v_mov_b32_e32 v44, v4
	v_mov_b32_e32 v45, v4
	v_mov_b32_e32 v46, v4
	v_mov_b32_e32 v47, v4
	v_mov_b32_e32 v16, v4
	v_mov_b32_e32 v17, v4
	v_mov_b32_e32 v18, v4
	v_mov_b32_e32 v19, v4
	v_mov_b32_e32 v48, v4
	v_mov_b32_e32 v49, v4
	v_mov_b32_e32 v50, v4
	v_mov_b32_e32 v51, v4
	v_mov_b32_e32 v68, v4
	v_mov_b32_e32 v69, v4
	v_mov_b32_e32 v70, v4
	v_mov_b32_e32 v71, v4
	v_mov_b32_e32 v100, v4
	v_mov_b32_e32 v101, v4
	v_mov_b32_e32 v102, v4
	v_mov_b32_e32 v103, v4
	v_mov_b32_e32 v72, v4
	v_mov_b32_e32 v73, v4
	v_mov_b32_e32 v74, v4
	v_mov_b32_e32 v75, v4
	v_mov_b32_e32 v104, v4
	v_mov_b32_e32 v105, v4
	v_mov_b32_e32 v106, v4
	v_mov_b32_e32 v107, v4
	v_mov_b32_e32 v76, v4
	v_mov_b32_e32 v77, v4
	v_mov_b32_e32 v78, v4
	v_mov_b32_e32 v79, v4
	v_mov_b32_e32 v108, v4
	v_mov_b32_e32 v109, v4
	v_mov_b32_e32 v110, v4
	v_mov_b32_e32 v111, v4
	v_mov_b32_e32 v80, v4
	v_mov_b32_e32 v81, v4
	v_mov_b32_e32 v82, v4
	v_mov_b32_e32 v83, v4
	v_mov_b32_e32 v112, v4
	v_mov_b32_e32 v113, v4
	v_mov_b32_e32 v114, v4
	v_mov_b32_e32 v115, v4
	v_mov_b32_e32 v20, v4
	v_mov_b32_e32 v21, v4
	v_mov_b32_e32 v22, v4
	v_mov_b32_e32 v23, v4
	v_mov_b32_e32 v52, v4
	v_mov_b32_e32 v53, v4
	v_mov_b32_e32 v54, v4
	v_mov_b32_e32 v55, v4
	v_mov_b32_e32 v24, v4
	v_mov_b32_e32 v25, v4
	v_mov_b32_e32 v26, v4
	v_mov_b32_e32 v27, v4
	v_mov_b32_e32 v56, v4
	v_mov_b32_e32 v57, v4
	v_mov_b32_e32 v58, v4
	v_mov_b32_e32 v59, v4
	v_mov_b32_e32 v28, v4
	v_mov_b32_e32 v29, v4
	v_mov_b32_e32 v30, v4
	v_mov_b32_e32 v31, v4
	v_mov_b32_e32 v60, v4
	v_mov_b32_e32 v61, v4
	v_mov_b32_e32 v62, v4
	v_mov_b32_e32 v63, v4
	v_mov_b32_e32 v32, v4
	v_mov_b32_e32 v33, v4
	v_mov_b32_e32 v34, v4
	v_mov_b32_e32 v35, v4
	v_mov_b32_e32 v64, v4
	v_mov_b32_e32 v65, v4
	v_mov_b32_e32 v66, v4
	v_mov_b32_e32 v67, v4
	v_mov_b32_e32 v84, v4
	v_mov_b32_e32 v85, v4
	v_mov_b32_e32 v86, v4
	v_mov_b32_e32 v87, v4
	v_mov_b32_e32 v116, v4
	v_mov_b32_e32 v117, v4
	v_mov_b32_e32 v118, v4
	v_mov_b32_e32 v119, v4
	v_mov_b32_e32 v88, v4
	v_mov_b32_e32 v89, v4
	v_mov_b32_e32 v90, v4
	v_mov_b32_e32 v91, v4
	v_mov_b32_e32 v120, v4
	v_mov_b32_e32 v121, v4
	v_mov_b32_e32 v122, v4
	v_mov_b32_e32 v123, v4
	v_mov_b32_e32 v92, v4
	v_mov_b32_e32 v93, v4
	v_mov_b32_e32 v94, v4
	v_mov_b32_e32 v95, v4
	v_mov_b32_e32 v124, v4
	v_mov_b32_e32 v125, v4
	v_mov_b32_e32 v126, v4
	v_mov_b32_e32 v127, v4
	v_mov_b32_e32 v96, v4
	v_mov_b32_e32 v97, v4
	v_mov_b32_e32 v98, v4
	v_mov_b32_e32 v99, v4
	v_mov_b32_e32 v128, v4
	v_mov_b32_e32 v129, v4
	v_mov_b32_e32 v130, v4
	v_mov_b32_e32 v131, v4
	s_cselect_b32 s99, 1, 0
	v_readfirstlane_b32 s98, v173
	s_nop 0
	s_cmpk_lt_u32 s98, 0x100
	s_cbranch_scc1 .Lprio_skip_LBB0182
	s_setprio 1
.Lprio_skip_LBB0182:
	s_cmp_lg_u32 s99, 0
	.p2align	6
.LBB0_182:
	s_add_u32 s86, s54, 0x100
	s_addc_u32 s87, s55, 0
	s_add_i32 s13, 0, 0x10000
	s_cmpk_eq_i32 s12, 0x5c
	s_cselect_b32 s91, s9, s87
	s_cselect_b32 s90, s8, s86
	s_cselect_b32 s89, s47, s17
	s_cselect_b32 s88, s46, s16
	s_add_i32 s74, 0, 0x14000
	v_add_u32_e32 v150, s13, v204
	v_add_u32_e32 v162, s74, v204
	ds_read_b128 v[138:141], v150
	ds_read_b128 v[142:145], v150 offset:1024
	ds_read_b128 v[146:149], v150 offset:2048
	ds_read_b128 v[150:153], v150 offset:3072
	ds_read_b128 v[154:157], v162
	ds_read_b128 v[158:161], v162 offset:1024
	ds_read_b128 v[174:177], v162 offset:2048
	ds_read_b128 v[178:181], v162 offset:3072
	v_lshl_add_u64 v[162:163], s[54:55], 0, v[134:135]
	s_add_i32 m0, s84, 0xc000
	ds_read_b128 v[182:185], v206
	ds_read_b128 v[186:189], v206 offset:1024
	ds_read_b128 v[190:193], v206 offset:2048
	ds_read_b128 v[194:197], v206 offset:3072
	ds_read_b128 v[198:201], v206 offset:4096
	ds_read_b128 v[210:213], v206 offset:5120
	ds_read_b128 v[220:223], v206 offset:6144
	ds_read_b128 v[234:237], v206 offset:7168
	global_load_lds_dwordx4 v[162:163], off
	v_lshl_add_u64 v[162:163], s[54:55], 0, v[136:137]
	s_add_i32 m0, s84, 0xe000
	s_nop 0
	global_load_lds_dwordx4 v[162:163], off
	s_waitcnt vmcnt(8)
	s_waitcnt lgkmcnt(0)
	s_barrier
; #define PG8_STAGE(bufoff, gbase, voff) do { _Pragma("unroll") for (int _i = 0; _i < 2; ++_i) \
;         __builtin_amdgcn_global_load_lds((const unsigned*)((const char*)(gbase) + (voff)[_i]), (LAS unsigned*)(lds + (bufoff) + ldsw + _i * 8192), 16, 0, 0); } while (0)
; #define PG8_LDA(dst, b, h) do { _Pragma("unroll") for (int m = 0; m < 4; ++m) _Pragma("unroll") for (int k = 0; k < 2; ++k) dst[m][k] = *(const LAS bf16x8*)(lds + PG8_SA(b, h) + aoff + m * 2048 + k * 1024); } while (0)
; #define PG8_MMA(ai, bj, At, Bt) do { __builtin_amdgcn_s_setprio(1); _Pragma("unroll") for (int m = 0; m < 4; ++m) _Pragma("unroll") for (int n = 0; n < 2; ++n) _Pragma("unroll") for (int k = 0; k < 2; ++k) \
;         acc[ai][bj][m][n] = __builtin_amdgcn_mfma_f32_16x16x32_bf16(Bt[n][k], At[m][k], acc[ai][bj][m][n], 0, 0, 0); __builtin_amdgcn_s_setprio(0); } while (0)
; #define PG8_WAIT_V(n) asm volatile("s_waitcnt vmcnt(" #n ")" ::: "memory")
; #define PG8_WAIT_L(n) asm volatile("s_waitcnt lgkmcnt(" #n ")" ::: "memory")
; #define PG8_BAR __builtin_amdgcn_s_barrier()
; #define PG8_SCHED __builtin_amdgcn_sched_barrier(0)
; template <class Epi, class Sched>
; __device__ __forceinline__ void gemm_phase(LAS unsigned char* lds, const Gemm g, const Sched& S, const Epi& E, const int tid) {
;     ...
;             PG8_WAIT_V(8); PG8_WAIT_L(0); PG8_BAR; PG8_MMA(0, 0, At, B0); PG8_MMA(0, 1, At, B1); PG8_BAR; PG8_SCHED;
;             PG8_LDA(At, 0, 1); PG8_STAGE(PG8_SB(0, 0), b2, voffB); PG8_STAGE(PG8_SB(0, 1), b2 + hstepB, voffB); PG8_STAGE(PG8_SA(0, 0), a2, voffA);
;             PG8_WAIT_V(8); PG8_WAIT_L(0); PG8_BAR; PG8_MMA(1, 0, At, B0); PG8_MMA(1, 1, At, B1); PG8_BAR; PG8_SCHED;
	s_waitcnt lgkmcnt(0)
	v_mfma_f32_16x16x32_bf16 v[128:131], v[138:141], v[182:185], v[128:131]
	v_mfma_f32_16x16x32_bf16 v[96:99], v[146:149], v[182:185], v[96:99]
	v_mfma_f32_16x16x32_bf16 v[124:127], v[138:141], v[190:193], v[124:127]
	v_mfma_f32_16x16x32_bf16 v[92:95], v[146:149], v[190:193], v[92:95]
	v_mfma_f32_16x16x32_bf16 v[120:123], v[138:141], v[198:201], v[120:123]
	v_mfma_f32_16x16x32_bf16 v[88:91], v[146:149], v[198:201], v[88:91]
	v_mfma_f32_16x16x32_bf16 v[116:119], v[138:141], v[220:223], v[116:119]
	v_mfma_f32_16x16x32_bf16 v[84:87], v[146:149], v[220:223], v[84:87]
	v_mfma_f32_16x16x32_bf16 v[128:131], v[142:145], v[186:189], v[128:131]
	v_mfma_f32_16x16x32_bf16 v[96:99], v[150:153], v[186:189], v[96:99]
	v_mfma_f32_16x16x32_bf16 v[124:127], v[142:145], v[194:197], v[124:127]
	v_mfma_f32_16x16x32_bf16 v[92:95], v[150:153], v[194:197], v[92:95]
	v_mfma_f32_16x16x32_bf16 v[120:123], v[142:145], v[210:213], v[120:123]
	v_mfma_f32_16x16x32_bf16 v[88:91], v[150:153], v[210:213], v[88:91]
	v_mfma_f32_16x16x32_bf16 v[116:119], v[142:145], v[234:237], v[116:119]
	v_mfma_f32_16x16x32_bf16 v[84:87], v[150:153], v[234:237], v[84:87]
	v_mfma_f32_16x16x32_bf16 v[64:67], v[154:157], v[182:185], v[64:67]
	v_mfma_f32_16x16x32_bf16 v[32:35], v[174:177], v[182:185], v[32:35]
	v_mfma_f32_16x16x32_bf16 v[60:63], v[154:157], v[190:193], v[60:63]
	v_mfma_f32_16x16x32_bf16 v[28:31], v[174:177], v[190:193], v[28:31]
	v_mfma_f32_16x16x32_bf16 v[56:59], v[154:157], v[198:201], v[56:59]
	v_mfma_f32_16x16x32_bf16 v[24:27], v[174:177], v[198:201], v[24:27]
	v_mfma_f32_16x16x32_bf16 v[52:55], v[154:157], v[220:223], v[52:55]
	v_mfma_f32_16x16x32_bf16 v[20:23], v[174:177], v[220:223], v[20:23]
	v_mfma_f32_16x16x32_bf16 v[64:67], v[158:161], v[186:189], v[64:67]
	v_mfma_f32_16x16x32_bf16 v[32:35], v[178:181], v[186:189], v[32:35]
	v_mfma_f32_16x16x32_bf16 v[60:63], v[158:161], v[194:197], v[60:63]
	v_mfma_f32_16x16x32_bf16 v[28:31], v[178:181], v[194:197], v[28:31]
	v_mfma_f32_16x16x32_bf16 v[56:59], v[158:161], v[210:213], v[56:59]
	v_mfma_f32_16x16x32_bf16 v[24:27], v[178:181], v[210:213], v[24:27]
	v_mfma_f32_16x16x32_bf16 v[52:55], v[158:161], v[234:237], v[52:55]
	v_mfma_f32_16x16x32_bf16 v[20:23], v[178:181], v[234:237], v[20:23]
	s_barrier
	s_add_i32 s13, s13, s79
	v_lshl_add_u64 v[162:163], s[88:89], 0, v[164:165]
	s_mov_b32 m0, s13
	ds_read_b128 v[182:185], v206 offset:16384
	ds_read_b128 v[186:189], v206 offset:17408
	ds_read_b128 v[190:193], v206 offset:18432
	ds_read_b128 v[194:197], v206 offset:19456
	ds_read_b128 v[198:201], v206 offset:20480
	ds_read_b128 v[210:213], v206 offset:21504
	ds_read_b128 v[220:223], v206 offset:22528
	ds_read_b128 v[234:237], v206 offset:23552
	global_load_lds_dwordx4 v[162:163], off
	s_add_i32 m0, s13, 0x2000
	s_add_u32 s54, s88, 0x180000
	v_lshl_add_u64 v[202:203], s[88:89], 0, v[132:133]
	s_addc_u32 s55, s89, 0
	s_add_i32 s13, s74, s79
	global_load_lds_dwordx4 v[202:203], off
	v_lshl_add_u64 v[224:225], s[54:55], 0, v[164:165]
	s_mov_b32 m0, s13
	v_lshl_add_u64 v[226:227], s[90:91], 0, v[132:133]
	global_load_lds_dwordx4 v[224:225], off
	v_lshl_add_u64 v[224:225], s[54:55], 0, v[132:133]
	s_add_i32 m0, s13, 0x2000
	s_nop 0
	global_load_lds_dwordx4 v[224:225], off
	v_lshl_add_u64 v[224:225], s[90:91], 0, v[164:165]
	s_mov_b32 m0, s84
	s_nop 0
	global_load_lds_dwordx4 v[224:225], off
	s_mov_b32 m0, s85
	s_nop 0
	global_load_lds_dwordx4 v[226:227], off
	s_waitcnt vmcnt(8)
	s_waitcnt lgkmcnt(0)
	s_barrier
	s_waitcnt lgkmcnt(0)
	v_mfma_f32_16x16x32_bf16 v[112:115], v[138:141], v[182:185], v[112:115]
	v_mfma_f32_16x16x32_bf16 v[80:83], v[146:149], v[182:185], v[80:83]
	v_mfma_f32_16x16x32_bf16 v[108:111], v[138:141], v[190:193], v[108:111]
	v_mfma_f32_16x16x32_bf16 v[76:79], v[146:149], v[190:193], v[76:79]
	v_mfma_f32_16x16x32_bf16 v[104:107], v[138:141], v[198:201], v[104:107]
	v_mfma_f32_16x16x32_bf16 v[72:75], v[146:149], v[198:201], v[72:75]
	v_mfma_f32_16x16x32_bf16 v[100:103], v[138:141], v[220:223], v[100:103]
	v_mfma_f32_16x16x32_bf16 v[68:71], v[146:149], v[220:223], v[68:71]
	v_mfma_f32_16x16x32_bf16 v[112:115], v[142:145], v[186:189], v[112:115]
	v_mfma_f32_16x16x32_bf16 v[80:83], v[150:153], v[186:189], v[80:83]
	v_mfma_f32_16x16x32_bf16 v[108:111], v[142:145], v[194:197], v[108:111]
	v_mfma_f32_16x16x32_bf16 v[76:79], v[150:153], v[194:197], v[76:79]
	v_mfma_f32_16x16x32_bf16 v[104:107], v[142:145], v[210:213], v[104:107]
	v_mfma_f32_16x16x32_bf16 v[72:75], v[150:153], v[210:213], v[72:75]
	v_mfma_f32_16x16x32_bf16 v[100:103], v[142:145], v[234:237], v[100:103]
	v_mfma_f32_16x16x32_bf16 v[68:71], v[150:153], v[234:237], v[68:71]
	v_mfma_f32_16x16x32_bf16 v[48:51], v[154:157], v[182:185], v[48:51]
	v_mfma_f32_16x16x32_bf16 v[16:19], v[174:177], v[182:185], v[16:19]
	v_mfma_f32_16x16x32_bf16 v[44:47], v[154:157], v[190:193], v[44:47]
	v_mfma_f32_16x16x32_bf16 v[12:15], v[174:177], v[190:193], v[12:15]
	v_mfma_f32_16x16x32_bf16 v[40:43], v[154:157], v[198:201], v[40:43]
	v_mfma_f32_16x16x32_bf16 v[8:11], v[174:177], v[198:201], v[8:11]
	v_mfma_f32_16x16x32_bf16 v[36:39], v[154:157], v[220:223], v[36:39]
	v_mfma_f32_16x16x32_bf16 v[4:7], v[174:177], v[220:223], v[4:7]
	v_mfma_f32_16x16x32_bf16 v[48:51], v[158:161], v[186:189], v[48:51]
	v_mfma_f32_16x16x32_bf16 v[16:19], v[178:181], v[186:189], v[16:19]
	v_mfma_f32_16x16x32_bf16 v[44:47], v[158:161], v[194:197], v[44:47]
	v_mfma_f32_16x16x32_bf16 v[12:15], v[178:181], v[194:197], v[12:15]
	v_mfma_f32_16x16x32_bf16 v[40:43], v[158:161], v[210:213], v[40:43]
	v_mfma_f32_16x16x32_bf16 v[8:11], v[178:181], v[210:213], v[8:11]
	v_mfma_f32_16x16x32_bf16 v[36:39], v[158:161], v[234:237], v[36:39]
	v_mfma_f32_16x16x32_bf16 v[4:7], v[178:181], v[234:237], v[4:7]
	s_barrier
; #define PG8_STAGE(bufoff, gbase, voff) do { _Pragma("unroll") for (int _i = 0; _i < 2; ++_i) \
;         __builtin_amdgcn_global_load_lds((const unsigned*)((const char*)(gbase) + (voff)[_i]), (LAS unsigned*)(lds + (bufoff) + ldsw + _i * 8192), 16, 0, 0); } while (0)
; #define PG8_LDA(dst, b, h) do { _Pragma("unroll") for (int m = 0; m < 4; ++m) _Pragma("unroll") for (int k = 0; k < 2; ++k) dst[m][k] = *(const LAS bf16x8*)(lds + PG8_SA(b, h) + aoff + m * 2048 + k * 1024); } while (0)
; #define PG8_LDB(dst, b, h) do { _Pragma("unroll") for (int n = 0; n < 2; ++n) _Pragma("unroll") for (int k = 0; k < 2; ++k) dst[n][k] = *(const LAS bf16x8*)(lds + PG8_SB(b, h) + boff + n * 2048 + k * 1024); } while (0)
; #define PG8_MMA(ai, bj, At, Bt) do { __builtin_amdgcn_s_setprio(1); _Pragma("unroll") for (int m = 0; m < 4; ++m) _Pragma("unroll") for (int n = 0; n < 2; ++n) _Pragma("unroll") for (int k = 0; k < 2; ++k) \
;         acc[ai][bj][m][n] = __builtin_amdgcn_mfma_f32_16x16x32_bf16(Bt[n][k], At[m][k], acc[ai][bj][m][n], 0, 0, 0); __builtin_amdgcn_s_setprio(0); } while (0)
; #define PG8_WAIT_V(n) asm volatile("s_waitcnt vmcnt(" #n ")" ::: "memory")
; #define PG8_WAIT_L(n) asm volatile("s_waitcnt lgkmcnt(" #n ")" ::: "memory")
; #define PG8_BAR __builtin_amdgcn_s_barrier()
; #define PG8_SCHED __builtin_amdgcn_sched_barrier(0)
; template <class Epi, class Sched>
; __device__ __forceinline__ void gemm_phase(LAS unsigned char* lds, const Gemm g, const Sched& S, const Epi& E, const int tid) {
;     ...
;             PG8_LDB(B0, 1, 0); PG8_LDB(B1, 1, 1); PG8_SCHED; PG8_LDA(At, 1, 0); PG8_STAGE(PG8_SA(0, 1), a2 + hstepA, voffA);
;             PG8_WAIT_V(8); PG8_WAIT_L(0); PG8_BAR; PG8_MMA(0, 0, At, B0); PG8_MMA(0, 1, At, B1); PG8_BAR; PG8_SCHED;
	s_add_i32 s13, 0, 0x18000
	s_add_i32 s74, 0, 0x1c000
	v_add_u32_e32 v150, s13, v204
	v_add_u32_e32 v178, s74, v204
	ds_read_b128 v[138:141], v150
	ds_read_b128 v[142:145], v150 offset:1024
	ds_read_b128 v[146:149], v150 offset:2048
	ds_read_b128 v[150:153], v150 offset:3072
	ds_read_b128 v[154:157], v178
	ds_read_b128 v[158:161], v178 offset:1024
	ds_read_b128 v[174:177], v178 offset:2048
	ds_read_b128 v[178:181], v178 offset:3072
	s_add_u32 s54, s90, 0x180000
	s_addc_u32 s55, s91, 0
	s_mov_b32 m0, s92
	v_lshl_add_u64 v[238:239], s[54:55], 0, v[164:165]
	ds_read_b128 v[182:185], v206 offset:32768
	ds_read_b128 v[186:189], v206 offset:33792
	ds_read_b128 v[190:193], v206 offset:34816
	ds_read_b128 v[194:197], v206 offset:35840
	ds_read_b128 v[198:201], v206 offset:36864
	ds_read_b128 v[210:213], v206 offset:37888
	ds_read_b128 v[220:223], v206 offset:38912
	ds_read_b128 v[234:237], v206 offset:39936
	global_load_lds_dwordx4 v[238:239], off
	v_lshl_add_u64 v[238:239], s[54:55], 0, v[132:133]
	s_mov_b32 m0, s93
	s_nop 0
	global_load_lds_dwordx4 v[238:239], off
	s_waitcnt vmcnt(8)
	s_waitcnt lgkmcnt(0)
	s_barrier
	s_waitcnt lgkmcnt(0)
	v_mfma_f32_16x16x32_bf16 v[128:131], v[138:141], v[182:185], v[128:131]
	v_mfma_f32_16x16x32_bf16 v[96:99], v[146:149], v[182:185], v[96:99]
	v_mfma_f32_16x16x32_bf16 v[124:127], v[138:141], v[190:193], v[124:127]
	v_mfma_f32_16x16x32_bf16 v[92:95], v[146:149], v[190:193], v[92:95]
	v_mfma_f32_16x16x32_bf16 v[120:123], v[138:141], v[198:201], v[120:123]
	v_mfma_f32_16x16x32_bf16 v[88:91], v[146:149], v[198:201], v[88:91]
	v_mfma_f32_16x16x32_bf16 v[116:119], v[138:141], v[220:223], v[116:119]
	v_mfma_f32_16x16x32_bf16 v[84:87], v[146:149], v[220:223], v[84:87]
	v_mfma_f32_16x16x32_bf16 v[128:131], v[142:145], v[186:189], v[128:131]
	v_mfma_f32_16x16x32_bf16 v[96:99], v[150:153], v[186:189], v[96:99]
	v_mfma_f32_16x16x32_bf16 v[124:127], v[142:145], v[194:197], v[124:127]
	v_mfma_f32_16x16x32_bf16 v[92:95], v[150:153], v[194:197], v[92:95]
	v_mfma_f32_16x16x32_bf16 v[120:123], v[142:145], v[210:213], v[120:123]
	v_mfma_f32_16x16x32_bf16 v[88:91], v[150:153], v[210:213], v[88:91]
	v_mfma_f32_16x16x32_bf16 v[116:119], v[142:145], v[234:237], v[116:119]
	v_mfma_f32_16x16x32_bf16 v[84:87], v[150:153], v[234:237], v[84:87]
	v_mfma_f32_16x16x32_bf16 v[64:67], v[154:157], v[182:185], v[64:67]
	v_mfma_f32_16x16x32_bf16 v[32:35], v[174:177], v[182:185], v[32:35]
	v_mfma_f32_16x16x32_bf16 v[60:63], v[154:157], v[190:193], v[60:63]
	v_mfma_f32_16x16x32_bf16 v[28:31], v[174:177], v[190:193], v[28:31]
	v_mfma_f32_16x16x32_bf16 v[56:59], v[154:157], v[198:201], v[56:59]
	v_mfma_f32_16x16x32_bf16 v[24:27], v[174:177], v[198:201], v[24:27]
	v_mfma_f32_16x16x32_bf16 v[52:55], v[154:157], v[220:223], v[52:55]
	v_mfma_f32_16x16x32_bf16 v[20:23], v[174:177], v[220:223], v[20:23]
	v_mfma_f32_16x16x32_bf16 v[64:67], v[158:161], v[186:189], v[64:67]
	v_mfma_f32_16x16x32_bf16 v[32:35], v[178:181], v[186:189], v[32:35]
	v_mfma_f32_16x16x32_bf16 v[60:63], v[158:161], v[194:197], v[60:63]
	v_mfma_f32_16x16x32_bf16 v[28:31], v[178:181], v[194:197], v[28:31]
	v_mfma_f32_16x16x32_bf16 v[56:59], v[158:161], v[210:213], v[56:59]
	v_mfma_f32_16x16x32_bf16 v[24:27], v[178:181], v[210:213], v[24:27]
	v_mfma_f32_16x16x32_bf16 v[52:55], v[158:161], v[234:237], v[52:55]
	v_mfma_f32_16x16x32_bf16 v[20:23], v[178:181], v[234:237], v[20:23]
	s_barrier
; #define PG8_STAGE(bufoff, gbase, voff) do { _Pragma("unroll") for (int _i = 0; _i < 2; ++_i) \
;         __builtin_amdgcn_global_load_lds((const unsigned*)((const char*)(gbase) + (voff)[_i]), (LAS unsigned*)(lds + (bufoff) + ldsw + _i * 8192), 16, 0, 0); } while (0)
; #define PG8_LDA(dst, b, h) do { _Pragma("unroll") for (int m = 0; m < 4; ++m) _Pragma("unroll") for (int k = 0; k < 2; ++k) dst[m][k] = *(const LAS bf16x8*)(lds + PG8_SA(b, h) + aoff + m * 2048 + k * 1024); } while (0)
; #define PG8_MMA(ai, bj, At, Bt) do { __builtin_amdgcn_s_setprio(1); _Pragma("unroll") for (int m = 0; m < 4; ++m) _Pragma("unroll") for (int n = 0; n < 2; ++n) _Pragma("unroll") for (int k = 0; k < 2; ++k) \
;         acc[ai][bj][m][n] = __builtin_amdgcn_mfma_f32_16x16x32_bf16(Bt[n][k], At[m][k], acc[ai][bj][m][n], 0, 0, 0); __builtin_amdgcn_s_setprio(0); } while (0)
; #define PG8_WAIT_V(n) asm volatile("s_waitcnt vmcnt(" #n ")" ::: "memory")
; #define PG8_WAIT_L(n) asm volatile("s_waitcnt lgkmcnt(" #n ")" ::: "memory")
; #define PG8_BAR __builtin_amdgcn_s_barrier()
; #define PG8_SCHED __builtin_amdgcn_sched_barrier(0)
; template <class Epi, class Sched>
; __device__ __forceinline__ void gemm_phase(LAS unsigned char* lds, const Gemm g, const Sched& S, const Epi& E, const int tid) {
;     ...
;             PG8_LDA(At, 1, 1); PG8_STAGE(PG8_SB(1, 0), b3, voffB); PG8_STAGE(PG8_SB(1, 1), b3 + hstepB, voffB); PG8_STAGE(PG8_SA(1, 0), a3, voffA);
;             PG8_WAIT_V(8); PG8_WAIT_L(0); PG8_BAR; PG8_MMA(1, 0, At, B0); PG8_MMA(1, 1, At, B1); PG8_BAR; PG8_SCHED;
;         }
;         if (wr == 0) PG8_BAR;
	s_add_i32 s13, s13, s79
	v_lshl_add_u64 v[162:163], v[162:163], 0, s[28:29]
	s_mov_b32 m0, s13
	ds_read_b128 v[182:185], v206 offset:49152
	ds_read_b128 v[186:189], v206 offset:50176
	ds_read_b128 v[190:193], v206 offset:51200
	ds_read_b128 v[194:197], v206 offset:52224
	ds_read_b128 v[198:201], v206 offset:53248
	ds_read_b128 v[210:213], v206 offset:54272
	ds_read_b128 v[220:223], v206 offset:55296
	ds_read_b128 v[234:237], v206 offset:56320
	global_load_lds_dwordx4 v[162:163], off
	s_add_i32 m0, s13, 0x2000
	s_add_u32 s54, s88, 0x180080
	v_lshl_add_u64 v[162:163], v[202:203], 0, s[28:29]
	s_addc_u32 s55, s89, 0
	s_add_i32 s13, s74, s79
	global_load_lds_dwordx4 v[162:163], off
	v_lshl_add_u64 v[162:163], s[54:55], 0, v[164:165]
	s_mov_b32 m0, s13
	s_nop 0
	global_load_lds_dwordx4 v[162:163], off
	v_lshl_add_u64 v[162:163], s[54:55], 0, v[132:133]
	s_add_i32 m0, s13, 0x2000
	s_nop 0
	global_load_lds_dwordx4 v[162:163], off
	v_lshl_add_u64 v[162:163], v[224:225], 0, s[28:29]
	s_mov_b32 m0, s94
	s_nop 0
	global_load_lds_dwordx4 v[162:163], off
	v_lshl_add_u64 v[162:163], v[226:227], 0, s[28:29]
	s_mov_b32 m0, s95
	s_nop 0
	global_load_lds_dwordx4 v[162:163], off
	s_waitcnt vmcnt(8)
	s_waitcnt lgkmcnt(0)
	s_barrier
	s_waitcnt lgkmcnt(0)
	v_mfma_f32_16x16x32_bf16 v[112:115], v[138:141], v[182:185], v[112:115]
	v_mfma_f32_16x16x32_bf16 v[80:83], v[146:149], v[182:185], v[80:83]
	v_mfma_f32_16x16x32_bf16 v[108:111], v[138:141], v[190:193], v[108:111]
	v_mfma_f32_16x16x32_bf16 v[76:79], v[146:149], v[190:193], v[76:79]
	v_mfma_f32_16x16x32_bf16 v[104:107], v[138:141], v[198:201], v[104:107]
	v_mfma_f32_16x16x32_bf16 v[72:75], v[146:149], v[198:201], v[72:75]
	v_mfma_f32_16x16x32_bf16 v[100:103], v[138:141], v[220:223], v[100:103]
	v_mfma_f32_16x16x32_bf16 v[68:71], v[146:149], v[220:223], v[68:71]
	v_mfma_f32_16x16x32_bf16 v[112:115], v[142:145], v[186:189], v[112:115]
	v_mfma_f32_16x16x32_bf16 v[80:83], v[150:153], v[186:189], v[80:83]
	v_mfma_f32_16x16x32_bf16 v[108:111], v[142:145], v[194:197], v[108:111]
	v_mfma_f32_16x16x32_bf16 v[76:79], v[150:153], v[194:197], v[76:79]
	v_mfma_f32_16x16x32_bf16 v[104:107], v[142:145], v[210:213], v[104:107]
	v_mfma_f32_16x16x32_bf16 v[72:75], v[150:153], v[210:213], v[72:75]
	v_mfma_f32_16x16x32_bf16 v[100:103], v[142:145], v[234:237], v[100:103]
	v_mfma_f32_16x16x32_bf16 v[68:71], v[150:153], v[234:237], v[68:71]
	v_mfma_f32_16x16x32_bf16 v[48:51], v[154:157], v[182:185], v[48:51]
	v_mfma_f32_16x16x32_bf16 v[16:19], v[174:177], v[182:185], v[16:19]
	v_mfma_f32_16x16x32_bf16 v[44:47], v[154:157], v[190:193], v[44:47]
	v_mfma_f32_16x16x32_bf16 v[12:15], v[174:177], v[190:193], v[12:15]
	v_mfma_f32_16x16x32_bf16 v[40:43], v[154:157], v[198:201], v[40:43]
	v_mfma_f32_16x16x32_bf16 v[8:11], v[174:177], v[198:201], v[8:11]
	v_mfma_f32_16x16x32_bf16 v[36:39], v[154:157], v[220:223], v[36:39]
	v_mfma_f32_16x16x32_bf16 v[4:7], v[174:177], v[220:223], v[4:7]
	v_mfma_f32_16x16x32_bf16 v[48:51], v[158:161], v[186:189], v[48:51]
	v_mfma_f32_16x16x32_bf16 v[16:19], v[178:181], v[186:189], v[16:19]
	v_mfma_f32_16x16x32_bf16 v[44:47], v[158:161], v[194:197], v[44:47]
	v_mfma_f32_16x16x32_bf16 v[12:15], v[178:181], v[194:197], v[12:15]
	v_mfma_f32_16x16x32_bf16 v[40:43], v[158:161], v[210:213], v[40:43]
	v_mfma_f32_16x16x32_bf16 v[8:11], v[178:181], v[210:213], v[8:11]
	v_mfma_f32_16x16x32_bf16 v[36:39], v[158:161], v[234:237], v[36:39]
	v_mfma_f32_16x16x32_bf16 v[4:7], v[178:181], v[234:237], v[4:7]
	s_barrier
	s_add_i32 s12, s12, 2
	s_add_u32 s16, s16, 0x100
	s_addc_u32 s17, s17, 0
	s_cmpk_gt_u32 s12, 0x5d
	s_mov_b64 s[54:55], s[86:87]
	s_cbranch_scc0 .LBB0_182
	s_setprio 0
	s_and_b64 vcc, exec, s[44:45]
	s_cbranch_vccz .LBB0_185
	s_barrier

; template <class Epi, class Sched>
; __device__ __forceinline__ void gemm_phase(LAS unsigned char* lds, const Gemm g, const Sched& S, const Epi& E, const int tid) {
;     ...
;         const bool has_next = S.next(ui + 1, nxt);
;         const char* nA = has_next ? (const char*)g.A + (size_t)nxt.pm * tstepA : cA; const char* nB = has_next ? (const char*)g.Bt + (size_t)nxt.pn * tstepB : cB;
;     ...
; #pragma unroll
;         for (int a = 0; a < 2; ++a)
; #pragma unroll
;             for (int b = 0; b < 2; ++b)
; #pragma unroll
;                 for (int m = 0; m < 4; ++m)
; #pragma unroll
;                     for (int n = 0; n < 2; ++n) acc[a][b][m][n] = (f32x4){0.f, 0.f, 0.f, 0.f};
;         cur = nxt; cA = nA; cB = nB; ++ui;
.LBB0_207:
	s_ashr_i32 s43, s42, 31
	s_lshl_b64 s[12:13], s[42:43], 20
	v_readlane_b32 s16, v255, 26
	s_add_u32 s44, s16, s12
	s_addc_u32 s45, s75, s13
	s_and_b64 s[12:13], s[6:7], exec
	s_cselect_b32 s16, s45, s55
	s_cselect_b32 s17, s44, s54
	s_ashr_i32 s39, s38, 31
	s_lshl_b64 s[12:13], s[38:39], 20
	s_add_u32 s46, s1, s12
	s_addc_u32 s47, s56, s13
	s_and_b64 s[12:13], s[6:7], exec
	s_cselect_b32 s39, s47, s87
	s_cselect_b32 s43, s46, s86
	s_add_u32 s54, s54, 0x80080
	s_addc_u32 s55, s55, 0
	s_add_u32 s93, s86, 0x100
	v_mov_b32_e32 v4, 0
	s_addc_u32 s94, s87, 0
	s_mov_b32 s95, -2
	v_mov_b32_e32 v5, v4
	v_mov_b32_e32 v6, v4
	v_mov_b32_e32 v7, v4
	v_mov_b32_e32 v8, v4
	v_mov_b32_e32 v9, v4
	v_mov_b32_e32 v10, v4
	v_mov_b32_e32 v11, v4
	v_mov_b32_e32 v12, v4
	v_mov_b32_e32 v13, v4
	v_mov_b32_e32 v14, v4
	v_mov_b32_e32 v15, v4
	v_mov_b32_e32 v16, v4
	v_mov_b32_e32 v17, v4
	v_mov_b32_e32 v18, v4
	v_mov_b32_e32 v19, v4
	v_mov_b32_e32 v28, v4
	v_mov_b32_e32 v29, v4
	v_mov_b32_e32 v30, v4
	v_mov_b32_e32 v31, v4
	v_mov_b32_e32 v32, v4
	v_mov_b32_e32 v33, v4
	v_mov_b32_e32 v34, v4
	v_mov_b32_e32 v35, v4
	v_mov_b32_e32 v44, v4
	v_mov_b32_e32 v45, v4
	v_mov_b32_e32 v46, v4
	v_mov_b32_e32 v47, v4
	v_mov_b32_e32 v48, v4
	v_mov_b32_e32 v49, v4
	v_mov_b32_e32 v50, v4
	v_mov_b32_e32 v51, v4
	v_mov_b32_e32 v20, v4
	v_mov_b32_e32 v21, v4
	v_mov_b32_e32 v22, v4
	v_mov_b32_e32 v23, v4
	v_mov_b32_e32 v24, v4
	v_mov_b32_e32 v25, v4
	v_mov_b32_e32 v26, v4
	v_mov_b32_e32 v27, v4
	v_mov_b32_e32 v36, v4
	v_mov_b32_e32 v37, v4
	v_mov_b32_e32 v38, v4
	v_mov_b32_e32 v39, v4
	v_mov_b32_e32 v40, v4
	v_mov_b32_e32 v41, v4
	v_mov_b32_e32 v42, v4
	v_mov_b32_e32 v43, v4
	v_mov_b32_e32 v52, v4
	v_mov_b32_e32 v53, v4
	v_mov_b32_e32 v54, v4
	v_mov_b32_e32 v55, v4
	v_mov_b32_e32 v56, v4
	v_mov_b32_e32 v57, v4
	v_mov_b32_e32 v58, v4
	v_mov_b32_e32 v59, v4
	v_mov_b32_e32 v60, v4
	v_mov_b32_e32 v61, v4
	v_mov_b32_e32 v62, v4
	v_mov_b32_e32 v63, v4
	v_mov_b32_e32 v64, v4
	v_mov_b32_e32 v65, v4
	v_mov_b32_e32 v66, v4
	v_mov_b32_e32 v67, v4
	v_mov_b32_e32 v68, v4
	v_mov_b32_e32 v69, v4
	v_mov_b32_e32 v70, v4
	v_mov_b32_e32 v71, v4
	v_mov_b32_e32 v72, v4
	v_mov_b32_e32 v73, v4
	v_mov_b32_e32 v74, v4
	v_mov_b32_e32 v75, v4
	v_mov_b32_e32 v76, v4
	v_mov_b32_e32 v77, v4
	v_mov_b32_e32 v78, v4
	v_mov_b32_e32 v79, v4
	v_mov_b32_e32 v80, v4
	v_mov_b32_e32 v81, v4
	v_mov_b32_e32 v82, v4
	v_mov_b32_e32 v83, v4
	v_mov_b32_e32 v92, v4
	v_mov_b32_e32 v93, v4
	v_mov_b32_e32 v94, v4
	v_mov_b32_e32 v95, v4
	v_mov_b32_e32 v96, v4
	v_mov_b32_e32 v97, v4
	v_mov_b32_e32 v98, v4
	v_mov_b32_e32 v99, v4
	v_mov_b32_e32 v108, v4
	v_mov_b32_e32 v109, v4
	v_mov_b32_e32 v110, v4
	v_mov_b32_e32 v111, v4
	v_mov_b32_e32 v112, v4
	v_mov_b32_e32 v113, v4
	v_mov_b32_e32 v114, v4
	v_mov_b32_e32 v115, v4
	v_mov_b32_e32 v84, v4
	v_mov_b32_e32 v85, v4
	v_mov_b32_e32 v86, v4
	v_mov_b32_e32 v87, v4
	v_mov_b32_e32 v88, v4
	v_mov_b32_e32 v89, v4
	v_mov_b32_e32 v90, v4
	v_mov_b32_e32 v91, v4
	v_mov_b32_e32 v100, v4
	v_mov_b32_e32 v101, v4
	v_mov_b32_e32 v102, v4
	v_mov_b32_e32 v103, v4
	v_mov_b32_e32 v104, v4
	v_mov_b32_e32 v105, v4
	v_mov_b32_e32 v106, v4
	v_mov_b32_e32 v107, v4
	v_mov_b32_e32 v116, v4
	v_mov_b32_e32 v117, v4
	v_mov_b32_e32 v118, v4
	v_mov_b32_e32 v119, v4
	v_mov_b32_e32 v120, v4
	v_mov_b32_e32 v121, v4
	v_mov_b32_e32 v122, v4
	v_mov_b32_e32 v123, v4
	v_mov_b32_e32 v124, v4
	v_mov_b32_e32 v125, v4
	v_mov_b32_e32 v126, v4
	v_mov_b32_e32 v127, v4
	v_mov_b32_e32 v128, v4
	v_mov_b32_e32 v129, v4
	v_mov_b32_e32 v130, v4
	v_mov_b32_e32 v131, v4
	s_cselect_b32 s99, 1, 0
	v_readfirstlane_b32 s98, v173
	s_nop 0
	s_cmpk_lt_u32 s98, 0x100
	s_cbranch_scc1 .Lprio_skip_LBB0208
	s_setprio 1

; #define PG8_STAGE(bufoff, gbase, voff) do { _Pragma("unroll") for (int _i = 0; _i < 2; ++_i) \
;         __builtin_amdgcn_global_load_lds((const unsigned*)((const char*)(gbase) + (voff)[_i]), (LAS unsigned*)(lds + (bufoff) + ldsw + _i * 8192), 16, 0, 0); } while (0)
; #define PG8_LDA(dst, b, h) do { _Pragma("unroll") for (int m = 0; m < 4; ++m) _Pragma("unroll") for (int k = 0; k < 2; ++k) dst[m][k] = *(const LAS bf16x8*)(lds + PG8_SA(b, h) + aoff + m * 2048 + k * 1024); } while (0)
; #define PG8_LDB(dst, b, h) do { _Pragma("unroll") for (int n = 0; n < 2; ++n) _Pragma("unroll") for (int k = 0; k < 2; ++k) dst[n][k] = *(const LAS bf16x8*)(lds + PG8_SB(b, h) + boff + n * 2048 + k * 1024); } while (0)
; #define PG8_MMA(ai, bj, At, Bt) do { __builtin_amdgcn_s_setprio(1); _Pragma("unroll") for (int m = 0; m < 4; ++m) _Pragma("unroll") for (int n = 0; n < 2; ++n) _Pragma("unroll") for (int k = 0; k < 2; ++k) \
;         acc[ai][bj][m][n] = __builtin_amdgcn_mfma_f32_16x16x32_bf16(Bt[n][k], At[m][k], acc[ai][bj][m][n], 0, 0, 0); __builtin_amdgcn_s_setprio(0); } while (0)
; #define PG8_WAIT_V(n) asm volatile("s_waitcnt vmcnt(" #n ")" ::: "memory")
; #define PG8_WAIT_L(n) asm volatile("s_waitcnt lgkmcnt(" #n ")" ::: "memory")
; #define PG8_BAR __builtin_amdgcn_s_barrier()
; #define PG8_SCHED __builtin_amdgcn_sched_barrier(0)
; template <class Epi, class Sched>
; __device__ __forceinline__ void gemm_phase(LAS unsigned char* lds, const Gemm g, const Sched& S, const Epi& E, const int tid) {
;     ...
;             const bool last = (t == nt - 2);
;             const char* a1 = cA + (size_t)(t + 1) * kstep;
;             const char* a2 = last ? nA : cA + (size_t)(t + 2) * kstep; const char* b2 = last ? nB : cB + (size_t)(t + 2) * kstep;
;             const char* a3 = a2 + kstep; const char* b3 = b2 + kstep;
;             PG8_LDB(B0, 0, 0); PG8_LDB(B1, 0, 1); PG8_SCHED; PG8_LDA(At, 0, 0); PG8_STAGE(PG8_SA(1, 1), a1 + hstepA, voffA);
;             PG8_WAIT_V(8); PG8_WAIT_L(0); PG8_BAR; PG8_MMA(0, 0, At, B0); PG8_MMA(0, 1, At, B1); PG8_BAR; PG8_SCHED;
;             PG8_LDA(At, 0, 1); PG8_STAGE(PG8_SB(0, 0), b2, voffB); PG8_STAGE(PG8_SB(0, 1), b2 + hstepB, voffB); PG8_STAGE(PG8_SA(0, 0), a2, voffA);
.LBB0_208:
	s_add_u32 s12, s54, 0xfff80080
	s_addc_u32 s13, s55, -1
	s_add_i32 s74, 0, 0x10000
	s_cmp_eq_u32 s95, 28
	s_cselect_b32 s89, s16, s13
	s_cselect_b32 s88, s17, s12
	s_cselect_b32 s87, s39, s94
	s_cselect_b32 s86, s43, s93
	s_add_i32 s96, 0, 0x14000
	v_add_u32_e32 v158, s74, v143
	v_add_u32_e32 v162, s96, v143
	ds_read_b128 v[146:149], v158
	ds_read_b128 v[150:153], v158 offset:1024
	ds_read_b128 v[154:157], v158 offset:2048
	ds_read_b128 v[158:161], v158 offset:3072
	ds_read_b128 v[174:177], v162
	ds_read_b128 v[178:181], v162 offset:1024
	ds_read_b128 v[182:185], v162 offset:2048
	ds_read_b128 v[186:189], v162 offset:3072
	v_lshl_add_u64 v[162:163], s[54:55], 0, v[138:139]
	s_add_i32 m0, s11, 0xc000
	ds_read_b128 v[190:193], v145
	ds_read_b128 v[194:197], v145 offset:1024
	ds_read_b128 v[198:201], v145 offset:2048
	ds_read_b128 v[202:205], v145 offset:3072
	ds_read_b128 v[210:213], v145 offset:4096
	ds_read_b128 v[220:223], v145 offset:5120
	ds_read_b128 v[234:237], v145 offset:6144
	ds_read_b128 v[238:241], v145 offset:7168
	global_load_lds_dwordx4 v[162:163], off
	v_lshl_add_u64 v[162:163], s[54:55], 0, v[140:141]
	s_add_i32 m0, s11, 0xe000
	s_nop 0
	global_load_lds_dwordx4 v[162:163], off
	s_waitcnt vmcnt(8)
	s_waitcnt lgkmcnt(0)
	s_barrier
	s_waitcnt lgkmcnt(0)
	v_mfma_f32_16x16x32_bf16 v[128:131], v[146:149], v[190:193], v[128:131]
	v_mfma_f32_16x16x32_bf16 v[124:127], v[154:157], v[190:193], v[124:127]
	v_mfma_f32_16x16x32_bf16 v[120:123], v[146:149], v[198:201], v[120:123]
	v_mfma_f32_16x16x32_bf16 v[116:119], v[154:157], v[198:201], v[116:119]
	v_mfma_f32_16x16x32_bf16 v[104:107], v[146:149], v[210:213], v[104:107]
	v_mfma_f32_16x16x32_bf16 v[100:103], v[154:157], v[210:213], v[100:103]
	v_mfma_f32_16x16x32_bf16 v[88:91], v[146:149], v[234:237], v[88:91]
	v_mfma_f32_16x16x32_bf16 v[84:87], v[154:157], v[234:237], v[84:87]
	v_mfma_f32_16x16x32_bf16 v[128:131], v[150:153], v[194:197], v[128:131]
	v_mfma_f32_16x16x32_bf16 v[124:127], v[158:161], v[194:197], v[124:127]
	v_mfma_f32_16x16x32_bf16 v[120:123], v[150:153], v[202:205], v[120:123]
	v_mfma_f32_16x16x32_bf16 v[116:119], v[158:161], v[202:205], v[116:119]
	v_mfma_f32_16x16x32_bf16 v[104:107], v[150:153], v[220:223], v[104:107]
	v_mfma_f32_16x16x32_bf16 v[100:103], v[158:161], v[220:223], v[100:103]
	v_mfma_f32_16x16x32_bf16 v[88:91], v[150:153], v[238:241], v[88:91]
	v_mfma_f32_16x16x32_bf16 v[84:87], v[158:161], v[238:241], v[84:87]
	v_mfma_f32_16x16x32_bf16 v[112:115], v[174:177], v[190:193], v[112:115]
	v_mfma_f32_16x16x32_bf16 v[108:111], v[182:185], v[190:193], v[108:111]
	v_mfma_f32_16x16x32_bf16 v[96:99], v[174:177], v[198:201], v[96:99]
	v_mfma_f32_16x16x32_bf16 v[92:95], v[182:185], v[198:201], v[92:95]
	v_mfma_f32_16x16x32_bf16 v[80:83], v[174:177], v[210:213], v[80:83]
	v_mfma_f32_16x16x32_bf16 v[76:79], v[182:185], v[210:213], v[76:79]
	v_mfma_f32_16x16x32_bf16 v[72:75], v[174:177], v[234:237], v[72:75]
	v_mfma_f32_16x16x32_bf16 v[68:71], v[182:185], v[234:237], v[68:71]
	v_mfma_f32_16x16x32_bf16 v[112:115], v[178:181], v[194:197], v[112:115]
	v_mfma_f32_16x16x32_bf16 v[108:111], v[186:189], v[194:197], v[108:111]
	v_mfma_f32_16x16x32_bf16 v[96:99], v[178:181], v[202:205], v[96:99]
	v_mfma_f32_16x16x32_bf16 v[92:95], v[186:189], v[202:205], v[92:95]
	v_mfma_f32_16x16x32_bf16 v[80:83], v[178:181], v[220:223], v[80:83]
	v_mfma_f32_16x16x32_bf16 v[76:79], v[186:189], v[220:223], v[76:79]
	v_mfma_f32_16x16x32_bf16 v[72:75], v[178:181], v[238:241], v[72:75]
	v_mfma_f32_16x16x32_bf16 v[68:71], v[186:189], v[238:241], v[68:71]
	s_barrier
	s_add_i32 s12, s74, s57
	v_lshl_add_u64 v[162:163], s[86:87], 0, v[164:165]
	s_mov_b32 m0, s12
	ds_read_b128 v[190:193], v145 offset:16384
	ds_read_b128 v[194:197], v145 offset:17408
	ds_read_b128 v[198:201], v145 offset:18432
	ds_read_b128 v[202:205], v145 offset:19456
	ds_read_b128 v[210:213], v145 offset:20480
	ds_read_b128 v[220:223], v145 offset:21504
	ds_read_b128 v[234:237], v145 offset:22528
	ds_read_b128 v[238:241], v145 offset:23552
	global_load_lds_dwordx4 v[162:163], off
	s_add_i32 m0, s12, 0x2000
	s_add_u32 s12, s86, 0x80000
	v_lshl_add_u64 v[206:207], s[86:87], 0, v[132:133]
	s_addc_u32 s13, s87, 0
	s_add_i32 s74, s96, s57
	global_load_lds_dwordx4 v[206:207], off
	v_lshl_add_u64 v[224:225], s[12:13], 0, v[164:165]
	s_mov_b32 m0, s74
	v_lshl_add_u64 v[226:227], s[88:89], 0, v[134:135]
	global_load_lds_dwordx4 v[224:225], off
	v_lshl_add_u64 v[224:225], s[12:13], 0, v[132:133]
	s_add_i32 m0, s74, 0x2000
	s_nop 0
	global_load_lds_dwordx4 v[224:225], off
	v_lshl_add_u64 v[224:225], s[88:89], 0, v[136:137]
	s_mov_b32 m0, s11
	s_nop 0
	global_load_lds_dwordx4 v[224:225], off
	s_mov_b32 m0, s59
	s_nop 0
	global_load_lds_dwordx4 v[226:227], off
	s_waitcnt vmcnt(8)
	s_waitcnt lgkmcnt(0)
	s_barrier
; #define PG8_STAGE(bufoff, gbase, voff) do { _Pragma("unroll") for (int _i = 0; _i < 2; ++_i) \
;         __builtin_amdgcn_global_load_lds((const unsigned*)((const char*)(gbase) + (voff)[_i]), (LAS unsigned*)(lds + (bufoff) + ldsw + _i * 8192), 16, 0, 0); } while (0)
; #define PG8_LDA(dst, b, h) do { _Pragma("unroll") for (int m = 0; m < 4; ++m) _Pragma("unroll") for (int k = 0; k < 2; ++k) dst[m][k] = *(const LAS bf16x8*)(lds + PG8_SA(b, h) + aoff + m * 2048 + k * 1024); } while (0)
; #define PG8_LDB(dst, b, h) do { _Pragma("unroll") for (int n = 0; n < 2; ++n) _Pragma("unroll") for (int k = 0; k < 2; ++k) dst[n][k] = *(const LAS bf16x8*)(lds + PG8_SB(b, h) + boff + n * 2048 + k * 1024); } while (0)
; #define PG8_MMA(ai, bj, At, Bt) do { __builtin_amdgcn_s_setprio(1); _Pragma("unroll") for (int m = 0; m < 4; ++m) _Pragma("unroll") for (int n = 0; n < 2; ++n) _Pragma("unroll") for (int k = 0; k < 2; ++k) \
;         acc[ai][bj][m][n] = __builtin_amdgcn_mfma_f32_16x16x32_bf16(Bt[n][k], At[m][k], acc[ai][bj][m][n], 0, 0, 0); __builtin_amdgcn_s_setprio(0); } while (0)
; #define PG8_WAIT_V(n) asm volatile("s_waitcnt vmcnt(" #n ")" ::: "memory")
; #define PG8_WAIT_L(n) asm volatile("s_waitcnt lgkmcnt(" #n ")" ::: "memory")
; #define PG8_BAR __builtin_amdgcn_s_barrier()
; #define PG8_SCHED __builtin_amdgcn_sched_barrier(0)
; template <class Epi, class Sched>
; __device__ __forceinline__ void gemm_phase(LAS unsigned char* lds, const Gemm g, const Sched& S, const Epi& E, const int tid) {
;     ...
;             PG8_WAIT_V(8); PG8_WAIT_L(0); PG8_BAR; PG8_MMA(1, 0, At, B0); PG8_MMA(1, 1, At, B1); PG8_BAR; PG8_SCHED;
;             PG8_LDB(B0, 1, 0); PG8_LDB(B1, 1, 1); PG8_SCHED; PG8_LDA(At, 1, 0); PG8_STAGE(PG8_SA(0, 1), a2 + hstepA, voffA);
;             PG8_WAIT_V(8); PG8_WAIT_L(0); PG8_BAR; PG8_MMA(0, 0, At, B0); PG8_MMA(0, 1, At, B1); PG8_BAR; PG8_SCHED;
	s_waitcnt lgkmcnt(0)
	v_mfma_f32_16x16x32_bf16 v[64:67], v[146:149], v[190:193], v[64:67]
	v_mfma_f32_16x16x32_bf16 v[60:63], v[154:157], v[190:193], v[60:63]
	v_mfma_f32_16x16x32_bf16 v[56:59], v[146:149], v[198:201], v[56:59]
	v_mfma_f32_16x16x32_bf16 v[52:55], v[154:157], v[198:201], v[52:55]
	v_mfma_f32_16x16x32_bf16 v[40:43], v[146:149], v[210:213], v[40:43]
	v_mfma_f32_16x16x32_bf16 v[36:39], v[154:157], v[210:213], v[36:39]
	v_mfma_f32_16x16x32_bf16 v[24:27], v[146:149], v[234:237], v[24:27]
	v_mfma_f32_16x16x32_bf16 v[20:23], v[154:157], v[234:237], v[20:23]
	v_mfma_f32_16x16x32_bf16 v[64:67], v[150:153], v[194:197], v[64:67]
	v_mfma_f32_16x16x32_bf16 v[60:63], v[158:161], v[194:197], v[60:63]
	v_mfma_f32_16x16x32_bf16 v[56:59], v[150:153], v[202:205], v[56:59]
	v_mfma_f32_16x16x32_bf16 v[52:55], v[158:161], v[202:205], v[52:55]
	v_mfma_f32_16x16x32_bf16 v[40:43], v[150:153], v[220:223], v[40:43]
	v_mfma_f32_16x16x32_bf16 v[36:39], v[158:161], v[220:223], v[36:39]
	v_mfma_f32_16x16x32_bf16 v[24:27], v[150:153], v[238:241], v[24:27]
	v_mfma_f32_16x16x32_bf16 v[20:23], v[158:161], v[238:241], v[20:23]
	v_mfma_f32_16x16x32_bf16 v[48:51], v[174:177], v[190:193], v[48:51]
	v_mfma_f32_16x16x32_bf16 v[44:47], v[182:185], v[190:193], v[44:47]
	v_mfma_f32_16x16x32_bf16 v[32:35], v[174:177], v[198:201], v[32:35]
	v_mfma_f32_16x16x32_bf16 v[28:31], v[182:185], v[198:201], v[28:31]
	v_mfma_f32_16x16x32_bf16 v[16:19], v[174:177], v[210:213], v[16:19]
	v_mfma_f32_16x16x32_bf16 v[12:15], v[182:185], v[210:213], v[12:15]
	v_mfma_f32_16x16x32_bf16 v[8:11], v[174:177], v[234:237], v[8:11]
	v_mfma_f32_16x16x32_bf16 v[4:7], v[182:185], v[234:237], v[4:7]
	v_mfma_f32_16x16x32_bf16 v[48:51], v[178:181], v[194:197], v[48:51]
	v_mfma_f32_16x16x32_bf16 v[44:47], v[186:189], v[194:197], v[44:47]
	v_mfma_f32_16x16x32_bf16 v[32:35], v[178:181], v[202:205], v[32:35]
	v_mfma_f32_16x16x32_bf16 v[28:31], v[186:189], v[202:205], v[28:31]
	v_mfma_f32_16x16x32_bf16 v[16:19], v[178:181], v[220:223], v[16:19]
	v_mfma_f32_16x16x32_bf16 v[12:15], v[186:189], v[220:223], v[12:15]
	v_mfma_f32_16x16x32_bf16 v[8:11], v[178:181], v[238:241], v[8:11]
	v_mfma_f32_16x16x32_bf16 v[4:7], v[186:189], v[238:241], v[4:7]
	s_barrier
	s_add_i32 s74, 0, 0x18000
	s_add_i32 s96, 0, 0x1c000
	v_add_u32_e32 v158, s74, v143
	v_add_u32_e32 v171, s96, v143
	ds_read_b128 v[146:149], v158
	ds_read_b128 v[150:153], v158 offset:1024
	ds_read_b128 v[154:157], v158 offset:2048
	ds_read_b128 v[158:161], v158 offset:3072
	ds_read_b128 v[174:177], v171
	ds_read_b128 v[178:181], v171 offset:1024
	ds_read_b128 v[182:185], v171 offset:2048
	ds_read_b128 v[186:189], v171 offset:3072
	s_add_u32 s12, s88, 0x80000
	s_addc_u32 s13, s89, 0
	s_mov_b32 m0, s79
	v_lshl_add_u64 v[242:243], s[12:13], 0, v[136:137]
	ds_read_b128 v[190:193], v145 offset:32768
	ds_read_b128 v[194:197], v145 offset:33792
	ds_read_b128 v[198:201], v145 offset:34816
	ds_read_b128 v[202:205], v145 offset:35840
	ds_read_b128 v[210:213], v145 offset:36864
	ds_read_b128 v[220:223], v145 offset:37888
	ds_read_b128 v[234:237], v145 offset:38912
	ds_read_b128 v[238:241], v145 offset:39936
	global_load_lds_dwordx4 v[242:243], off
	v_lshl_add_u64 v[242:243], s[12:13], 0, v[134:135]
	s_mov_b32 m0, s84
	s_nop 0
	global_load_lds_dwordx4 v[242:243], off
	s_waitcnt vmcnt(8)
	s_waitcnt lgkmcnt(0)
	s_barrier
	s_waitcnt lgkmcnt(0)
	v_mfma_f32_16x16x32_bf16 v[128:131], v[146:149], v[190:193], v[128:131]
	v_mfma_f32_16x16x32_bf16 v[124:127], v[154:157], v[190:193], v[124:127]
	v_mfma_f32_16x16x32_bf16 v[120:123], v[146:149], v[198:201], v[120:123]
	v_mfma_f32_16x16x32_bf16 v[116:119], v[154:157], v[198:201], v[116:119]
	v_mfma_f32_16x16x32_bf16 v[104:107], v[146:149], v[210:213], v[104:107]
	v_mfma_f32_16x16x32_bf16 v[100:103], v[154:157], v[210:213], v[100:103]
	v_mfma_f32_16x16x32_bf16 v[88:91], v[146:149], v[234:237], v[88:91]
	v_mfma_f32_16x16x32_bf16 v[84:87], v[154:157], v[234:237], v[84:87]
	v_mfma_f32_16x16x32_bf16 v[128:131], v[150:153], v[194:197], v[128:131]
	v_mfma_f32_16x16x32_bf16 v[124:127], v[158:161], v[194:197], v[124:127]
	v_mfma_f32_16x16x32_bf16 v[120:123], v[150:153], v[202:205], v[120:123]
	v_mfma_f32_16x16x32_bf16 v[116:119], v[158:161], v[202:205], v[116:119]
	v_mfma_f32_16x16x32_bf16 v[104:107], v[150:153], v[220:223], v[104:107]
	v_mfma_f32_16x16x32_bf16 v[100:103], v[158:161], v[220:223], v[100:103]
	v_mfma_f32_16x16x32_bf16 v[88:91], v[150:153], v[238:241], v[88:91]
	v_mfma_f32_16x16x32_bf16 v[84:87], v[158:161], v[238:241], v[84:87]
	v_mfma_f32_16x16x32_bf16 v[112:115], v[174:177], v[190:193], v[112:115]
	v_mfma_f32_16x16x32_bf16 v[108:111], v[182:185], v[190:193], v[108:111]
	v_mfma_f32_16x16x32_bf16 v[96:99], v[174:177], v[198:201], v[96:99]
	v_mfma_f32_16x16x32_bf16 v[92:95], v[182:185], v[198:201], v[92:95]
	v_mfma_f32_16x16x32_bf16 v[80:83], v[174:177], v[210:213], v[80:83]
	v_mfma_f32_16x16x32_bf16 v[76:79], v[182:185], v[210:213], v[76:79]
	v_mfma_f32_16x16x32_bf16 v[72:75], v[174:177], v[234:237], v[72:75]
	v_mfma_f32_16x16x32_bf16 v[68:71], v[182:185], v[234:237], v[68:71]
	v_mfma_f32_16x16x32_bf16 v[112:115], v[178:181], v[194:197], v[112:115]
	v_mfma_f32_16x16x32_bf16 v[108:111], v[186:189], v[194:197], v[108:111]
	v_mfma_f32_16x16x32_bf16 v[96:99], v[178:181], v[202:205], v[96:99]
	v_mfma_f32_16x16x32_bf16 v[92:95], v[186:189], v[202:205], v[92:95]
	v_mfma_f32_16x16x32_bf16 v[80:83], v[178:181], v[220:223], v[80:83]
	v_mfma_f32_16x16x32_bf16 v[76:79], v[186:189], v[220:223], v[76:79]
	v_mfma_f32_16x16x32_bf16 v[72:75], v[178:181], v[238:241], v[72:75]
	v_mfma_f32_16x16x32_bf16 v[68:71], v[186:189], v[238:241], v[68:71]
	s_barrier
; #define PG8_STAGE(bufoff, gbase, voff) do { _Pragma("unroll") for (int _i = 0; _i < 2; ++_i) \
;         __builtin_amdgcn_global_load_lds((const unsigned*)((const char*)(gbase) + (voff)[_i]), (LAS unsigned*)(lds + (bufoff) + ldsw + _i * 8192), 16, 0, 0); } while (0)
; #define PG8_LDA(dst, b, h) do { _Pragma("unroll") for (int m = 0; m < 4; ++m) _Pragma("unroll") for (int k = 0; k < 2; ++k) dst[m][k] = *(const LAS bf16x8*)(lds + PG8_SA(b, h) + aoff + m * 2048 + k * 1024); } while (0)
; #define PG8_MMA(ai, bj, At, Bt) do { __builtin_amdgcn_s_setprio(1); _Pragma("unroll") for (int m = 0; m < 4; ++m) _Pragma("unroll") for (int n = 0; n < 2; ++n) _Pragma("unroll") for (int k = 0; k < 2; ++k) \
;         acc[ai][bj][m][n] = __builtin_amdgcn_mfma_f32_16x16x32_bf16(Bt[n][k], At[m][k], acc[ai][bj][m][n], 0, 0, 0); __builtin_amdgcn_s_setprio(0); } while (0)
; #define PG8_WAIT_V(n) asm volatile("s_waitcnt vmcnt(" #n ")" ::: "memory")
; #define PG8_WAIT_L(n) asm volatile("s_waitcnt lgkmcnt(" #n ")" ::: "memory")
; #define PG8_BAR __builtin_amdgcn_s_barrier()
; #define PG8_SCHED __builtin_amdgcn_sched_barrier(0)
; template <class Epi, class Sched>
; __device__ __forceinline__ void gemm_phase(LAS unsigned char* lds, const Gemm g, const Sched& S, const Epi& E, const int tid) {
;     ...
;             PG8_LDA(At, 1, 1); PG8_STAGE(PG8_SB(1, 0), b3, voffB); PG8_STAGE(PG8_SB(1, 1), b3 + hstepB, voffB); PG8_STAGE(PG8_SA(1, 0), a3, voffA);
;             PG8_WAIT_V(8); PG8_WAIT_L(0); PG8_BAR; PG8_MMA(1, 0, At, B0); PG8_MMA(1, 1, At, B1); PG8_BAR; PG8_SCHED;
;         }
;         if (wr == 0) PG8_BAR;
	s_add_i32 s12, s74, s57
	v_lshl_add_u64 v[162:163], v[162:163], 0, s[28:29]
	s_mov_b32 m0, s12
	ds_read_b128 v[190:193], v145 offset:49152
	ds_read_b128 v[194:197], v145 offset:50176
	ds_read_b128 v[198:201], v145 offset:51200
	ds_read_b128 v[202:205], v145 offset:52224
	ds_read_b128 v[210:213], v145 offset:53248
	ds_read_b128 v[220:223], v145 offset:54272
	ds_read_b128 v[234:237], v145 offset:55296
	ds_read_b128 v[238:241], v145 offset:56320
	global_load_lds_dwordx4 v[162:163], off
	s_add_i32 m0, s12, 0x2000
	s_add_u32 s12, s86, 0x80080
	v_lshl_add_u64 v[162:163], v[206:207], 0, s[28:29]
	s_addc_u32 s13, s87, 0
	s_add_i32 s74, s96, s57
	global_load_lds_dwordx4 v[162:163], off
	v_lshl_add_u64 v[162:163], s[12:13], 0, v[164:165]
	s_mov_b32 m0, s74
	s_nop 0
	global_load_lds_dwordx4 v[162:163], off
	v_lshl_add_u64 v[162:163], s[12:13], 0, v[132:133]
	s_add_i32 m0, s74, 0x2000
	s_nop 0
	global_load_lds_dwordx4 v[162:163], off
	v_lshl_add_u64 v[162:163], v[224:225], 0, s[28:29]
	s_mov_b32 m0, s85
	s_nop 0
	global_load_lds_dwordx4 v[162:163], off
	v_lshl_add_u64 v[162:163], v[226:227], 0, s[28:29]
	s_mov_b32 m0, s90
	s_nop 0
	global_load_lds_dwordx4 v[162:163], off
	s_waitcnt vmcnt(8)
	s_waitcnt lgkmcnt(0)
	s_barrier
	s_waitcnt lgkmcnt(0)
	v_mfma_f32_16x16x32_bf16 v[64:67], v[146:149], v[190:193], v[64:67]
	v_mfma_f32_16x16x32_bf16 v[60:63], v[154:157], v[190:193], v[60:63]
	v_mfma_f32_16x16x32_bf16 v[56:59], v[146:149], v[198:201], v[56:59]
	v_mfma_f32_16x16x32_bf16 v[52:55], v[154:157], v[198:201], v[52:55]
	v_mfma_f32_16x16x32_bf16 v[40:43], v[146:149], v[210:213], v[40:43]
	v_mfma_f32_16x16x32_bf16 v[36:39], v[154:157], v[210:213], v[36:39]
	v_mfma_f32_16x16x32_bf16 v[24:27], v[146:149], v[234:237], v[24:27]
	v_mfma_f32_16x16x32_bf16 v[20:23], v[154:157], v[234:237], v[20:23]
	v_mfma_f32_16x16x32_bf16 v[64:67], v[150:153], v[194:197], v[64:67]
	v_mfma_f32_16x16x32_bf16 v[60:63], v[158:161], v[194:197], v[60:63]
	v_mfma_f32_16x16x32_bf16 v[56:59], v[150:153], v[202:205], v[56:59]
	v_mfma_f32_16x16x32_bf16 v[52:55], v[158:161], v[202:205], v[52:55]
	v_mfma_f32_16x16x32_bf16 v[40:43], v[150:153], v[220:223], v[40:43]
	v_mfma_f32_16x16x32_bf16 v[36:39], v[158:161], v[220:223], v[36:39]
	v_mfma_f32_16x16x32_bf16 v[24:27], v[150:153], v[238:241], v[24:27]
	v_mfma_f32_16x16x32_bf16 v[20:23], v[158:161], v[238:241], v[20:23]
	v_mfma_f32_16x16x32_bf16 v[48:51], v[174:177], v[190:193], v[48:51]
	v_mfma_f32_16x16x32_bf16 v[44:47], v[182:185], v[190:193], v[44:47]
	v_mfma_f32_16x16x32_bf16 v[32:35], v[174:177], v[198:201], v[32:35]
	v_mfma_f32_16x16x32_bf16 v[28:31], v[182:185], v[198:201], v[28:31]
	v_mfma_f32_16x16x32_bf16 v[16:19], v[174:177], v[210:213], v[16:19]
	v_mfma_f32_16x16x32_bf16 v[12:15], v[182:185], v[210:213], v[12:15]
	v_mfma_f32_16x16x32_bf16 v[8:11], v[174:177], v[234:237], v[8:11]
	v_mfma_f32_16x16x32_bf16 v[4:7], v[182:185], v[234:237], v[4:7]
	v_mfma_f32_16x16x32_bf16 v[48:51], v[178:181], v[194:197], v[48:51]
	v_mfma_f32_16x16x32_bf16 v[44:47], v[186:189], v[194:197], v[44:47]
	v_mfma_f32_16x16x32_bf16 v[32:35], v[178:181], v[202:205], v[32:35]
	v_mfma_f32_16x16x32_bf16 v[28:31], v[186:189], v[202:205], v[28:31]
	v_mfma_f32_16x16x32_bf16 v[16:19], v[178:181], v[220:223], v[16:19]
	v_mfma_f32_16x16x32_bf16 v[12:15], v[186:189], v[220:223], v[12:15]
	v_mfma_f32_16x16x32_bf16 v[8:11], v[178:181], v[238:241], v[8:11]
	v_mfma_f32_16x16x32_bf16 v[4:7], v[186:189], v[238:241], v[4:7]
	s_barrier
	s_add_i32 s95, s95, 2
	s_add_u32 s54, s54, 0x100
	s_addc_u32 s55, s55, 0
	s_add_u32 s93, s93, 0x100
	s_addc_u32 s94, s94, 0
	s_cmp_gt_u32 s95, 29
	s_cbranch_scc0 .LBB0_208
	s_setprio 0
	s_and_b64 vcc, exec, s[30:31]
	s_cbranch_vccz .LBB0_211
	s_barrier

; template <class Epi, class Sched>
; __device__ __forceinline__ void gemm_phase(LAS unsigned char* lds, const Gemm g, const Sched& S, const Epi& E, const int tid) {
;     ...
;         const bool has_next = S.next(ui + 1, nxt);
;         const char* nA = has_next ? (const char*)g.A + (size_t)nxt.pm * tstepA : cA; const char* nB = has_next ? (const char*)g.Bt + (size_t)nxt.pn * tstepB : cB;
;     ...
; #pragma unroll
;         for (int a = 0; a < 2; ++a)
; #pragma unroll
;             for (int b = 0; b < 2; ++b)
; #pragma unroll
;                 for (int m = 0; m < 4; ++m)
; #pragma unroll
;                     for (int n = 0; n < 2; ++n) acc[a][b][m][n] = (f32x4){0.f, 0.f, 0.f, 0.f};
;         cur = nxt; cA = nA; cB = nB; ++ui;
.LBB0_250:
	s_ashr_i32 s45, s44, 31
	s_lshl_b64 s[12:13], s[44:45], 20
	s_add_u32 s54, s56, s12
	s_addc_u32 s55, s57, s13
	s_and_b64 s[8:9], s[8:9], exec
	s_cselect_b32 s17, s55, s89
	s_cselect_b32 s45, s54, s88
	s_add_u32 vcc_lo, s88, 0x100
	v_mov_b32_e32 v4, 0
	s_addc_u32 vcc_hi, s89, 0
	s_mov_b32 s12, -2
	v_mov_b32_e32 v5, v4
	v_mov_b32_e32 v6, v4
	v_mov_b32_e32 v7, v4
	v_mov_b32_e32 v36, v4
	v_mov_b32_e32 v37, v4
	v_mov_b32_e32 v38, v4
	v_mov_b32_e32 v39, v4
	v_mov_b32_e32 v8, v4
	v_mov_b32_e32 v9, v4
	v_mov_b32_e32 v10, v4
	v_mov_b32_e32 v11, v4
	v_mov_b32_e32 v40, v4
	v_mov_b32_e32 v41, v4
	v_mov_b32_e32 v42, v4
	v_mov_b32_e32 v43, v4
	v_mov_b32_e32 v12, v4
	v_mov_b32_e32 v13, v4
	v_mov_b32_e32 v14, v4
	v_mov_b32_e32 v15, v4
	v_mov_b32_e32 v44, v4
	v_mov_b32_e32 v45, v4
	v_mov_b32_e32 v46, v4
	v_mov_b32_e32 v47, v4
	v_mov_b32_e32 v16, v4
	v_mov_b32_e32 v17, v4
	v_mov_b32_e32 v18, v4
	v_mov_b32_e32 v19, v4
	v_mov_b32_e32 v48, v4
	v_mov_b32_e32 v49, v4
	v_mov_b32_e32 v50, v4
	v_mov_b32_e32 v51, v4
	v_mov_b32_e32 v68, v4
	v_mov_b32_e32 v69, v4
	v_mov_b32_e32 v70, v4
	v_mov_b32_e32 v71, v4
	v_mov_b32_e32 v100, v4
	v_mov_b32_e32 v101, v4
	v_mov_b32_e32 v102, v4
	v_mov_b32_e32 v103, v4
	v_mov_b32_e32 v72, v4
	v_mov_b32_e32 v73, v4
	v_mov_b32_e32 v74, v4
	v_mov_b32_e32 v75, v4
	v_mov_b32_e32 v104, v4
	v_mov_b32_e32 v105, v4
	v_mov_b32_e32 v106, v4
	v_mov_b32_e32 v107, v4
	v_mov_b32_e32 v76, v4
	v_mov_b32_e32 v77, v4
	v_mov_b32_e32 v78, v4
	v_mov_b32_e32 v79, v4
	v_mov_b32_e32 v108, v4
	v_mov_b32_e32 v109, v4
	v_mov_b32_e32 v110, v4
	v_mov_b32_e32 v111, v4
	v_mov_b32_e32 v80, v4
	v_mov_b32_e32 v81, v4
	v_mov_b32_e32 v82, v4
	v_mov_b32_e32 v83, v4
	v_mov_b32_e32 v112, v4
	v_mov_b32_e32 v113, v4
	v_mov_b32_e32 v114, v4
	v_mov_b32_e32 v115, v4
	v_mov_b32_e32 v20, v4
	v_mov_b32_e32 v21, v4
	v_mov_b32_e32 v22, v4
	v_mov_b32_e32 v23, v4
	v_mov_b32_e32 v52, v4
	v_mov_b32_e32 v53, v4
	v_mov_b32_e32 v54, v4
	v_mov_b32_e32 v55, v4
	v_mov_b32_e32 v24, v4
	v_mov_b32_e32 v25, v4
	v_mov_b32_e32 v26, v4
	v_mov_b32_e32 v27, v4
	v_mov_b32_e32 v56, v4
	v_mov_b32_e32 v57, v4
	v_mov_b32_e32 v58, v4
	v_mov_b32_e32 v59, v4
	v_mov_b32_e32 v28, v4
	v_mov_b32_e32 v29, v4
	v_mov_b32_e32 v30, v4
	v_mov_b32_e32 v31, v4
	v_mov_b32_e32 v60, v4
	v_mov_b32_e32 v61, v4
	v_mov_b32_e32 v62, v4
	v_mov_b32_e32 v63, v4
	v_mov_b32_e32 v32, v4
	v_mov_b32_e32 v33, v4
	v_mov_b32_e32 v34, v4
	v_mov_b32_e32 v35, v4
	v_mov_b32_e32 v64, v4
	v_mov_b32_e32 v65, v4
	v_mov_b32_e32 v66, v4
	v_mov_b32_e32 v67, v4
	v_mov_b32_e32 v84, v4
	v_mov_b32_e32 v85, v4
	v_mov_b32_e32 v86, v4
	v_mov_b32_e32 v87, v4
	v_mov_b32_e32 v116, v4
	v_mov_b32_e32 v117, v4
	v_mov_b32_e32 v118, v4
	v_mov_b32_e32 v119, v4
	v_mov_b32_e32 v88, v4
	v_mov_b32_e32 v89, v4
	v_mov_b32_e32 v90, v4
	v_mov_b32_e32 v91, v4
	v_mov_b32_e32 v120, v4
	v_mov_b32_e32 v121, v4
	v_mov_b32_e32 v122, v4
	v_mov_b32_e32 v123, v4
	v_mov_b32_e32 v92, v4
	v_mov_b32_e32 v93, v4
	v_mov_b32_e32 v94, v4
	v_mov_b32_e32 v95, v4
	v_mov_b32_e32 v124, v4
	v_mov_b32_e32 v125, v4
	v_mov_b32_e32 v126, v4
	v_mov_b32_e32 v127, v4
	v_mov_b32_e32 v96, v4
	v_mov_b32_e32 v97, v4
	v_mov_b32_e32 v98, v4
	v_mov_b32_e32 v99, v4
	v_mov_b32_e32 v128, v4
	v_mov_b32_e32 v129, v4
	v_mov_b32_e32 v130, v4
	v_mov_b32_e32 v131, v4
	s_cselect_b32 s99, 1, 0
	v_readfirstlane_b32 s98, v173
	s_nop 0
	s_cmpk_lt_u32 s98, 0x100
	s_cbranch_scc1 .Lprio_skip_LBB0251
	s_setprio 1

; #define PG8_STAGE(bufoff, gbase, voff) do { _Pragma("unroll") for (int _i = 0; _i < 2; ++_i) \
;         __builtin_amdgcn_global_load_lds((const unsigned*)((const char*)(gbase) + (voff)[_i]), (LAS unsigned*)(lds + (bufoff) + ldsw + _i * 8192), 16, 0, 0); } while (0)
; #define PG8_LDA(dst, b, h) do { _Pragma("unroll") for (int m = 0; m < 4; ++m) _Pragma("unroll") for (int k = 0; k < 2; ++k) dst[m][k] = *(const LAS bf16x8*)(lds + PG8_SA(b, h) + aoff + m * 2048 + k * 1024); } while (0)
; #define PG8_LDB(dst, b, h) do { _Pragma("unroll") for (int n = 0; n < 2; ++n) _Pragma("unroll") for (int k = 0; k < 2; ++k) dst[n][k] = *(const LAS bf16x8*)(lds + PG8_SB(b, h) + boff + n * 2048 + k * 1024); } while (0)
; #define PG8_MMA(ai, bj, At, Bt) do { __builtin_amdgcn_s_setprio(1); _Pragma("unroll") for (int m = 0; m < 4; ++m) _Pragma("unroll") for (int n = 0; n < 2; ++n) _Pragma("unroll") for (int k = 0; k < 2; ++k) \
;         acc[ai][bj][m][n] = __builtin_amdgcn_mfma_f32_16x16x32_bf16(Bt[n][k], At[m][k], acc[ai][bj][m][n], 0, 0, 0); __builtin_amdgcn_s_setprio(0); } while (0)
; #define PG8_WAIT_V(n) asm volatile("s_waitcnt vmcnt(" #n ")" ::: "memory")
; #define PG8_WAIT_L(n) asm volatile("s_waitcnt lgkmcnt(" #n ")" ::: "memory")
; #define PG8_BAR __builtin_amdgcn_s_barrier()
; #define PG8_SCHED __builtin_amdgcn_sched_barrier(0)
; template <class Epi, class Sched>
; __device__ __forceinline__ void gemm_phase(LAS unsigned char* lds, const Gemm g, const Sched& S, const Epi& E, const int tid) {
;     ...
;             const bool last = (t == nt - 2);
;             const char* a1 = cA + (size_t)(t + 1) * kstep;
;             const char* a2 = last ? nA : cA + (size_t)(t + 2) * kstep; const char* b2 = last ? nB : cB + (size_t)(t + 2) * kstep;
;             const char* a3 = a2 + kstep; const char* b3 = b2 + kstep;
;             PG8_LDB(B0, 0, 0); PG8_LDB(B1, 0, 1); PG8_SCHED; PG8_LDA(At, 0, 0); PG8_STAGE(PG8_SA(1, 1), a1 + hstepA, voffA);
;             PG8_WAIT_V(8); PG8_WAIT_L(0); PG8_BAR; PG8_MMA(0, 0, At, B0); PG8_MMA(0, 1, At, B1); PG8_BAR; PG8_SCHED;
;             PG8_LDA(At, 0, 1); PG8_STAGE(PG8_SB(0, 0), b2, voffB); PG8_STAGE(PG8_SB(0, 1), b2 + hstepB, voffB); PG8_STAGE(PG8_SA(0, 0), a2, voffA);
.LBB0_251:
	s_add_u32 s8, s86, 0x100
	s_addc_u32 s9, s87, 0
	s_add_i32 s13, 0, 0x10000
	s_cmp_eq_u32 s12, 28
	s_cselect_b32 s91, s47, s9
	s_cselect_b32 s90, s46, s8
	s_cselect_b32 s89, s17, vcc_hi
	s_cselect_b32 s88, s45, vcc_lo
	s_add_i32 s74, 0, 0x14000
	v_add_u32_e32 v154, s13, v233
	v_add_u32_e32 v162, s74, v233
	ds_read_b128 v[142:145], v154
	ds_read_b128 v[146:149], v154 offset:1024
	ds_read_b128 v[150:153], v154 offset:2048
	ds_read_b128 v[154:157], v154 offset:3072
	ds_read_b128 v[158:161], v162
	ds_read_b128 v[174:177], v162 offset:1024
	ds_read_b128 v[178:181], v162 offset:2048
	ds_read_b128 v[182:185], v162 offset:3072
	v_lshl_add_u64 v[162:163], s[86:87], 0, v[138:139]
	s_add_i32 m0, s79, 0xc000
	ds_read_b128 v[186:189], v235
	ds_read_b128 v[190:193], v235 offset:1024
	ds_read_b128 v[194:197], v235 offset:2048
	ds_read_b128 v[198:201], v235 offset:3072
	ds_read_b128 v[202:205], v235 offset:4096
	ds_read_b128 v[210:213], v235 offset:5120
	ds_read_b128 v[220:223], v235 offset:6144
	ds_read_b128 v[236:239], v235 offset:7168
	global_load_lds_dwordx4 v[162:163], off
	v_lshl_add_u64 v[162:163], s[86:87], 0, v[140:141]
	s_add_i32 m0, s79, 0xe000
	s_nop 0
	global_load_lds_dwordx4 v[162:163], off
	s_waitcnt vmcnt(8)
	s_waitcnt lgkmcnt(0)
	s_barrier
	s_waitcnt lgkmcnt(0)
	v_mfma_f32_16x16x32_bf16 v[128:131], v[142:145], v[186:189], v[128:131]
	v_mfma_f32_16x16x32_bf16 v[96:99], v[150:153], v[186:189], v[96:99]
	v_mfma_f32_16x16x32_bf16 v[124:127], v[142:145], v[194:197], v[124:127]
	v_mfma_f32_16x16x32_bf16 v[92:95], v[150:153], v[194:197], v[92:95]
	v_mfma_f32_16x16x32_bf16 v[120:123], v[142:145], v[202:205], v[120:123]
	v_mfma_f32_16x16x32_bf16 v[88:91], v[150:153], v[202:205], v[88:91]
	v_mfma_f32_16x16x32_bf16 v[116:119], v[142:145], v[220:223], v[116:119]
	v_mfma_f32_16x16x32_bf16 v[84:87], v[150:153], v[220:223], v[84:87]
	v_mfma_f32_16x16x32_bf16 v[128:131], v[146:149], v[190:193], v[128:131]
	v_mfma_f32_16x16x32_bf16 v[96:99], v[154:157], v[190:193], v[96:99]
	v_mfma_f32_16x16x32_bf16 v[124:127], v[146:149], v[198:201], v[124:127]
	v_mfma_f32_16x16x32_bf16 v[92:95], v[154:157], v[198:201], v[92:95]
	v_mfma_f32_16x16x32_bf16 v[120:123], v[146:149], v[210:213], v[120:123]
	v_mfma_f32_16x16x32_bf16 v[88:91], v[154:157], v[210:213], v[88:91]
	v_mfma_f32_16x16x32_bf16 v[116:119], v[146:149], v[236:239], v[116:119]
	v_mfma_f32_16x16x32_bf16 v[84:87], v[154:157], v[236:239], v[84:87]
	v_mfma_f32_16x16x32_bf16 v[64:67], v[158:161], v[186:189], v[64:67]
	v_mfma_f32_16x16x32_bf16 v[32:35], v[178:181], v[186:189], v[32:35]
	v_mfma_f32_16x16x32_bf16 v[60:63], v[158:161], v[194:197], v[60:63]
	v_mfma_f32_16x16x32_bf16 v[28:31], v[178:181], v[194:197], v[28:31]
	v_mfma_f32_16x16x32_bf16 v[56:59], v[158:161], v[202:205], v[56:59]
	v_mfma_f32_16x16x32_bf16 v[24:27], v[178:181], v[202:205], v[24:27]
	v_mfma_f32_16x16x32_bf16 v[52:55], v[158:161], v[220:223], v[52:55]
	v_mfma_f32_16x16x32_bf16 v[20:23], v[178:181], v[220:223], v[20:23]
	v_mfma_f32_16x16x32_bf16 v[64:67], v[174:177], v[190:193], v[64:67]
	v_mfma_f32_16x16x32_bf16 v[32:35], v[182:185], v[190:193], v[32:35]
	v_mfma_f32_16x16x32_bf16 v[60:63], v[174:177], v[198:201], v[60:63]
	v_mfma_f32_16x16x32_bf16 v[28:31], v[182:185], v[198:201], v[28:31]
	v_mfma_f32_16x16x32_bf16 v[56:59], v[174:177], v[210:213], v[56:59]
	v_mfma_f32_16x16x32_bf16 v[24:27], v[182:185], v[210:213], v[24:27]
	v_mfma_f32_16x16x32_bf16 v[52:55], v[174:177], v[236:239], v[52:55]
	v_mfma_f32_16x16x32_bf16 v[20:23], v[182:185], v[236:239], v[20:23]
	s_barrier
	s_add_i32 s13, s13, s59
	v_lshl_add_u64 v[162:163], s[88:89], 0, v[164:165]
	s_mov_b32 m0, s13
	ds_read_b128 v[186:189], v235 offset:16384
	ds_read_b128 v[190:193], v235 offset:17408
	ds_read_b128 v[194:197], v235 offset:18432
	ds_read_b128 v[198:201], v235 offset:19456
	ds_read_b128 v[202:205], v235 offset:20480
	ds_read_b128 v[210:213], v235 offset:21504
	ds_read_b128 v[220:223], v235 offset:22528
	ds_read_b128 v[236:239], v235 offset:23552
	global_load_lds_dwordx4 v[162:163], off
	s_add_i32 m0, s13, 0x2000
	s_add_u32 s86, s88, 0x80000
	v_lshl_add_u64 v[206:207], s[88:89], 0, v[136:137]
	s_addc_u32 s87, s89, 0
	s_add_i32 s13, s74, s59
	global_load_lds_dwordx4 v[206:207], off
	v_lshl_add_u64 v[224:225], s[86:87], 0, v[164:165]
	s_mov_b32 m0, s13
	v_lshl_add_u64 v[226:227], s[90:91], 0, v[134:135]
	global_load_lds_dwordx4 v[224:225], off
	v_lshl_add_u64 v[224:225], s[86:87], 0, v[136:137]
	s_add_i32 m0, s13, 0x2000
	s_nop 0
	global_load_lds_dwordx4 v[224:225], off
	v_lshl_add_u64 v[224:225], s[90:91], 0, v[132:133]
	s_mov_b32 m0, s79
	s_nop 0
	global_load_lds_dwordx4 v[224:225], off
	s_mov_b32 m0, s84
	s_nop 0
	global_load_lds_dwordx4 v[226:227], off
	s_waitcnt vmcnt(8)
	s_waitcnt lgkmcnt(0)
	s_barrier
; #define PG8_STAGE(bufoff, gbase, voff) do { _Pragma("unroll") for (int _i = 0; _i < 2; ++_i) \
;         __builtin_amdgcn_global_load_lds((const unsigned*)((const char*)(gbase) + (voff)[_i]), (LAS unsigned*)(lds + (bufoff) + ldsw + _i * 8192), 16, 0, 0); } while (0)
; #define PG8_LDA(dst, b, h) do { _Pragma("unroll") for (int m = 0; m < 4; ++m) _Pragma("unroll") for (int k = 0; k < 2; ++k) dst[m][k] = *(const LAS bf16x8*)(lds + PG8_SA(b, h) + aoff + m * 2048 + k * 1024); } while (0)
; #define PG8_LDB(dst, b, h) do { _Pragma("unroll") for (int n = 0; n < 2; ++n) _Pragma("unroll") for (int k = 0; k < 2; ++k) dst[n][k] = *(const LAS bf16x8*)(lds + PG8_SB(b, h) + boff + n * 2048 + k * 1024); } while (0)
; #define PG8_MMA(ai, bj, At, Bt) do { __builtin_amdgcn_s_setprio(1); _Pragma("unroll") for (int m = 0; m < 4; ++m) _Pragma("unroll") for (int n = 0; n < 2; ++n) _Pragma("unroll") for (int k = 0; k < 2; ++k) \
;         acc[ai][bj][m][n] = __builtin_amdgcn_mfma_f32_16x16x32_bf16(Bt[n][k], At[m][k], acc[ai][bj][m][n], 0, 0, 0); __builtin_amdgcn_s_setprio(0); } while (0)
; #define PG8_WAIT_V(n) asm volatile("s_waitcnt vmcnt(" #n ")" ::: "memory")
; #define PG8_WAIT_L(n) asm volatile("s_waitcnt lgkmcnt(" #n ")" ::: "memory")
; #define PG8_BAR __builtin_amdgcn_s_barrier()
; #define PG8_SCHED __builtin_amdgcn_sched_barrier(0)
; template <class Epi, class Sched>
; __device__ __forceinline__ void gemm_phase(LAS unsigned char* lds, const Gemm g, const Sched& S, const Epi& E, const int tid) {
;     ...
;             PG8_WAIT_V(8); PG8_WAIT_L(0); PG8_BAR; PG8_MMA(1, 0, At, B0); PG8_MMA(1, 1, At, B1); PG8_BAR; PG8_SCHED;
;             PG8_LDB(B0, 1, 0); PG8_LDB(B1, 1, 1); PG8_SCHED; PG8_LDA(At, 1, 0); PG8_STAGE(PG8_SA(0, 1), a2 + hstepA, voffA);
;             PG8_WAIT_V(8); PG8_WAIT_L(0); PG8_BAR; PG8_MMA(0, 0, At, B0); PG8_MMA(0, 1, At, B1); PG8_BAR; PG8_SCHED;
	s_waitcnt lgkmcnt(0)
	v_mfma_f32_16x16x32_bf16 v[112:115], v[142:145], v[186:189], v[112:115]
	v_mfma_f32_16x16x32_bf16 v[80:83], v[150:153], v[186:189], v[80:83]
	v_mfma_f32_16x16x32_bf16 v[108:111], v[142:145], v[194:197], v[108:111]
	v_mfma_f32_16x16x32_bf16 v[76:79], v[150:153], v[194:197], v[76:79]
	v_mfma_f32_16x16x32_bf16 v[104:107], v[142:145], v[202:205], v[104:107]
	v_mfma_f32_16x16x32_bf16 v[72:75], v[150:153], v[202:205], v[72:75]
	v_mfma_f32_16x16x32_bf16 v[100:103], v[142:145], v[220:223], v[100:103]
	v_mfma_f32_16x16x32_bf16 v[68:71], v[150:153], v[220:223], v[68:71]
	v_mfma_f32_16x16x32_bf16 v[112:115], v[146:149], v[190:193], v[112:115]
	v_mfma_f32_16x16x32_bf16 v[80:83], v[154:157], v[190:193], v[80:83]
	v_mfma_f32_16x16x32_bf16 v[108:111], v[146:149], v[198:201], v[108:111]
	v_mfma_f32_16x16x32_bf16 v[76:79], v[154:157], v[198:201], v[76:79]
	v_mfma_f32_16x16x32_bf16 v[104:107], v[146:149], v[210:213], v[104:107]
	v_mfma_f32_16x16x32_bf16 v[72:75], v[154:157], v[210:213], v[72:75]
	v_mfma_f32_16x16x32_bf16 v[100:103], v[146:149], v[236:239], v[100:103]
	v_mfma_f32_16x16x32_bf16 v[68:71], v[154:157], v[236:239], v[68:71]
	v_mfma_f32_16x16x32_bf16 v[48:51], v[158:161], v[186:189], v[48:51]
	v_mfma_f32_16x16x32_bf16 v[16:19], v[178:181], v[186:189], v[16:19]
	v_mfma_f32_16x16x32_bf16 v[44:47], v[158:161], v[194:197], v[44:47]
	v_mfma_f32_16x16x32_bf16 v[12:15], v[178:181], v[194:197], v[12:15]
	v_mfma_f32_16x16x32_bf16 v[40:43], v[158:161], v[202:205], v[40:43]
	v_mfma_f32_16x16x32_bf16 v[8:11], v[178:181], v[202:205], v[8:11]
	v_mfma_f32_16x16x32_bf16 v[36:39], v[158:161], v[220:223], v[36:39]
	v_mfma_f32_16x16x32_bf16 v[4:7], v[178:181], v[220:223], v[4:7]
	v_mfma_f32_16x16x32_bf16 v[48:51], v[174:177], v[190:193], v[48:51]
	v_mfma_f32_16x16x32_bf16 v[16:19], v[182:185], v[190:193], v[16:19]
	v_mfma_f32_16x16x32_bf16 v[44:47], v[174:177], v[198:201], v[44:47]
	v_mfma_f32_16x16x32_bf16 v[12:15], v[182:185], v[198:201], v[12:15]
	v_mfma_f32_16x16x32_bf16 v[40:43], v[174:177], v[210:213], v[40:43]
	v_mfma_f32_16x16x32_bf16 v[8:11], v[182:185], v[210:213], v[8:11]
	v_mfma_f32_16x16x32_bf16 v[36:39], v[174:177], v[236:239], v[36:39]
	v_mfma_f32_16x16x32_bf16 v[4:7], v[182:185], v[236:239], v[4:7]
	s_barrier
	s_add_i32 s13, 0, 0x18000
	s_add_i32 s74, 0, 0x1c000
	v_add_u32_e32 v154, s13, v233
	v_add_u32_e32 v182, s74, v233
	ds_read_b128 v[142:145], v154
	ds_read_b128 v[146:149], v154 offset:1024
	ds_read_b128 v[150:153], v154 offset:2048
	ds_read_b128 v[154:157], v154 offset:3072
	ds_read_b128 v[158:161], v182
	ds_read_b128 v[174:177], v182 offset:1024
	ds_read_b128 v[178:181], v182 offset:2048
	ds_read_b128 v[182:185], v182 offset:3072
	s_add_u32 s86, s90, 0x242000
	s_addc_u32 s87, s91, 0
	s_mov_b32 m0, s85
	v_lshl_add_u64 v[240:241], s[86:87], 0, v[132:133]
	ds_read_b128 v[186:189], v235 offset:32768
	ds_read_b128 v[190:193], v235 offset:33792
	ds_read_b128 v[194:197], v235 offset:34816
	ds_read_b128 v[198:201], v235 offset:35840
	ds_read_b128 v[202:205], v235 offset:36864
	ds_read_b128 v[210:213], v235 offset:37888
	ds_read_b128 v[220:223], v235 offset:38912
	ds_read_b128 v[236:239], v235 offset:39936
	global_load_lds_dwordx4 v[240:241], off
	v_lshl_add_u64 v[240:241], s[86:87], 0, v[134:135]
	s_mov_b32 m0, s92
	s_nop 0
	global_load_lds_dwordx4 v[240:241], off
	s_waitcnt vmcnt(8)
	s_waitcnt lgkmcnt(0)
	s_barrier
	s_waitcnt lgkmcnt(0)
	v_mfma_f32_16x16x32_bf16 v[128:131], v[142:145], v[186:189], v[128:131]
	v_mfma_f32_16x16x32_bf16 v[96:99], v[150:153], v[186:189], v[96:99]
	v_mfma_f32_16x16x32_bf16 v[124:127], v[142:145], v[194:197], v[124:127]
	v_mfma_f32_16x16x32_bf16 v[92:95], v[150:153], v[194:197], v[92:95]
	v_mfma_f32_16x16x32_bf16 v[120:123], v[142:145], v[202:205], v[120:123]
	v_mfma_f32_16x16x32_bf16 v[88:91], v[150:153], v[202:205], v[88:91]
	v_mfma_f32_16x16x32_bf16 v[116:119], v[142:145], v[220:223], v[116:119]
	v_mfma_f32_16x16x32_bf16 v[84:87], v[150:153], v[220:223], v[84:87]
	v_mfma_f32_16x16x32_bf16 v[128:131], v[146:149], v[190:193], v[128:131]
	v_mfma_f32_16x16x32_bf16 v[96:99], v[154:157], v[190:193], v[96:99]
	v_mfma_f32_16x16x32_bf16 v[124:127], v[146:149], v[198:201], v[124:127]
	v_mfma_f32_16x16x32_bf16 v[92:95], v[154:157], v[198:201], v[92:95]
	v_mfma_f32_16x16x32_bf16 v[120:123], v[146:149], v[210:213], v[120:123]
	v_mfma_f32_16x16x32_bf16 v[88:91], v[154:157], v[210:213], v[88:91]
	v_mfma_f32_16x16x32_bf16 v[116:119], v[146:149], v[236:239], v[116:119]
	v_mfma_f32_16x16x32_bf16 v[84:87], v[154:157], v[236:239], v[84:87]
	v_mfma_f32_16x16x32_bf16 v[64:67], v[158:161], v[186:189], v[64:67]
	v_mfma_f32_16x16x32_bf16 v[32:35], v[178:181], v[186:189], v[32:35]
	v_mfma_f32_16x16x32_bf16 v[60:63], v[158:161], v[194:197], v[60:63]
	v_mfma_f32_16x16x32_bf16 v[28:31], v[178:181], v[194:197], v[28:31]
	v_mfma_f32_16x16x32_bf16 v[56:59], v[158:161], v[202:205], v[56:59]
	v_mfma_f32_16x16x32_bf16 v[24:27], v[178:181], v[202:205], v[24:27]
	v_mfma_f32_16x16x32_bf16 v[52:55], v[158:161], v[220:223], v[52:55]
	v_mfma_f32_16x16x32_bf16 v[20:23], v[178:181], v[220:223], v[20:23]
	v_mfma_f32_16x16x32_bf16 v[64:67], v[174:177], v[190:193], v[64:67]
	v_mfma_f32_16x16x32_bf16 v[32:35], v[182:185], v[190:193], v[32:35]
	v_mfma_f32_16x16x32_bf16 v[60:63], v[174:177], v[198:201], v[60:63]
	v_mfma_f32_16x16x32_bf16 v[28:31], v[182:185], v[198:201], v[28:31]
	v_mfma_f32_16x16x32_bf16 v[56:59], v[174:177], v[210:213], v[56:59]
	v_mfma_f32_16x16x32_bf16 v[24:27], v[182:185], v[210:213], v[24:27]
	v_mfma_f32_16x16x32_bf16 v[52:55], v[174:177], v[236:239], v[52:55]
	v_mfma_f32_16x16x32_bf16 v[20:23], v[182:185], v[236:239], v[20:23]
	s_barrier
; #define PG8_STAGE(bufoff, gbase, voff) do { _Pragma("unroll") for (int _i = 0; _i < 2; ++_i) \
;         __builtin_amdgcn_global_load_lds((const unsigned*)((const char*)(gbase) + (voff)[_i]), (LAS unsigned*)(lds + (bufoff) + ldsw + _i * 8192), 16, 0, 0); } while (0)
; #define PG8_LDA(dst, b, h) do { _Pragma("unroll") for (int m = 0; m < 4; ++m) _Pragma("unroll") for (int k = 0; k < 2; ++k) dst[m][k] = *(const LAS bf16x8*)(lds + PG8_SA(b, h) + aoff + m * 2048 + k * 1024); } while (0)
; #define PG8_MMA(ai, bj, At, Bt) do { __builtin_amdgcn_s_setprio(1); _Pragma("unroll") for (int m = 0; m < 4; ++m) _Pragma("unroll") for (int n = 0; n < 2; ++n) _Pragma("unroll") for (int k = 0; k < 2; ++k) \
;         acc[ai][bj][m][n] = __builtin_amdgcn_mfma_f32_16x16x32_bf16(Bt[n][k], At[m][k], acc[ai][bj][m][n], 0, 0, 0); __builtin_amdgcn_s_setprio(0); } while (0)
; #define PG8_WAIT_V(n) asm volatile("s_waitcnt vmcnt(" #n ")" ::: "memory")
; #define PG8_WAIT_L(n) asm volatile("s_waitcnt lgkmcnt(" #n ")" ::: "memory")
; #define PG8_BAR __builtin_amdgcn_s_barrier()
; #define PG8_SCHED __builtin_amdgcn_sched_barrier(0)
; template <class Epi, class Sched>
; __device__ __forceinline__ void gemm_phase(LAS unsigned char* lds, const Gemm g, const Sched& S, const Epi& E, const int tid) {
;     ...
;             PG8_LDA(At, 1, 1); PG8_STAGE(PG8_SB(1, 0), b3, voffB); PG8_STAGE(PG8_SB(1, 1), b3 + hstepB, voffB); PG8_STAGE(PG8_SA(1, 0), a3, voffA);
;             PG8_WAIT_V(8); PG8_WAIT_L(0); PG8_BAR; PG8_MMA(1, 0, At, B0); PG8_MMA(1, 1, At, B1); PG8_BAR; PG8_SCHED;
;         }
;         if (wr == 0) PG8_BAR;
	s_add_i32 s13, s13, s59
	v_lshl_add_u64 v[162:163], v[162:163], 0, s[28:29]
	s_mov_b32 m0, s13
	ds_read_b128 v[186:189], v235 offset:49152
	ds_read_b128 v[190:193], v235 offset:50176
	ds_read_b128 v[194:197], v235 offset:51200
	ds_read_b128 v[198:201], v235 offset:52224
	ds_read_b128 v[202:205], v235 offset:53248
	ds_read_b128 v[210:213], v235 offset:54272
	ds_read_b128 v[220:223], v235 offset:55296
	ds_read_b128 v[236:239], v235 offset:56320
	global_load_lds_dwordx4 v[162:163], off
	s_add_i32 m0, s13, 0x2000
	s_add_u32 s86, s88, 0x80080
	v_lshl_add_u64 v[162:163], v[206:207], 0, s[28:29]
	s_addc_u32 s87, s89, 0
	s_add_i32 s13, s74, s59
	global_load_lds_dwordx4 v[162:163], off
	v_lshl_add_u64 v[162:163], s[86:87], 0, v[164:165]
	s_mov_b32 m0, s13
	s_nop 0
	global_load_lds_dwordx4 v[162:163], off
	v_lshl_add_u64 v[162:163], s[86:87], 0, v[136:137]
	s_add_i32 m0, s13, 0x2000
	s_nop 0
	global_load_lds_dwordx4 v[162:163], off
	v_lshl_add_u64 v[162:163], v[224:225], 0, s[28:29]
	s_mov_b32 m0, s93
	s_nop 0
	global_load_lds_dwordx4 v[162:163], off
	v_lshl_add_u64 v[162:163], v[226:227], 0, s[28:29]
	s_mov_b32 m0, s94
	s_nop 0
	global_load_lds_dwordx4 v[162:163], off
	s_waitcnt vmcnt(8)
	s_waitcnt lgkmcnt(0)
	s_barrier
	s_waitcnt lgkmcnt(0)
	v_mfma_f32_16x16x32_bf16 v[112:115], v[142:145], v[186:189], v[112:115]
	v_mfma_f32_16x16x32_bf16 v[80:83], v[150:153], v[186:189], v[80:83]
	v_mfma_f32_16x16x32_bf16 v[108:111], v[142:145], v[194:197], v[108:111]
	v_mfma_f32_16x16x32_bf16 v[76:79], v[150:153], v[194:197], v[76:79]
	v_mfma_f32_16x16x32_bf16 v[104:107], v[142:145], v[202:205], v[104:107]
	v_mfma_f32_16x16x32_bf16 v[72:75], v[150:153], v[202:205], v[72:75]
	v_mfma_f32_16x16x32_bf16 v[100:103], v[142:145], v[220:223], v[100:103]
	v_mfma_f32_16x16x32_bf16 v[68:71], v[150:153], v[220:223], v[68:71]
	v_mfma_f32_16x16x32_bf16 v[112:115], v[146:149], v[190:193], v[112:115]
	v_mfma_f32_16x16x32_bf16 v[80:83], v[154:157], v[190:193], v[80:83]
	v_mfma_f32_16x16x32_bf16 v[108:111], v[146:149], v[198:201], v[108:111]
	v_mfma_f32_16x16x32_bf16 v[76:79], v[154:157], v[198:201], v[76:79]
	v_mfma_f32_16x16x32_bf16 v[104:107], v[146:149], v[210:213], v[104:107]
	v_mfma_f32_16x16x32_bf16 v[72:75], v[154:157], v[210:213], v[72:75]
	v_mfma_f32_16x16x32_bf16 v[100:103], v[146:149], v[236:239], v[100:103]
	v_mfma_f32_16x16x32_bf16 v[68:71], v[154:157], v[236:239], v[68:71]
	v_mfma_f32_16x16x32_bf16 v[48:51], v[158:161], v[186:189], v[48:51]
	v_mfma_f32_16x16x32_bf16 v[16:19], v[178:181], v[186:189], v[16:19]
	v_mfma_f32_16x16x32_bf16 v[44:47], v[158:161], v[194:197], v[44:47]
	v_mfma_f32_16x16x32_bf16 v[12:15], v[178:181], v[194:197], v[12:15]
	v_mfma_f32_16x16x32_bf16 v[40:43], v[158:161], v[202:205], v[40:43]
	v_mfma_f32_16x16x32_bf16 v[8:11], v[178:181], v[202:205], v[8:11]
	v_mfma_f32_16x16x32_bf16 v[36:39], v[158:161], v[220:223], v[36:39]
	v_mfma_f32_16x16x32_bf16 v[4:7], v[178:181], v[220:223], v[4:7]
	v_mfma_f32_16x16x32_bf16 v[48:51], v[174:177], v[190:193], v[48:51]
	v_mfma_f32_16x16x32_bf16 v[16:19], v[182:185], v[190:193], v[16:19]
	v_mfma_f32_16x16x32_bf16 v[44:47], v[174:177], v[198:201], v[44:47]
	v_mfma_f32_16x16x32_bf16 v[12:15], v[182:185], v[198:201], v[12:15]
	v_mfma_f32_16x16x32_bf16 v[40:43], v[174:177], v[210:213], v[40:43]
	v_mfma_f32_16x16x32_bf16 v[8:11], v[182:185], v[210:213], v[8:11]
	v_mfma_f32_16x16x32_bf16 v[36:39], v[174:177], v[236:239], v[36:39]
	v_mfma_f32_16x16x32_bf16 v[4:7], v[182:185], v[236:239], v[4:7]
	s_barrier
	s_add_i32 s12, s12, 2
	s_add_u32 vcc_lo, vcc_lo, 0x100
	s_addc_u32 vcc_hi, vcc_hi, 0
	s_cmp_gt_u32 s12, 29
	s_mov_b64 s[86:87], s[8:9]
	s_cbranch_scc0 .LBB0_251
	s_setprio 0
	s_and_b64 vcc, exec, s[42:43]
	s_cbranch_vccz .LBB0_254
	s_barrier

; template <class Epi, class Sched>
; __device__ __forceinline__ void gemm_phase(LAS unsigned char* lds, const Gemm g, const Sched& S, const Epi& E, const int tid) {
;     ...
;     for (;;) {
;         const bool has_next = S.next(ui + 1, nxt);
;         const char* nA = has_next ? (const char*)g.A + (size_t)nxt.pm * tstepA : cA; const char* nB = has_next ? (const char*)g.Bt + (size_t)nxt.pn * tstepB : cB;
;         for (int t = 0; t < nt; t += 2) {
;     ...
; #pragma unroll
;         for (int a = 0; a < 2; ++a)
; #pragma unroll
;             for (int b = 0; b < 2; ++b)
; #pragma unroll
;                 for (int m = 0; m < 4; ++m)
; #pragma unroll
;                     for (int n = 0; n < 2; ++n) acc[a][b][m][n] = (f32x4){0.f, 0.f, 0.f, 0.f};
.LBB0_278:
	s_ashr_i32 s31, s30, 31
	s_lshl_b64 s[12:13], s[30:31], 20
	s_add_u32 s42, s56, s12
	s_addc_u32 s43, s57, s13
	s_and_b64 s[8:9], s[8:9], exec
	s_cselect_b32 s16, s43, s47
	s_cselect_b32 s17, s42, s46
	s_add_u32 s31, s46, 0x100
	v_mov_b32_e32 v4, 0
	s_addc_u32 s93, s47, 0
	s_mov_b32 s94, -2
	v_mov_b32_e32 v5, v4
	v_mov_b32_e32 v6, v4
	v_mov_b32_e32 v7, v4
	v_mov_b32_e32 v36, v4
	v_mov_b32_e32 v37, v4
	v_mov_b32_e32 v38, v4
	v_mov_b32_e32 v39, v4
	v_mov_b32_e32 v8, v4
	v_mov_b32_e32 v9, v4
	v_mov_b32_e32 v10, v4
	v_mov_b32_e32 v11, v4
	v_mov_b32_e32 v40, v4
	v_mov_b32_e32 v41, v4
	v_mov_b32_e32 v42, v4
	v_mov_b32_e32 v43, v4
	v_mov_b32_e32 v12, v4
	v_mov_b32_e32 v13, v4
	v_mov_b32_e32 v14, v4
	v_mov_b32_e32 v15, v4
	v_mov_b32_e32 v44, v4
	v_mov_b32_e32 v45, v4
	v_mov_b32_e32 v46, v4
	v_mov_b32_e32 v47, v4
	v_mov_b32_e32 v16, v4
	v_mov_b32_e32 v17, v4
	v_mov_b32_e32 v18, v4
	v_mov_b32_e32 v19, v4
	v_mov_b32_e32 v48, v4
	v_mov_b32_e32 v49, v4
	v_mov_b32_e32 v50, v4
	v_mov_b32_e32 v51, v4
	v_mov_b32_e32 v68, v4
	v_mov_b32_e32 v69, v4
	v_mov_b32_e32 v70, v4
	v_mov_b32_e32 v71, v4
	v_mov_b32_e32 v100, v4
	v_mov_b32_e32 v101, v4
	v_mov_b32_e32 v102, v4
	v_mov_b32_e32 v103, v4
	v_mov_b32_e32 v72, v4
	v_mov_b32_e32 v73, v4
	v_mov_b32_e32 v74, v4
	v_mov_b32_e32 v75, v4
	v_mov_b32_e32 v104, v4
	v_mov_b32_e32 v105, v4
	v_mov_b32_e32 v106, v4
	v_mov_b32_e32 v107, v4
	v_mov_b32_e32 v76, v4
	v_mov_b32_e32 v77, v4
	v_mov_b32_e32 v78, v4
	v_mov_b32_e32 v79, v4
	v_mov_b32_e32 v108, v4
	v_mov_b32_e32 v109, v4
	v_mov_b32_e32 v110, v4
	v_mov_b32_e32 v111, v4
	v_mov_b32_e32 v80, v4
	v_mov_b32_e32 v81, v4
	v_mov_b32_e32 v82, v4
	v_mov_b32_e32 v83, v4
	v_mov_b32_e32 v112, v4
	v_mov_b32_e32 v113, v4
	v_mov_b32_e32 v114, v4
	v_mov_b32_e32 v115, v4
	v_mov_b32_e32 v20, v4
	v_mov_b32_e32 v21, v4
	v_mov_b32_e32 v22, v4
	v_mov_b32_e32 v23, v4
	v_mov_b32_e32 v52, v4
	v_mov_b32_e32 v53, v4
	v_mov_b32_e32 v54, v4
	v_mov_b32_e32 v55, v4
	v_mov_b32_e32 v24, v4
	v_mov_b32_e32 v25, v4
	v_mov_b32_e32 v26, v4
	v_mov_b32_e32 v27, v4
	v_mov_b32_e32 v56, v4
	v_mov_b32_e32 v57, v4
	v_mov_b32_e32 v58, v4
	v_mov_b32_e32 v59, v4
	v_mov_b32_e32 v28, v4
	v_mov_b32_e32 v29, v4
	v_mov_b32_e32 v30, v4
	v_mov_b32_e32 v31, v4
	v_mov_b32_e32 v60, v4
	v_mov_b32_e32 v61, v4
	v_mov_b32_e32 v62, v4
	v_mov_b32_e32 v63, v4
	v_mov_b32_e32 v32, v4
	v_mov_b32_e32 v33, v4
	v_mov_b32_e32 v34, v4
	v_mov_b32_e32 v35, v4
	v_mov_b32_e32 v64, v4
	v_mov_b32_e32 v65, v4
	v_mov_b32_e32 v66, v4
	v_mov_b32_e32 v67, v4
	v_mov_b32_e32 v84, v4
	v_mov_b32_e32 v85, v4
	v_mov_b32_e32 v86, v4
	v_mov_b32_e32 v87, v4
	v_mov_b32_e32 v116, v4
	v_mov_b32_e32 v117, v4
	v_mov_b32_e32 v118, v4
	v_mov_b32_e32 v119, v4
	v_mov_b32_e32 v88, v4
	v_mov_b32_e32 v89, v4
	v_mov_b32_e32 v90, v4
	v_mov_b32_e32 v91, v4
	v_mov_b32_e32 v120, v4
	v_mov_b32_e32 v121, v4
	v_mov_b32_e32 v122, v4
	v_mov_b32_e32 v123, v4
	v_mov_b32_e32 v92, v4
	v_mov_b32_e32 v93, v4
	v_mov_b32_e32 v94, v4
	v_mov_b32_e32 v95, v4
	v_mov_b32_e32 v124, v4
	v_mov_b32_e32 v125, v4
	v_mov_b32_e32 v126, v4
	v_mov_b32_e32 v127, v4
	v_mov_b32_e32 v96, v4
	v_mov_b32_e32 v97, v4
	v_mov_b32_e32 v98, v4
	v_mov_b32_e32 v99, v4
	v_mov_b32_e32 v128, v4
	v_mov_b32_e32 v129, v4
	v_mov_b32_e32 v130, v4
	v_mov_b32_e32 v131, v4
	s_cselect_b32 s99, 1, 0
	v_readfirstlane_b32 s98, v173
	s_nop 0
	s_cmpk_lt_u32 s98, 0x100
	s_cbranch_scc1 .Lprio_skip_LBB0279
	s_setprio 1

; #define PG8_STAGE(bufoff, gbase, voff) do { _Pragma("unroll") for (int _i = 0; _i < 2; ++_i) \
;         __builtin_amdgcn_global_load_lds((const unsigned*)((const char*)(gbase) + (voff)[_i]), (LAS unsigned*)(lds + (bufoff) + ldsw + _i * 8192), 16, 0, 0); } while (0)
; #define PG8_LDA(dst, b, h) do { _Pragma("unroll") for (int m = 0; m < 4; ++m) _Pragma("unroll") for (int k = 0; k < 2; ++k) dst[m][k] = *(const LAS bf16x8*)(lds + PG8_SA(b, h) + aoff + m * 2048 + k * 1024); } while (0)
; #define PG8_LDB(dst, b, h) do { _Pragma("unroll") for (int n = 0; n < 2; ++n) _Pragma("unroll") for (int k = 0; k < 2; ++k) dst[n][k] = *(const LAS bf16x8*)(lds + PG8_SB(b, h) + boff + n * 2048 + k * 1024); } while (0)
; #define PG8_MMA(ai, bj, At, Bt) do { __builtin_amdgcn_s_setprio(1); _Pragma("unroll") for (int m = 0; m < 4; ++m) _Pragma("unroll") for (int n = 0; n < 2; ++n) _Pragma("unroll") for (int k = 0; k < 2; ++k) \
;         acc[ai][bj][m][n] = __builtin_amdgcn_mfma_f32_16x16x32_bf16(Bt[n][k], At[m][k], acc[ai][bj][m][n], 0, 0, 0); __builtin_amdgcn_s_setprio(0); } while (0)
; #define PG8_WAIT_V(n) asm volatile("s_waitcnt vmcnt(" #n ")" ::: "memory")
; #define PG8_WAIT_L(n) asm volatile("s_waitcnt lgkmcnt(" #n ")" ::: "memory")
; #define PG8_BAR __builtin_amdgcn_s_barrier()
; #define PG8_SCHED __builtin_amdgcn_sched_barrier(0)
; template <class Epi, class Sched>
; __device__ __forceinline__ void gemm_phase(LAS unsigned char* lds, const Gemm g, const Sched& S, const Epi& E, const int tid) {
;     ...
;         for (int t = 0; t < nt; t += 2) {
;             const bool last = (t == nt - 2);
;             const char* a1 = cA + (size_t)(t + 1) * kstep;
;             const char* a2 = last ? nA : cA + (size_t)(t + 2) * kstep; const char* b2 = last ? nB : cB + (size_t)(t + 2) * kstep;
;             const char* a3 = a2 + kstep; const char* b3 = b2 + kstep;
;             PG8_LDB(B0, 0, 0); PG8_LDB(B1, 0, 1); PG8_SCHED; PG8_LDA(At, 0, 0); PG8_STAGE(PG8_SA(1, 1), a1 + hstepA, voffA);
;             PG8_WAIT_V(8); PG8_WAIT_L(0); PG8_BAR; PG8_MMA(0, 0, At, B0); PG8_MMA(0, 1, At, B1); PG8_BAR; PG8_SCHED;
;             PG8_LDA(At, 0, 1); PG8_STAGE(PG8_SB(0, 0), b2, voffB); PG8_STAGE(PG8_SB(0, 1), b2 + hstepB, voffB); PG8_STAGE(PG8_SA(0, 0), a2, voffA);
;             PG8_WAIT_V(8); PG8_WAIT_L(0); PG8_BAR; PG8_MMA(1, 0, At, B0); PG8_MMA(1, 1, At, B1); PG8_BAR; PG8_SCHED;
.LBB0_279:
	s_add_u32 s8, s44, 0x100
	s_addc_u32 s9, s45, 0
	s_add_i32 s12, 0, 0x10000
	s_cmp_eq_u32 s94, 28
	s_cselect_b32 s55, s39, s9
	s_cselect_b32 s54, s38, s8
	s_cselect_b32 s47, s16, s93
	s_cselect_b32 s46, s17, s31
	s_add_i32 s95, 0, 0x14000
	v_add_u32_e32 v158, s12, v155
	v_add_u32_e32 v162, s95, v155
	ds_read_b128 v[142:145], v158
	ds_read_b128 v[146:149], v158 offset:1024
	ds_read_b128 v[150:153], v158 offset:2048
	ds_read_b128 v[158:161], v158 offset:3072
	ds_read_b128 v[174:177], v162
	ds_read_b128 v[178:181], v162 offset:1024
	ds_read_b128 v[182:185], v162 offset:2048
	ds_read_b128 v[186:189], v162 offset:3072
	v_lshl_add_u64 v[162:163], s[44:45], 0, v[138:139]
	s_add_i32 m0, s79, 0xc000
	ds_read_b128 v[190:193], v157
	ds_read_b128 v[194:197], v157 offset:1024
	ds_read_b128 v[198:201], v157 offset:2048
	ds_read_b128 v[202:205], v157 offset:3072
	ds_read_b128 v[210:213], v157 offset:4096
	ds_read_b128 v[220:223], v157 offset:5120
	ds_read_b128 v[234:237], v157 offset:6144
	ds_read_b128 v[238:241], v157 offset:7168
	global_load_lds_dwordx4 v[162:163], off
	v_lshl_add_u64 v[162:163], s[44:45], 0, v[140:141]
	s_add_i32 m0, s79, 0xe000
	s_nop 0
	global_load_lds_dwordx4 v[162:163], off
	s_waitcnt vmcnt(8)
	s_waitcnt lgkmcnt(0)
	s_barrier
	s_waitcnt lgkmcnt(0)
	v_mfma_f32_16x16x32_bf16 v[128:131], v[142:145], v[190:193], v[128:131]
	v_mfma_f32_16x16x32_bf16 v[96:99], v[150:153], v[190:193], v[96:99]
	v_mfma_f32_16x16x32_bf16 v[124:127], v[142:145], v[198:201], v[124:127]
	v_mfma_f32_16x16x32_bf16 v[92:95], v[150:153], v[198:201], v[92:95]
	v_mfma_f32_16x16x32_bf16 v[120:123], v[142:145], v[210:213], v[120:123]
	v_mfma_f32_16x16x32_bf16 v[88:91], v[150:153], v[210:213], v[88:91]
	v_mfma_f32_16x16x32_bf16 v[116:119], v[142:145], v[234:237], v[116:119]
	v_mfma_f32_16x16x32_bf16 v[84:87], v[150:153], v[234:237], v[84:87]
	v_mfma_f32_16x16x32_bf16 v[128:131], v[146:149], v[194:197], v[128:131]
	v_mfma_f32_16x16x32_bf16 v[96:99], v[158:161], v[194:197], v[96:99]
	v_mfma_f32_16x16x32_bf16 v[124:127], v[146:149], v[202:205], v[124:127]
	v_mfma_f32_16x16x32_bf16 v[92:95], v[158:161], v[202:205], v[92:95]
	v_mfma_f32_16x16x32_bf16 v[120:123], v[146:149], v[220:223], v[120:123]
	v_mfma_f32_16x16x32_bf16 v[88:91], v[158:161], v[220:223], v[88:91]
	v_mfma_f32_16x16x32_bf16 v[116:119], v[146:149], v[238:241], v[116:119]
	v_mfma_f32_16x16x32_bf16 v[84:87], v[158:161], v[238:241], v[84:87]
	v_mfma_f32_16x16x32_bf16 v[64:67], v[174:177], v[190:193], v[64:67]
	v_mfma_f32_16x16x32_bf16 v[32:35], v[182:185], v[190:193], v[32:35]
	v_mfma_f32_16x16x32_bf16 v[60:63], v[174:177], v[198:201], v[60:63]
	v_mfma_f32_16x16x32_bf16 v[28:31], v[182:185], v[198:201], v[28:31]
	v_mfma_f32_16x16x32_bf16 v[56:59], v[174:177], v[210:213], v[56:59]
	v_mfma_f32_16x16x32_bf16 v[24:27], v[182:185], v[210:213], v[24:27]
	v_mfma_f32_16x16x32_bf16 v[52:55], v[174:177], v[234:237], v[52:55]
	v_mfma_f32_16x16x32_bf16 v[20:23], v[182:185], v[234:237], v[20:23]
	v_mfma_f32_16x16x32_bf16 v[64:67], v[178:181], v[194:197], v[64:67]
	v_mfma_f32_16x16x32_bf16 v[32:35], v[186:189], v[194:197], v[32:35]
	v_mfma_f32_16x16x32_bf16 v[60:63], v[178:181], v[202:205], v[60:63]
	v_mfma_f32_16x16x32_bf16 v[28:31], v[186:189], v[202:205], v[28:31]
	v_mfma_f32_16x16x32_bf16 v[56:59], v[178:181], v[220:223], v[56:59]
	v_mfma_f32_16x16x32_bf16 v[24:27], v[186:189], v[220:223], v[24:27]
	v_mfma_f32_16x16x32_bf16 v[52:55], v[178:181], v[238:241], v[52:55]
	v_mfma_f32_16x16x32_bf16 v[20:23], v[186:189], v[238:241], v[20:23]
	s_barrier
	s_add_i32 s12, s12, s59
	v_lshl_add_u64 v[162:163], s[46:47], 0, v[164:165]
	s_mov_b32 m0, s12
	ds_read_b128 v[190:193], v157 offset:16384
	ds_read_b128 v[194:197], v157 offset:17408
	ds_read_b128 v[198:201], v157 offset:18432
	ds_read_b128 v[202:205], v157 offset:19456
	ds_read_b128 v[210:213], v157 offset:20480
	ds_read_b128 v[220:223], v157 offset:21504
	ds_read_b128 v[234:237], v157 offset:22528
	ds_read_b128 v[238:241], v157 offset:23552
	global_load_lds_dwordx4 v[162:163], off
	s_add_i32 m0, s12, 0x2000
	s_add_u32 s12, s46, 0x80000
	v_lshl_add_u64 v[206:207], s[46:47], 0, v[136:137]
	s_addc_u32 s13, s47, 0
	s_add_i32 s44, s95, s59
	global_load_lds_dwordx4 v[206:207], off
	v_lshl_add_u64 v[224:225], s[12:13], 0, v[164:165]
	s_mov_b32 m0, s44
	v_lshl_add_u64 v[226:227], s[54:55], 0, v[134:135]
	global_load_lds_dwordx4 v[224:225], off
	v_lshl_add_u64 v[224:225], s[12:13], 0, v[136:137]
	s_add_i32 m0, s44, 0x2000
	s_nop 0
	global_load_lds_dwordx4 v[224:225], off
	v_lshl_add_u64 v[224:225], s[54:55], 0, v[132:133]
	s_mov_b32 m0, s79
	s_nop 0
	global_load_lds_dwordx4 v[224:225], off
	s_mov_b32 m0, s84
	s_nop 0
	global_load_lds_dwordx4 v[226:227], off
	s_waitcnt vmcnt(8)
	s_waitcnt lgkmcnt(0)
	s_barrier
; #define PG8_STAGE(bufoff, gbase, voff) do { _Pragma("unroll") for (int _i = 0; _i < 2; ++_i) \
;         __builtin_amdgcn_global_load_lds((const unsigned*)((const char*)(gbase) + (voff)[_i]), (LAS unsigned*)(lds + (bufoff) + ldsw + _i * 8192), 16, 0, 0); } while (0)
; #define PG8_LDA(dst, b, h) do { _Pragma("unroll") for (int m = 0; m < 4; ++m) _Pragma("unroll") for (int k = 0; k < 2; ++k) dst[m][k] = *(const LAS bf16x8*)(lds + PG8_SA(b, h) + aoff + m * 2048 + k * 1024); } while (0)
; #define PG8_LDB(dst, b, h) do { _Pragma("unroll") for (int n = 0; n < 2; ++n) _Pragma("unroll") for (int k = 0; k < 2; ++k) dst[n][k] = *(const LAS bf16x8*)(lds + PG8_SB(b, h) + boff + n * 2048 + k * 1024); } while (0)
; #define PG8_MMA(ai, bj, At, Bt) do { __builtin_amdgcn_s_setprio(1); _Pragma("unroll") for (int m = 0; m < 4; ++m) _Pragma("unroll") for (int n = 0; n < 2; ++n) _Pragma("unroll") for (int k = 0; k < 2; ++k) \
;         acc[ai][bj][m][n] = __builtin_amdgcn_mfma_f32_16x16x32_bf16(Bt[n][k], At[m][k], acc[ai][bj][m][n], 0, 0, 0); __builtin_amdgcn_s_setprio(0); } while (0)
; #define PG8_WAIT_V(n) asm volatile("s_waitcnt vmcnt(" #n ")" ::: "memory")
; #define PG8_WAIT_L(n) asm volatile("s_waitcnt lgkmcnt(" #n ")" ::: "memory")
; #define PG8_BAR __builtin_amdgcn_s_barrier()
; #define PG8_SCHED __builtin_amdgcn_sched_barrier(0)
; template <class Epi, class Sched>
; __device__ __forceinline__ void gemm_phase(LAS unsigned char* lds, const Gemm g, const Sched& S, const Epi& E, const int tid) {
;     ...
;             PG8_WAIT_V(8); PG8_WAIT_L(0); PG8_BAR; PG8_MMA(1, 0, At, B0); PG8_MMA(1, 1, At, B1); PG8_BAR; PG8_SCHED;
;             PG8_LDB(B0, 1, 0); PG8_LDB(B1, 1, 1); PG8_SCHED; PG8_LDA(At, 1, 0); PG8_STAGE(PG8_SA(0, 1), a2 + hstepA, voffA);
;             PG8_WAIT_V(8); PG8_WAIT_L(0); PG8_BAR; PG8_MMA(0, 0, At, B0); PG8_MMA(0, 1, At, B1); PG8_BAR; PG8_SCHED;
	s_waitcnt lgkmcnt(0)
	v_mfma_f32_16x16x32_bf16 v[112:115], v[142:145], v[190:193], v[112:115]
	v_mfma_f32_16x16x32_bf16 v[80:83], v[150:153], v[190:193], v[80:83]
	v_mfma_f32_16x16x32_bf16 v[108:111], v[142:145], v[198:201], v[108:111]
	v_mfma_f32_16x16x32_bf16 v[76:79], v[150:153], v[198:201], v[76:79]
	v_mfma_f32_16x16x32_bf16 v[104:107], v[142:145], v[210:213], v[104:107]
	v_mfma_f32_16x16x32_bf16 v[72:75], v[150:153], v[210:213], v[72:75]
	v_mfma_f32_16x16x32_bf16 v[100:103], v[142:145], v[234:237], v[100:103]
	v_mfma_f32_16x16x32_bf16 v[68:71], v[150:153], v[234:237], v[68:71]
	v_mfma_f32_16x16x32_bf16 v[112:115], v[146:149], v[194:197], v[112:115]
	v_mfma_f32_16x16x32_bf16 v[80:83], v[158:161], v[194:197], v[80:83]
	v_mfma_f32_16x16x32_bf16 v[108:111], v[146:149], v[202:205], v[108:111]
	v_mfma_f32_16x16x32_bf16 v[76:79], v[158:161], v[202:205], v[76:79]
	v_mfma_f32_16x16x32_bf16 v[104:107], v[146:149], v[220:223], v[104:107]
	v_mfma_f32_16x16x32_bf16 v[72:75], v[158:161], v[220:223], v[72:75]
	v_mfma_f32_16x16x32_bf16 v[100:103], v[146:149], v[238:241], v[100:103]
	v_mfma_f32_16x16x32_bf16 v[68:71], v[158:161], v[238:241], v[68:71]
	v_mfma_f32_16x16x32_bf16 v[48:51], v[174:177], v[190:193], v[48:51]
	v_mfma_f32_16x16x32_bf16 v[16:19], v[182:185], v[190:193], v[16:19]
	v_mfma_f32_16x16x32_bf16 v[44:47], v[174:177], v[198:201], v[44:47]
	v_mfma_f32_16x16x32_bf16 v[12:15], v[182:185], v[198:201], v[12:15]
	v_mfma_f32_16x16x32_bf16 v[40:43], v[174:177], v[210:213], v[40:43]
	v_mfma_f32_16x16x32_bf16 v[8:11], v[182:185], v[210:213], v[8:11]
	v_mfma_f32_16x16x32_bf16 v[36:39], v[174:177], v[234:237], v[36:39]
	v_mfma_f32_16x16x32_bf16 v[4:7], v[182:185], v[234:237], v[4:7]
	v_mfma_f32_16x16x32_bf16 v[48:51], v[178:181], v[194:197], v[48:51]
	v_mfma_f32_16x16x32_bf16 v[16:19], v[186:189], v[194:197], v[16:19]
	v_mfma_f32_16x16x32_bf16 v[44:47], v[178:181], v[202:205], v[44:47]
	v_mfma_f32_16x16x32_bf16 v[12:15], v[186:189], v[202:205], v[12:15]
	v_mfma_f32_16x16x32_bf16 v[40:43], v[178:181], v[220:223], v[40:43]
	v_mfma_f32_16x16x32_bf16 v[8:11], v[186:189], v[220:223], v[8:11]
	v_mfma_f32_16x16x32_bf16 v[36:39], v[178:181], v[238:241], v[36:39]
	v_mfma_f32_16x16x32_bf16 v[4:7], v[186:189], v[238:241], v[4:7]
	s_barrier
	s_add_i32 s44, 0, 0x18000
	s_add_i32 s45, 0, 0x1c000
	v_add_u32_e32 v158, s44, v155
	v_add_u32_e32 v171, s45, v155
	ds_read_b128 v[142:145], v158
	ds_read_b128 v[146:149], v158 offset:1024
	ds_read_b128 v[150:153], v158 offset:2048
	ds_read_b128 v[158:161], v158 offset:3072
	ds_read_b128 v[174:177], v171
	ds_read_b128 v[178:181], v171 offset:1024
	ds_read_b128 v[182:185], v171 offset:2048
	ds_read_b128 v[186:189], v171 offset:3072
	s_add_u32 s12, s54, 0x242000
	s_addc_u32 s13, s55, 0
	s_mov_b32 m0, s85
	v_lshl_add_u64 v[242:243], s[12:13], 0, v[132:133]
	ds_read_b128 v[190:193], v157 offset:32768
	ds_read_b128 v[194:197], v157 offset:33792
	ds_read_b128 v[198:201], v157 offset:34816
	ds_read_b128 v[202:205], v157 offset:35840
	ds_read_b128 v[210:213], v157 offset:36864
	ds_read_b128 v[220:223], v157 offset:37888
	ds_read_b128 v[234:237], v157 offset:38912
	ds_read_b128 v[238:241], v157 offset:39936
	global_load_lds_dwordx4 v[242:243], off
	v_lshl_add_u64 v[242:243], s[12:13], 0, v[134:135]
	s_mov_b32 m0, s86
	s_nop 0
	global_load_lds_dwordx4 v[242:243], off
	s_waitcnt vmcnt(8)
	s_waitcnt lgkmcnt(0)
	s_barrier
	s_waitcnt lgkmcnt(0)
	v_mfma_f32_16x16x32_bf16 v[128:131], v[142:145], v[190:193], v[128:131]
	v_mfma_f32_16x16x32_bf16 v[96:99], v[150:153], v[190:193], v[96:99]
	v_mfma_f32_16x16x32_bf16 v[124:127], v[142:145], v[198:201], v[124:127]
	v_mfma_f32_16x16x32_bf16 v[92:95], v[150:153], v[198:201], v[92:95]
	v_mfma_f32_16x16x32_bf16 v[120:123], v[142:145], v[210:213], v[120:123]
	v_mfma_f32_16x16x32_bf16 v[88:91], v[150:153], v[210:213], v[88:91]
	v_mfma_f32_16x16x32_bf16 v[116:119], v[142:145], v[234:237], v[116:119]
	v_mfma_f32_16x16x32_bf16 v[84:87], v[150:153], v[234:237], v[84:87]
	v_mfma_f32_16x16x32_bf16 v[128:131], v[146:149], v[194:197], v[128:131]
	v_mfma_f32_16x16x32_bf16 v[96:99], v[158:161], v[194:197], v[96:99]
	v_mfma_f32_16x16x32_bf16 v[124:127], v[146:149], v[202:205], v[124:127]
	v_mfma_f32_16x16x32_bf16 v[92:95], v[158:161], v[202:205], v[92:95]
	v_mfma_f32_16x16x32_bf16 v[120:123], v[146:149], v[220:223], v[120:123]
	v_mfma_f32_16x16x32_bf16 v[88:91], v[158:161], v[220:223], v[88:91]
	v_mfma_f32_16x16x32_bf16 v[116:119], v[146:149], v[238:241], v[116:119]
	v_mfma_f32_16x16x32_bf16 v[84:87], v[158:161], v[238:241], v[84:87]
	v_mfma_f32_16x16x32_bf16 v[64:67], v[174:177], v[190:193], v[64:67]
	v_mfma_f32_16x16x32_bf16 v[32:35], v[182:185], v[190:193], v[32:35]
	v_mfma_f32_16x16x32_bf16 v[60:63], v[174:177], v[198:201], v[60:63]
	v_mfma_f32_16x16x32_bf16 v[28:31], v[182:185], v[198:201], v[28:31]
	v_mfma_f32_16x16x32_bf16 v[56:59], v[174:177], v[210:213], v[56:59]
	v_mfma_f32_16x16x32_bf16 v[24:27], v[182:185], v[210:213], v[24:27]
	v_mfma_f32_16x16x32_bf16 v[52:55], v[174:177], v[234:237], v[52:55]
	v_mfma_f32_16x16x32_bf16 v[20:23], v[182:185], v[234:237], v[20:23]
	v_mfma_f32_16x16x32_bf16 v[64:67], v[178:181], v[194:197], v[64:67]
	v_mfma_f32_16x16x32_bf16 v[32:35], v[186:189], v[194:197], v[32:35]
	v_mfma_f32_16x16x32_bf16 v[60:63], v[178:181], v[202:205], v[60:63]
	v_mfma_f32_16x16x32_bf16 v[28:31], v[186:189], v[202:205], v[28:31]
	v_mfma_f32_16x16x32_bf16 v[56:59], v[178:181], v[220:223], v[56:59]
	v_mfma_f32_16x16x32_bf16 v[24:27], v[186:189], v[220:223], v[24:27]
	v_mfma_f32_16x16x32_bf16 v[52:55], v[178:181], v[238:241], v[52:55]
	v_mfma_f32_16x16x32_bf16 v[20:23], v[186:189], v[238:241], v[20:23]
	s_barrier
; #define PG8_STAGE(bufoff, gbase, voff) do { _Pragma("unroll") for (int _i = 0; _i < 2; ++_i) \
;         __builtin_amdgcn_global_load_lds((const unsigned*)((const char*)(gbase) + (voff)[_i]), (LAS unsigned*)(lds + (bufoff) + ldsw + _i * 8192), 16, 0, 0); } while (0)
; #define PG8_LDA(dst, b, h) do { _Pragma("unroll") for (int m = 0; m < 4; ++m) _Pragma("unroll") for (int k = 0; k < 2; ++k) dst[m][k] = *(const LAS bf16x8*)(lds + PG8_SA(b, h) + aoff + m * 2048 + k * 1024); } while (0)
; #define PG8_MMA(ai, bj, At, Bt) do { __builtin_amdgcn_s_setprio(1); _Pragma("unroll") for (int m = 0; m < 4; ++m) _Pragma("unroll") for (int n = 0; n < 2; ++n) _Pragma("unroll") for (int k = 0; k < 2; ++k) \
;         acc[ai][bj][m][n] = __builtin_amdgcn_mfma_f32_16x16x32_bf16(Bt[n][k], At[m][k], acc[ai][bj][m][n], 0, 0, 0); __builtin_amdgcn_s_setprio(0); } while (0)
; #define PG8_WAIT_V(n) asm volatile("s_waitcnt vmcnt(" #n ")" ::: "memory")
; #define PG8_WAIT_L(n) asm volatile("s_waitcnt lgkmcnt(" #n ")" ::: "memory")
; #define PG8_BAR __builtin_amdgcn_s_barrier()
; #define PG8_SCHED __builtin_amdgcn_sched_barrier(0)
; template <class Epi, class Sched>
; __device__ __forceinline__ void gemm_phase(LAS unsigned char* lds, const Gemm g, const Sched& S, const Epi& E, const int tid) {
;     ...
;             PG8_LDA(At, 1, 1); PG8_STAGE(PG8_SB(1, 0), b3, voffB); PG8_STAGE(PG8_SB(1, 1), b3 + hstepB, voffB); PG8_STAGE(PG8_SA(1, 0), a3, voffA);
;             PG8_WAIT_V(8); PG8_WAIT_L(0); PG8_BAR; PG8_MMA(1, 0, At, B0); PG8_MMA(1, 1, At, B1); PG8_BAR; PG8_SCHED;
;         }
;         if (wr == 0) PG8_BAR;
	s_add_i32 s12, s44, s59
	v_lshl_add_u64 v[162:163], v[162:163], 0, s[28:29]
	s_mov_b32 m0, s12
	ds_read_b128 v[190:193], v157 offset:49152
	ds_read_b128 v[194:197], v157 offset:50176
	ds_read_b128 v[198:201], v157 offset:51200
	ds_read_b128 v[202:205], v157 offset:52224
	ds_read_b128 v[210:213], v157 offset:53248
	ds_read_b128 v[220:223], v157 offset:54272
	ds_read_b128 v[234:237], v157 offset:55296
	ds_read_b128 v[238:241], v157 offset:56320
	global_load_lds_dwordx4 v[162:163], off
	s_add_i32 m0, s12, 0x2000
	s_add_u32 s12, s46, 0x80080
	v_lshl_add_u64 v[162:163], v[206:207], 0, s[28:29]
	s_addc_u32 s13, s47, 0
	s_add_i32 s44, s45, s59
	global_load_lds_dwordx4 v[162:163], off
	v_lshl_add_u64 v[162:163], s[12:13], 0, v[164:165]
	s_mov_b32 m0, s44
	s_nop 0
	global_load_lds_dwordx4 v[162:163], off
	v_lshl_add_u64 v[162:163], s[12:13], 0, v[136:137]
	s_add_i32 m0, s44, 0x2000
	s_nop 0
	global_load_lds_dwordx4 v[162:163], off
	v_lshl_add_u64 v[162:163], v[224:225], 0, s[28:29]
	s_mov_b32 m0, s87
	s_nop 0
	global_load_lds_dwordx4 v[162:163], off
	v_lshl_add_u64 v[162:163], v[226:227], 0, s[28:29]
	s_mov_b32 m0, s88
	s_nop 0
	global_load_lds_dwordx4 v[162:163], off
	s_waitcnt vmcnt(8)
	s_waitcnt lgkmcnt(0)
	s_barrier
	s_waitcnt lgkmcnt(0)
	v_mfma_f32_16x16x32_bf16 v[112:115], v[142:145], v[190:193], v[112:115]
	v_mfma_f32_16x16x32_bf16 v[80:83], v[150:153], v[190:193], v[80:83]
	v_mfma_f32_16x16x32_bf16 v[108:111], v[142:145], v[198:201], v[108:111]
	v_mfma_f32_16x16x32_bf16 v[76:79], v[150:153], v[198:201], v[76:79]
	v_mfma_f32_16x16x32_bf16 v[104:107], v[142:145], v[210:213], v[104:107]
	v_mfma_f32_16x16x32_bf16 v[72:75], v[150:153], v[210:213], v[72:75]
	v_mfma_f32_16x16x32_bf16 v[100:103], v[142:145], v[234:237], v[100:103]
	v_mfma_f32_16x16x32_bf16 v[68:71], v[150:153], v[234:237], v[68:71]
	v_mfma_f32_16x16x32_bf16 v[112:115], v[146:149], v[194:197], v[112:115]
	v_mfma_f32_16x16x32_bf16 v[80:83], v[158:161], v[194:197], v[80:83]
	v_mfma_f32_16x16x32_bf16 v[108:111], v[146:149], v[202:205], v[108:111]
	v_mfma_f32_16x16x32_bf16 v[76:79], v[158:161], v[202:205], v[76:79]
	v_mfma_f32_16x16x32_bf16 v[104:107], v[146:149], v[220:223], v[104:107]
	v_mfma_f32_16x16x32_bf16 v[72:75], v[158:161], v[220:223], v[72:75]
	v_mfma_f32_16x16x32_bf16 v[100:103], v[146:149], v[238:241], v[100:103]
	v_mfma_f32_16x16x32_bf16 v[68:71], v[158:161], v[238:241], v[68:71]
	v_mfma_f32_16x16x32_bf16 v[48:51], v[174:177], v[190:193], v[48:51]
	v_mfma_f32_16x16x32_bf16 v[16:19], v[182:185], v[190:193], v[16:19]
	v_mfma_f32_16x16x32_bf16 v[44:47], v[174:177], v[198:201], v[44:47]
	v_mfma_f32_16x16x32_bf16 v[12:15], v[182:185], v[198:201], v[12:15]
	v_mfma_f32_16x16x32_bf16 v[40:43], v[174:177], v[210:213], v[40:43]
	v_mfma_f32_16x16x32_bf16 v[8:11], v[182:185], v[210:213], v[8:11]
	v_mfma_f32_16x16x32_bf16 v[36:39], v[174:177], v[234:237], v[36:39]
	v_mfma_f32_16x16x32_bf16 v[4:7], v[182:185], v[234:237], v[4:7]
	v_mfma_f32_16x16x32_bf16 v[48:51], v[178:181], v[194:197], v[48:51]
	v_mfma_f32_16x16x32_bf16 v[16:19], v[186:189], v[194:197], v[16:19]
	v_mfma_f32_16x16x32_bf16 v[44:47], v[178:181], v[202:205], v[44:47]
	v_mfma_f32_16x16x32_bf16 v[12:15], v[186:189], v[202:205], v[12:15]
	v_mfma_f32_16x16x32_bf16 v[40:43], v[178:181], v[220:223], v[40:43]
	v_mfma_f32_16x16x32_bf16 v[8:11], v[186:189], v[220:223], v[8:11]
	v_mfma_f32_16x16x32_bf16 v[36:39], v[178:181], v[238:241], v[36:39]
	v_mfma_f32_16x16x32_bf16 v[4:7], v[186:189], v[238:241], v[4:7]
	s_barrier
	s_add_i32 s94, s94, 2
	s_add_u32 s31, s31, 0x100
	s_addc_u32 s93, s93, 0
	s_cmp_gt_u32 s94, 29
	s_mov_b64 s[44:45], s[8:9]
	s_cbranch_scc0 .LBB0_279
	s_setprio 0
	s_and_b64 vcc, exec, s[20:21]
	s_cbranch_vccz .LBB0_282
	s_barrier

; template <class Epi, class Sched>
; __device__ __forceinline__ void gemm_phase(LAS unsigned char* lds, const Gemm g, const Sched& S, const Epi& E, const int tid) {
;     ...
;     for (;;) {
;         const bool has_next = S.next(ui + 1, nxt);
;         const char* nA = has_next ? (const char*)g.A + (size_t)nxt.pm * tstepA : cA; const char* nB = has_next ? (const char*)g.Bt + (size_t)nxt.pn * tstepB : cB;
;         for (int t = 0; t < nt; t += 2) {
;     ...
; #pragma unroll
;         for (int a = 0; a < 2; ++a)
; #pragma unroll
;             for (int b = 0; b < 2; ++b)
; #pragma unroll
;                 for (int m = 0; m < 4; ++m)
; #pragma unroll
;                     for (int n = 0; n < 2; ++n) acc[a][b][m][n] = (f32x4){0.f, 0.f, 0.f, 0.f};
.LBB0_307:
	s_ashr_i32 s39, s38, 31
	s_lshl_b64 s[12:13], s[38:39], 19
	s_add_u32 s42, s26, s12
	s_addc_u32 s43, s56, s13
	s_and_b64 s[12:13], s[6:7], exec
	s_cselect_b32 s16, s43, s55
	s_cselect_b32 s17, s42, s54
	s_ashr_i32 s31, s30, 31
	s_lshl_b64 s[12:13], s[30:31], 19
	s_add_u32 s44, s57, s12
	s_addc_u32 s45, s58, s13
	s_and_b64 s[12:13], s[6:7], exec
	s_cselect_b32 s31, s45, s91
	s_cselect_b32 s39, s44, s90
	s_add_u32 s54, s54, 0x40080
	s_addc_u32 s55, s55, 0
	s_add_u32 s47, s90, 0x100
	v_mov_b32_e32 v4, 0
	s_addc_u32 s96, s91, 0
	s_mov_b32 s97, -2
	v_mov_b32_e32 v5, v4
	v_mov_b32_e32 v6, v4
	v_mov_b32_e32 v7, v4
	v_mov_b32_e32 v8, v4
	v_mov_b32_e32 v9, v4
	v_mov_b32_e32 v10, v4
	v_mov_b32_e32 v11, v4
	v_mov_b32_e32 v16, v4
	v_mov_b32_e32 v17, v4
	v_mov_b32_e32 v18, v4
	v_mov_b32_e32 v19, v4
	v_mov_b32_e32 v24, v4
	v_mov_b32_e32 v25, v4
	v_mov_b32_e32 v26, v4
	v_mov_b32_e32 v27, v4
	v_mov_b32_e32 v36, v4
	v_mov_b32_e32 v37, v4
	v_mov_b32_e32 v38, v4
	v_mov_b32_e32 v39, v4
	v_mov_b32_e32 v40, v4
	v_mov_b32_e32 v41, v4
	v_mov_b32_e32 v42, v4
	v_mov_b32_e32 v43, v4
	v_mov_b32_e32 v44, v4
	v_mov_b32_e32 v45, v4
	v_mov_b32_e32 v46, v4
	v_mov_b32_e32 v47, v4
	v_mov_b32_e32 v52, v4
	v_mov_b32_e32 v53, v4
	v_mov_b32_e32 v54, v4
	v_mov_b32_e32 v55, v4
	v_mov_b32_e32 v12, v4
	v_mov_b32_e32 v13, v4
	v_mov_b32_e32 v14, v4
	v_mov_b32_e32 v15, v4
	v_mov_b32_e32 v20, v4
	v_mov_b32_e32 v21, v4
	v_mov_b32_e32 v22, v4
	v_mov_b32_e32 v23, v4
	v_mov_b32_e32 v28, v4
	v_mov_b32_e32 v29, v4
	v_mov_b32_e32 v30, v4
	v_mov_b32_e32 v31, v4
	v_mov_b32_e32 v32, v4
	v_mov_b32_e32 v33, v4
	v_mov_b32_e32 v34, v4
	v_mov_b32_e32 v35, v4
	v_mov_b32_e32 v48, v4
	v_mov_b32_e32 v49, v4
	v_mov_b32_e32 v50, v4
	v_mov_b32_e32 v51, v4
	v_mov_b32_e32 v56, v4
	v_mov_b32_e32 v57, v4
	v_mov_b32_e32 v58, v4
	v_mov_b32_e32 v59, v4
	v_mov_b32_e32 v60, v4
	v_mov_b32_e32 v61, v4
	v_mov_b32_e32 v62, v4
	v_mov_b32_e32 v63, v4
	v_mov_b32_e32 v64, v4
	v_mov_b32_e32 v65, v4
	v_mov_b32_e32 v66, v4
	v_mov_b32_e32 v67, v4
	v_mov_b32_e32 v68, v4
	v_mov_b32_e32 v69, v4
	v_mov_b32_e32 v70, v4
	v_mov_b32_e32 v71, v4
	v_mov_b32_e32 v72, v4
	v_mov_b32_e32 v73, v4
	v_mov_b32_e32 v74, v4
	v_mov_b32_e32 v75, v4
	v_mov_b32_e32 v76, v4
	v_mov_b32_e32 v77, v4
	v_mov_b32_e32 v78, v4
	v_mov_b32_e32 v79, v4
	v_mov_b32_e32 v84, v4
	v_mov_b32_e32 v85, v4
	v_mov_b32_e32 v86, v4
	v_mov_b32_e32 v87, v4
	v_mov_b32_e32 v100, v4
	v_mov_b32_e32 v101, v4
	v_mov_b32_e32 v102, v4
	v_mov_b32_e32 v103, v4
	v_mov_b32_e32 v104, v4
	v_mov_b32_e32 v105, v4
	v_mov_b32_e32 v106, v4
	v_mov_b32_e32 v107, v4
	v_mov_b32_e32 v108, v4
	v_mov_b32_e32 v109, v4
	v_mov_b32_e32 v110, v4
	v_mov_b32_e32 v111, v4
	v_mov_b32_e32 v116, v4
	v_mov_b32_e32 v117, v4
	v_mov_b32_e32 v118, v4
	v_mov_b32_e32 v119, v4
	v_mov_b32_e32 v80, v4
	v_mov_b32_e32 v81, v4
	v_mov_b32_e32 v82, v4
	v_mov_b32_e32 v83, v4
	v_mov_b32_e32 v88, v4
	v_mov_b32_e32 v89, v4
	v_mov_b32_e32 v90, v4
	v_mov_b32_e32 v91, v4
	v_mov_b32_e32 v92, v4
	v_mov_b32_e32 v93, v4
	v_mov_b32_e32 v94, v4
	v_mov_b32_e32 v95, v4
	v_mov_b32_e32 v96, v4
	v_mov_b32_e32 v97, v4
	v_mov_b32_e32 v98, v4
	v_mov_b32_e32 v99, v4
	v_mov_b32_e32 v112, v4
	v_mov_b32_e32 v113, v4
	v_mov_b32_e32 v114, v4
	v_mov_b32_e32 v115, v4
	v_mov_b32_e32 v120, v4
	v_mov_b32_e32 v121, v4
	v_mov_b32_e32 v122, v4
	v_mov_b32_e32 v123, v4
	v_mov_b32_e32 v124, v4
	v_mov_b32_e32 v125, v4
	v_mov_b32_e32 v126, v4
	v_mov_b32_e32 v127, v4
	v_mov_b32_e32 v128, v4
	v_mov_b32_e32 v129, v4
	v_mov_b32_e32 v130, v4
	v_mov_b32_e32 v131, v4
	s_cselect_b32 s99, 1, 0
	v_readfirstlane_b32 s98, v173
	s_nop 0
	s_cmpk_lt_u32 s98, 0x100
	s_cbranch_scc1 .Lprio_skip_LBB0308
	s_setprio 1

; #define PG8_STAGE(bufoff, gbase, voff) do { _Pragma("unroll") for (int _i = 0; _i < 2; ++_i) \
;         __builtin_amdgcn_global_load_lds((const unsigned*)((const char*)(gbase) + (voff)[_i]), (LAS unsigned*)(lds + (bufoff) + ldsw + _i * 8192), 16, 0, 0); } while (0)
; #define PG8_LDA(dst, b, h) do { _Pragma("unroll") for (int m = 0; m < 4; ++m) _Pragma("unroll") for (int k = 0; k < 2; ++k) dst[m][k] = *(const LAS bf16x8*)(lds + PG8_SA(b, h) + aoff + m * 2048 + k * 1024); } while (0)
; #define PG8_LDB(dst, b, h) do { _Pragma("unroll") for (int n = 0; n < 2; ++n) _Pragma("unroll") for (int k = 0; k < 2; ++k) dst[n][k] = *(const LAS bf16x8*)(lds + PG8_SB(b, h) + boff + n * 2048 + k * 1024); } while (0)
; #define PG8_MMA(ai, bj, At, Bt) do { __builtin_amdgcn_s_setprio(1); _Pragma("unroll") for (int m = 0; m < 4; ++m) _Pragma("unroll") for (int n = 0; n < 2; ++n) _Pragma("unroll") for (int k = 0; k < 2; ++k) \
;         acc[ai][bj][m][n] = __builtin_amdgcn_mfma_f32_16x16x32_bf16(Bt[n][k], At[m][k], acc[ai][bj][m][n], 0, 0, 0); __builtin_amdgcn_s_setprio(0); } while (0)
; #define PG8_WAIT_V(n) asm volatile("s_waitcnt vmcnt(" #n ")" ::: "memory")
; #define PG8_WAIT_L(n) asm volatile("s_waitcnt lgkmcnt(" #n ")" ::: "memory")
; #define PG8_BAR __builtin_amdgcn_s_barrier()
; #define PG8_SCHED __builtin_amdgcn_sched_barrier(0)
; template <class Epi, class Sched>
; __device__ __forceinline__ void gemm_phase(LAS unsigned char* lds, const Gemm g, const Sched& S, const Epi& E, const int tid) {
;     ...
;         for (int t = 0; t < nt; t += 2) {
;             const bool last = (t == nt - 2);
;             const char* a1 = cA + (size_t)(t + 1) * kstep;
;             const char* a2 = last ? nA : cA + (size_t)(t + 2) * kstep; const char* b2 = last ? nB : cB + (size_t)(t + 2) * kstep;
;             const char* a3 = a2 + kstep; const char* b3 = b2 + kstep;
;             PG8_LDB(B0, 0, 0); PG8_LDB(B1, 0, 1); PG8_SCHED; PG8_LDA(At, 0, 0); PG8_STAGE(PG8_SA(1, 1), a1 + hstepA, voffA);
;             PG8_WAIT_V(8); PG8_WAIT_L(0); PG8_BAR; PG8_MMA(0, 0, At, B0); PG8_MMA(0, 1, At, B1); PG8_BAR; PG8_SCHED;
;             PG8_LDA(At, 0, 1); PG8_STAGE(PG8_SB(0, 0), b2, voffB); PG8_STAGE(PG8_SB(0, 1), b2 + hstepB, voffB); PG8_STAGE(PG8_SA(0, 0), a2, voffA);
;             PG8_WAIT_V(8); PG8_WAIT_L(0); PG8_BAR; PG8_MMA(1, 0, At, B0); PG8_MMA(1, 1, At, B1); PG8_BAR; PG8_SCHED;
.LBB0_308:
	s_add_u32 s12, s54, 0xfffc0080
	s_addc_u32 s13, s55, -1
	s_add_i32 vcc_lo, 0, 0x10000
	s_cmp_eq_u32 s97, 12
	s_cselect_b32 s93, s16, s13
	s_cselect_b32 s92, s17, s12
	v_add_u32_e32 v154, vcc_lo, v151
	s_cselect_b32 s91, s31, s96
	s_cselect_b32 s90, s39, s47
	s_add_i32 vcc_hi, 0, 0x14000
	ds_read_b128 v[136:139], v154
	ds_read_b128 v[174:177], v154 offset:1024
	ds_read_b128 v[178:181], v154 offset:2048
	ds_read_b128 v[182:185], v154 offset:3072
	v_add_u32_e32 v154, vcc_hi, v151
	ds_read_b128 v[186:189], v154
	ds_read_b128 v[190:193], v154 offset:1024
	ds_read_b128 v[194:197], v154 offset:2048
	ds_read_b128 v[198:201], v154 offset:3072
	v_lshl_add_u64 v[154:155], s[54:55], 0, v[132:133]
	s_add_i32 m0, s79, 0xc000
	ds_read_b128 v[202:205], v153
	ds_read_b128 v[220:223], v153 offset:1024
	ds_read_b128 v[234:237], v153 offset:2048
	ds_read_b128 v[238:241], v153 offset:3072
	ds_read_b128 v[242:245], v153 offset:4096
	ds_read_b128 v[246:249], v153 offset:5120
	ds_read_b128 v[250:253], v153 offset:6144
	ds_read_b128 v[210:213], v153 offset:7168
	global_load_lds_dwordx4 v[154:155], off
	v_lshl_add_u64 v[154:155], s[54:55], 0, v[134:135]
	s_add_i32 m0, s79, 0xe000
	s_nop 0
	global_load_lds_dwordx4 v[154:155], off
	s_waitcnt vmcnt(8)
	s_waitcnt lgkmcnt(0)
	s_barrier
	s_waitcnt lgkmcnt(0)
	v_mfma_f32_16x16x32_bf16 v[128:131], v[136:139], v[202:205], v[128:131]
	v_mfma_f32_16x16x32_bf16 v[124:127], v[178:181], v[202:205], v[124:127]
	v_mfma_f32_16x16x32_bf16 v[120:123], v[136:139], v[234:237], v[120:123]
	v_mfma_f32_16x16x32_bf16 v[112:115], v[178:181], v[234:237], v[112:115]
	v_mfma_f32_16x16x32_bf16 v[96:99], v[136:139], v[242:245], v[96:99]
	v_mfma_f32_16x16x32_bf16 v[92:95], v[178:181], v[242:245], v[92:95]
	v_mfma_f32_16x16x32_bf16 v[88:91], v[136:139], v[250:253], v[88:91]
	v_mfma_f32_16x16x32_bf16 v[80:83], v[178:181], v[250:253], v[80:83]
	v_mfma_f32_16x16x32_bf16 v[128:131], v[174:177], v[220:223], v[128:131]
	v_mfma_f32_16x16x32_bf16 v[124:127], v[182:185], v[220:223], v[124:127]
	v_mfma_f32_16x16x32_bf16 v[120:123], v[174:177], v[238:241], v[120:123]
	v_mfma_f32_16x16x32_bf16 v[112:115], v[182:185], v[238:241], v[112:115]
	v_mfma_f32_16x16x32_bf16 v[96:99], v[174:177], v[246:249], v[96:99]
	v_mfma_f32_16x16x32_bf16 v[92:95], v[182:185], v[246:249], v[92:95]
	v_mfma_f32_16x16x32_bf16 v[88:91], v[174:177], v[210:213], v[88:91]
	v_mfma_f32_16x16x32_bf16 v[80:83], v[182:185], v[210:213], v[80:83]
	v_mfma_f32_16x16x32_bf16 v[116:119], v[186:189], v[202:205], v[116:119]
	v_mfma_f32_16x16x32_bf16 v[108:111], v[194:197], v[202:205], v[108:111]
	v_mfma_f32_16x16x32_bf16 v[104:107], v[186:189], v[234:237], v[104:107]
	v_mfma_f32_16x16x32_bf16 v[100:103], v[194:197], v[234:237], v[100:103]
	v_mfma_f32_16x16x32_bf16 v[84:87], v[186:189], v[242:245], v[84:87]
	v_mfma_f32_16x16x32_bf16 v[76:79], v[194:197], v[242:245], v[76:79]
	v_mfma_f32_16x16x32_bf16 v[72:75], v[186:189], v[250:253], v[72:75]
	v_mfma_f32_16x16x32_bf16 v[68:71], v[194:197], v[250:253], v[68:71]
	v_mfma_f32_16x16x32_bf16 v[116:119], v[190:193], v[220:223], v[116:119]
	v_mfma_f32_16x16x32_bf16 v[108:111], v[198:201], v[220:223], v[108:111]
	v_mfma_f32_16x16x32_bf16 v[104:107], v[190:193], v[238:241], v[104:107]
	v_mfma_f32_16x16x32_bf16 v[100:103], v[198:201], v[238:241], v[100:103]
	v_mfma_f32_16x16x32_bf16 v[84:87], v[190:193], v[246:249], v[84:87]
	v_mfma_f32_16x16x32_bf16 v[76:79], v[198:201], v[246:249], v[76:79]
	v_mfma_f32_16x16x32_bf16 v[72:75], v[190:193], v[210:213], v[72:75]
	v_mfma_f32_16x16x32_bf16 v[68:71], v[198:201], v[210:213], v[68:71]
	s_barrier
	s_add_i32 s12, vcc_lo, s59
	v_lshl_add_u64 v[154:155], s[90:91], 0, v[164:165]
	s_mov_b32 m0, s12
	ds_read_b128 v[202:205], v153 offset:16384
	ds_read_b128 v[210:213], v153 offset:17408
	ds_read_b128 v[220:223], v153 offset:18432
	ds_read_b128 v[234:237], v153 offset:19456
	ds_read_b128 v[238:241], v153 offset:20480
	ds_read_b128 v[242:245], v153 offset:21504
	ds_read_b128 v[246:249], v153 offset:22528
	ds_read_b128 v[250:253], v153 offset:23552
	global_load_lds_dwordx4 v[154:155], off
	s_add_i32 m0, s12, 0x2000
	s_add_u32 s12, s90, 0x40000
	v_lshl_add_u64 v[162:163], s[90:91], 0, v[160:161]
	s_addc_u32 s13, s91, 0
	s_add_i32 vcc_lo, vcc_hi, s59
	global_load_lds_dwordx4 v[162:163], off
	v_lshl_add_u64 v[206:207], s[12:13], 0, v[164:165]
	s_mov_b32 m0, vcc_lo
	v_lshl_add_u64 v[224:225], s[92:93], 0, v[158:159]
	global_load_lds_dwordx4 v[206:207], off
	v_lshl_add_u64 v[206:207], s[12:13], 0, v[160:161]
	s_add_i32 m0, vcc_lo, 0x2000
	s_nop 0
	global_load_lds_dwordx4 v[206:207], off
	v_lshl_add_u64 v[206:207], s[92:93], 0, v[156:157]
	s_mov_b32 m0, s79
	s_nop 0
	global_load_lds_dwordx4 v[206:207], off
	s_mov_b32 m0, s85
	s_nop 0
	global_load_lds_dwordx4 v[224:225], off
	s_waitcnt vmcnt(8)
	s_waitcnt lgkmcnt(0)
	s_barrier
; #define PG8_STAGE(bufoff, gbase, voff) do { _Pragma("unroll") for (int _i = 0; _i < 2; ++_i) \
;         __builtin_amdgcn_global_load_lds((const unsigned*)((const char*)(gbase) + (voff)[_i]), (LAS unsigned*)(lds + (bufoff) + ldsw + _i * 8192), 16, 0, 0); } while (0)
; #define PG8_LDA(dst, b, h) do { _Pragma("unroll") for (int m = 0; m < 4; ++m) _Pragma("unroll") for (int k = 0; k < 2; ++k) dst[m][k] = *(const LAS bf16x8*)(lds + PG8_SA(b, h) + aoff + m * 2048 + k * 1024); } while (0)
; #define PG8_LDB(dst, b, h) do { _Pragma("unroll") for (int n = 0; n < 2; ++n) _Pragma("unroll") for (int k = 0; k < 2; ++k) dst[n][k] = *(const LAS bf16x8*)(lds + PG8_SB(b, h) + boff + n * 2048 + k * 1024); } while (0)
; #define PG8_MMA(ai, bj, At, Bt) do { __builtin_amdgcn_s_setprio(1); _Pragma("unroll") for (int m = 0; m < 4; ++m) _Pragma("unroll") for (int n = 0; n < 2; ++n) _Pragma("unroll") for (int k = 0; k < 2; ++k) \
;         acc[ai][bj][m][n] = __builtin_amdgcn_mfma_f32_16x16x32_bf16(Bt[n][k], At[m][k], acc[ai][bj][m][n], 0, 0, 0); __builtin_amdgcn_s_setprio(0); } while (0)
; #define PG8_WAIT_V(n) asm volatile("s_waitcnt vmcnt(" #n ")" ::: "memory")
; #define PG8_WAIT_L(n) asm volatile("s_waitcnt lgkmcnt(" #n ")" ::: "memory")
; #define PG8_BAR __builtin_amdgcn_s_barrier()
; #define PG8_SCHED __builtin_amdgcn_sched_barrier(0)
; template <class Epi, class Sched>
; __device__ __forceinline__ void gemm_phase(LAS unsigned char* lds, const Gemm g, const Sched& S, const Epi& E, const int tid) {
;     ...
;             PG8_WAIT_V(8); PG8_WAIT_L(0); PG8_BAR; PG8_MMA(1, 0, At, B0); PG8_MMA(1, 1, At, B1); PG8_BAR; PG8_SCHED;
;             PG8_LDB(B0, 1, 0); PG8_LDB(B1, 1, 1); PG8_SCHED; PG8_LDA(At, 1, 0); PG8_STAGE(PG8_SA(0, 1), a2 + hstepA, voffA);
;             PG8_WAIT_V(8); PG8_WAIT_L(0); PG8_BAR; PG8_MMA(0, 0, At, B0); PG8_MMA(0, 1, At, B1); PG8_BAR; PG8_SCHED;
	s_waitcnt lgkmcnt(0)
	v_mfma_f32_16x16x32_bf16 v[64:67], v[136:139], v[202:205], v[64:67]
	v_mfma_f32_16x16x32_bf16 v[60:63], v[178:181], v[202:205], v[60:63]
	v_mfma_f32_16x16x32_bf16 v[56:59], v[136:139], v[220:223], v[56:59]
	v_mfma_f32_16x16x32_bf16 v[48:51], v[178:181], v[220:223], v[48:51]
	v_mfma_f32_16x16x32_bf16 v[32:35], v[136:139], v[238:241], v[32:35]
	v_mfma_f32_16x16x32_bf16 v[28:31], v[178:181], v[238:241], v[28:31]
	v_mfma_f32_16x16x32_bf16 v[20:23], v[136:139], v[246:249], v[20:23]
	v_mfma_f32_16x16x32_bf16 v[12:15], v[178:181], v[246:249], v[12:15]
	v_mfma_f32_16x16x32_bf16 v[64:67], v[174:177], v[210:213], v[64:67]
	v_mfma_f32_16x16x32_bf16 v[60:63], v[182:185], v[210:213], v[60:63]
	v_mfma_f32_16x16x32_bf16 v[56:59], v[174:177], v[234:237], v[56:59]
	v_mfma_f32_16x16x32_bf16 v[48:51], v[182:185], v[234:237], v[48:51]
	v_mfma_f32_16x16x32_bf16 v[32:35], v[174:177], v[242:245], v[32:35]
	v_mfma_f32_16x16x32_bf16 v[28:31], v[182:185], v[242:245], v[28:31]
	v_mfma_f32_16x16x32_bf16 v[20:23], v[174:177], v[250:253], v[20:23]
	v_mfma_f32_16x16x32_bf16 v[12:15], v[182:185], v[250:253], v[12:15]
	v_mfma_f32_16x16x32_bf16 v[52:55], v[186:189], v[202:205], v[52:55]
	v_mfma_f32_16x16x32_bf16 v[44:47], v[194:197], v[202:205], v[44:47]
	v_mfma_f32_16x16x32_bf16 v[40:43], v[186:189], v[220:223], v[40:43]
	v_mfma_f32_16x16x32_bf16 v[36:39], v[194:197], v[220:223], v[36:39]
	v_mfma_f32_16x16x32_bf16 v[24:27], v[186:189], v[238:241], v[24:27]
	v_mfma_f32_16x16x32_bf16 v[16:19], v[194:197], v[238:241], v[16:19]
	v_mfma_f32_16x16x32_bf16 v[8:11], v[186:189], v[246:249], v[8:11]
	v_mfma_f32_16x16x32_bf16 v[4:7], v[194:197], v[246:249], v[4:7]
	v_mfma_f32_16x16x32_bf16 v[52:55], v[190:193], v[210:213], v[52:55]
	v_mfma_f32_16x16x32_bf16 v[44:47], v[198:201], v[210:213], v[44:47]
	v_mfma_f32_16x16x32_bf16 v[40:43], v[190:193], v[234:237], v[40:43]
	v_mfma_f32_16x16x32_bf16 v[36:39], v[198:201], v[234:237], v[36:39]
	v_mfma_f32_16x16x32_bf16 v[24:27], v[190:193], v[242:245], v[24:27]
	v_mfma_f32_16x16x32_bf16 v[16:19], v[198:201], v[242:245], v[16:19]
	v_mfma_f32_16x16x32_bf16 v[8:11], v[190:193], v[250:253], v[8:11]
	v_mfma_f32_16x16x32_bf16 v[4:7], v[198:201], v[250:253], v[4:7]
	s_barrier
	s_add_i32 vcc_lo, 0, 0x18000
	v_add_u32_e32 v171, vcc_lo, v151
	s_add_i32 vcc_hi, 0, 0x1c000
	ds_read_b128 v[136:139], v171
	ds_read_b128 v[174:177], v171 offset:1024
	ds_read_b128 v[178:181], v171 offset:2048
	ds_read_b128 v[182:185], v171 offset:3072
	v_add_u32_e32 v171, vcc_hi, v151
	ds_read_b128 v[186:189], v171
	ds_read_b128 v[190:193], v171 offset:1024
	ds_read_b128 v[194:197], v171 offset:2048
	ds_read_b128 v[198:201], v171 offset:3072
	s_add_u32 s12, s92, 0x40000
	s_addc_u32 s13, s93, 0
	s_mov_b32 m0, s86
	v_lshl_add_u64 v[226:227], s[12:13], 0, v[156:157]
	ds_read_b128 v[202:205], v153 offset:32768
	ds_read_b128 v[210:213], v153 offset:33792
	ds_read_b128 v[220:223], v153 offset:34816
	ds_read_b128 v[234:237], v153 offset:35840
	ds_read_b128 v[238:241], v153 offset:36864
	ds_read_b128 v[242:245], v153 offset:37888
	ds_read_b128 v[246:249], v153 offset:38912
	ds_read_b128 v[250:253], v153 offset:39936
	global_load_lds_dwordx4 v[226:227], off
	v_lshl_add_u64 v[226:227], s[12:13], 0, v[158:159]
	s_mov_b32 m0, s87
	s_nop 0
	global_load_lds_dwordx4 v[226:227], off
	s_waitcnt vmcnt(8)
	s_waitcnt lgkmcnt(0)
	s_barrier
	s_waitcnt lgkmcnt(0)
	v_mfma_f32_16x16x32_bf16 v[128:131], v[136:139], v[202:205], v[128:131]
	v_mfma_f32_16x16x32_bf16 v[124:127], v[178:181], v[202:205], v[124:127]
	v_mfma_f32_16x16x32_bf16 v[120:123], v[136:139], v[220:223], v[120:123]
	v_mfma_f32_16x16x32_bf16 v[112:115], v[178:181], v[220:223], v[112:115]
	v_mfma_f32_16x16x32_bf16 v[96:99], v[136:139], v[238:241], v[96:99]
	v_mfma_f32_16x16x32_bf16 v[92:95], v[178:181], v[238:241], v[92:95]
	v_mfma_f32_16x16x32_bf16 v[88:91], v[136:139], v[246:249], v[88:91]
	v_mfma_f32_16x16x32_bf16 v[80:83], v[178:181], v[246:249], v[80:83]
	v_mfma_f32_16x16x32_bf16 v[128:131], v[174:177], v[210:213], v[128:131]
	v_mfma_f32_16x16x32_bf16 v[124:127], v[182:185], v[210:213], v[124:127]
	v_mfma_f32_16x16x32_bf16 v[120:123], v[174:177], v[234:237], v[120:123]
	v_mfma_f32_16x16x32_bf16 v[112:115], v[182:185], v[234:237], v[112:115]
	v_mfma_f32_16x16x32_bf16 v[96:99], v[174:177], v[242:245], v[96:99]
	v_mfma_f32_16x16x32_bf16 v[92:95], v[182:185], v[242:245], v[92:95]
	v_mfma_f32_16x16x32_bf16 v[88:91], v[174:177], v[250:253], v[88:91]
	v_mfma_f32_16x16x32_bf16 v[80:83], v[182:185], v[250:253], v[80:83]
	v_mfma_f32_16x16x32_bf16 v[116:119], v[186:189], v[202:205], v[116:119]
	v_mfma_f32_16x16x32_bf16 v[108:111], v[194:197], v[202:205], v[108:111]
	v_mfma_f32_16x16x32_bf16 v[104:107], v[186:189], v[220:223], v[104:107]
	v_mfma_f32_16x16x32_bf16 v[100:103], v[194:197], v[220:223], v[100:103]
	v_mfma_f32_16x16x32_bf16 v[84:87], v[186:189], v[238:241], v[84:87]
	v_mfma_f32_16x16x32_bf16 v[76:79], v[194:197], v[238:241], v[76:79]
	v_mfma_f32_16x16x32_bf16 v[72:75], v[186:189], v[246:249], v[72:75]
	v_mfma_f32_16x16x32_bf16 v[68:71], v[194:197], v[246:249], v[68:71]
	v_mfma_f32_16x16x32_bf16 v[116:119], v[190:193], v[210:213], v[116:119]
	v_mfma_f32_16x16x32_bf16 v[108:111], v[198:201], v[210:213], v[108:111]
	v_mfma_f32_16x16x32_bf16 v[104:107], v[190:193], v[234:237], v[104:107]
	v_mfma_f32_16x16x32_bf16 v[100:103], v[198:201], v[234:237], v[100:103]
	v_mfma_f32_16x16x32_bf16 v[84:87], v[190:193], v[242:245], v[84:87]
	v_mfma_f32_16x16x32_bf16 v[76:79], v[198:201], v[242:245], v[76:79]
	v_mfma_f32_16x16x32_bf16 v[72:75], v[190:193], v[250:253], v[72:75]
	v_mfma_f32_16x16x32_bf16 v[68:71], v[198:201], v[250:253], v[68:71]
	s_barrier
; #define PG8_STAGE(bufoff, gbase, voff) do { _Pragma("unroll") for (int _i = 0; _i < 2; ++_i) \
;         __builtin_amdgcn_global_load_lds((const unsigned*)((const char*)(gbase) + (voff)[_i]), (LAS unsigned*)(lds + (bufoff) + ldsw + _i * 8192), 16, 0, 0); } while (0)
; #define PG8_LDA(dst, b, h) do { _Pragma("unroll") for (int m = 0; m < 4; ++m) _Pragma("unroll") for (int k = 0; k < 2; ++k) dst[m][k] = *(const LAS bf16x8*)(lds + PG8_SA(b, h) + aoff + m * 2048 + k * 1024); } while (0)
; #define PG8_MMA(ai, bj, At, Bt) do { __builtin_amdgcn_s_setprio(1); _Pragma("unroll") for (int m = 0; m < 4; ++m) _Pragma("unroll") for (int n = 0; n < 2; ++n) _Pragma("unroll") for (int k = 0; k < 2; ++k) \
;         acc[ai][bj][m][n] = __builtin_amdgcn_mfma_f32_16x16x32_bf16(Bt[n][k], At[m][k], acc[ai][bj][m][n], 0, 0, 0); __builtin_amdgcn_s_setprio(0); } while (0)
; #define PG8_WAIT_V(n) asm volatile("s_waitcnt vmcnt(" #n ")" ::: "memory")
; #define PG8_WAIT_L(n) asm volatile("s_waitcnt lgkmcnt(" #n ")" ::: "memory")
; #define PG8_BAR __builtin_amdgcn_s_barrier()
; #define PG8_SCHED __builtin_amdgcn_sched_barrier(0)
; template <class Epi, class Sched>
; __device__ __forceinline__ void gemm_phase(LAS unsigned char* lds, const Gemm g, const Sched& S, const Epi& E, const int tid) {
;     ...
;             PG8_LDA(At, 1, 1); PG8_STAGE(PG8_SB(1, 0), b3, voffB); PG8_STAGE(PG8_SB(1, 1), b3 + hstepB, voffB); PG8_STAGE(PG8_SA(1, 0), a3, voffA);
;             PG8_WAIT_V(8); PG8_WAIT_L(0); PG8_BAR; PG8_MMA(1, 0, At, B0); PG8_MMA(1, 1, At, B1); PG8_BAR; PG8_SCHED;
;         }
;         if (wr == 0) PG8_BAR;
	s_add_i32 s12, vcc_lo, s59
	v_lshl_add_u64 v[154:155], v[154:155], 0, s[28:29]
	s_mov_b32 m0, s12
	ds_read_b128 v[202:205], v153 offset:49152
	ds_read_b128 v[210:213], v153 offset:50176
	ds_read_b128 v[220:223], v153 offset:51200
	ds_read_b128 v[234:237], v153 offset:52224
	ds_read_b128 v[238:241], v153 offset:53248
	ds_read_b128 v[242:245], v153 offset:54272
	ds_read_b128 v[246:249], v153 offset:55296
	ds_read_b128 v[250:253], v153 offset:56320
	global_load_lds_dwordx4 v[154:155], off
	s_add_i32 m0, s12, 0x2000
	s_add_u32 s12, s90, 0x40080
	v_lshl_add_u64 v[154:155], v[162:163], 0, s[28:29]
	s_addc_u32 s13, s91, 0
	s_add_i32 s90, vcc_hi, s59
	global_load_lds_dwordx4 v[154:155], off
	v_lshl_add_u64 v[154:155], s[12:13], 0, v[164:165]
	s_mov_b32 m0, s90
	s_nop 0
	global_load_lds_dwordx4 v[154:155], off
	v_lshl_add_u64 v[154:155], s[12:13], 0, v[160:161]
	s_add_i32 m0, s90, 0x2000
	s_nop 0
	global_load_lds_dwordx4 v[154:155], off
	v_lshl_add_u64 v[154:155], v[206:207], 0, s[28:29]
	s_mov_b32 m0, s88
	s_nop 0
	global_load_lds_dwordx4 v[154:155], off
	v_lshl_add_u64 v[154:155], v[224:225], 0, s[28:29]
	s_mov_b32 m0, s89
	s_nop 0
	global_load_lds_dwordx4 v[154:155], off
	s_waitcnt vmcnt(8)
	s_waitcnt lgkmcnt(0)
	s_barrier
	s_waitcnt lgkmcnt(0)
	v_mfma_f32_16x16x32_bf16 v[64:67], v[136:139], v[202:205], v[64:67]
	v_mfma_f32_16x16x32_bf16 v[60:63], v[178:181], v[202:205], v[60:63]
	v_mfma_f32_16x16x32_bf16 v[56:59], v[136:139], v[220:223], v[56:59]
	v_mfma_f32_16x16x32_bf16 v[48:51], v[178:181], v[220:223], v[48:51]
	v_mfma_f32_16x16x32_bf16 v[32:35], v[136:139], v[238:241], v[32:35]
	v_mfma_f32_16x16x32_bf16 v[28:31], v[178:181], v[238:241], v[28:31]
	v_mfma_f32_16x16x32_bf16 v[20:23], v[136:139], v[246:249], v[20:23]
	v_mfma_f32_16x16x32_bf16 v[12:15], v[178:181], v[246:249], v[12:15]
	v_mfma_f32_16x16x32_bf16 v[64:67], v[174:177], v[210:213], v[64:67]
	v_mfma_f32_16x16x32_bf16 v[60:63], v[182:185], v[210:213], v[60:63]
	v_mfma_f32_16x16x32_bf16 v[56:59], v[174:177], v[234:237], v[56:59]
	v_mfma_f32_16x16x32_bf16 v[48:51], v[182:185], v[234:237], v[48:51]
	v_mfma_f32_16x16x32_bf16 v[32:35], v[174:177], v[242:245], v[32:35]
	v_mfma_f32_16x16x32_bf16 v[28:31], v[182:185], v[242:245], v[28:31]
	v_mfma_f32_16x16x32_bf16 v[20:23], v[174:177], v[250:253], v[20:23]
	v_mfma_f32_16x16x32_bf16 v[12:15], v[182:185], v[250:253], v[12:15]
	v_mfma_f32_16x16x32_bf16 v[52:55], v[186:189], v[202:205], v[52:55]
	v_mfma_f32_16x16x32_bf16 v[44:47], v[194:197], v[202:205], v[44:47]
	v_mfma_f32_16x16x32_bf16 v[40:43], v[186:189], v[220:223], v[40:43]
	v_mfma_f32_16x16x32_bf16 v[36:39], v[194:197], v[220:223], v[36:39]
	v_mfma_f32_16x16x32_bf16 v[24:27], v[186:189], v[238:241], v[24:27]
	v_mfma_f32_16x16x32_bf16 v[16:19], v[194:197], v[238:241], v[16:19]
	v_mfma_f32_16x16x32_bf16 v[8:11], v[186:189], v[246:249], v[8:11]
	v_mfma_f32_16x16x32_bf16 v[4:7], v[194:197], v[246:249], v[4:7]
	v_mfma_f32_16x16x32_bf16 v[52:55], v[190:193], v[210:213], v[52:55]
	v_mfma_f32_16x16x32_bf16 v[44:47], v[198:201], v[210:213], v[44:47]
	v_mfma_f32_16x16x32_bf16 v[40:43], v[190:193], v[234:237], v[40:43]
	v_mfma_f32_16x16x32_bf16 v[36:39], v[198:201], v[234:237], v[36:39]
	v_mfma_f32_16x16x32_bf16 v[24:27], v[190:193], v[242:245], v[24:27]
	v_mfma_f32_16x16x32_bf16 v[16:19], v[198:201], v[242:245], v[16:19]
	v_mfma_f32_16x16x32_bf16 v[8:11], v[190:193], v[250:253], v[8:11]
	v_mfma_f32_16x16x32_bf16 v[4:7], v[198:201], v[250:253], v[4:7]
	s_barrier
	s_add_i32 s97, s97, 2
	s_add_u32 s54, s54, 0x100
	s_addc_u32 s55, s55, 0
	s_add_u32 s47, s47, 0x100
	s_addc_u32 s96, s96, 0
	s_cmp_gt_u32 s97, 13
	s_cbranch_scc0 .LBB0_308
	s_setprio 0
	s_and_b64 vcc, exec, s[20:21]
	s_cbranch_vccz .LBB0_311
	s_barrier

; template <class Epi, class Sched>
; __device__ __forceinline__ void gemm_phase(LAS unsigned char* lds, const Gemm g, const Sched& S, const Epi& E, const int tid) {
;     ...
;     for (;;) {
;         const bool has_next = S.next(ui + 1, nxt);
;         const char* nA = has_next ? (const char*)g.A + (size_t)nxt.pm * tstepA : cA; const char* nB = has_next ? (const char*)g.Bt + (size_t)nxt.pn * tstepB : cB;
;         for (int t = 0; t < nt; t += 2) {
;     ...
; #pragma unroll
;         for (int a = 0; a < 2; ++a)
; #pragma unroll
;             for (int b = 0; b < 2; ++b)
; #pragma unroll
;                 for (int m = 0; m < 4; ++m)
; #pragma unroll
;                     for (int n = 0; n < 2; ++n) acc[a][b][m][n] = (f32x4){0.f, 0.f, 0.f, 0.f};
.LBB0_331:
	s_ashr_i32 s39, s38, 31
	s_lshl_b64 s[12:13], s[38:39], 19
	s_add_u32 s42, s26, s12
	s_addc_u32 s43, s56, s13
	s_and_b64 s[12:13], s[6:7], exec
	s_cselect_b32 s16, s43, s55
	s_cselect_b32 s17, s42, s54
	s_ashr_i32 s31, s30, 31
	s_lshl_b64 s[12:13], s[30:31], 19
	s_add_u32 s44, s57, s12
	s_addc_u32 s45, s58, s13
	s_and_b64 s[12:13], s[6:7], exec
	s_cselect_b32 s31, s45, s91
	s_cselect_b32 s39, s44, s90
	s_add_u32 s54, s54, 0x40080
	s_addc_u32 s55, s55, 0
	s_add_u32 s47, s90, 0x100
	v_mov_b32_e32 v4, 0
	s_addc_u32 s96, s91, 0
	s_mov_b32 s97, -2
	v_mov_b32_e32 v5, v4
	v_mov_b32_e32 v6, v4
	v_mov_b32_e32 v7, v4
	v_mov_b32_e32 v8, v4
	v_mov_b32_e32 v9, v4
	v_mov_b32_e32 v10, v4
	v_mov_b32_e32 v11, v4
	v_mov_b32_e32 v20, v4
	v_mov_b32_e32 v21, v4
	v_mov_b32_e32 v22, v4
	v_mov_b32_e32 v23, v4
	v_mov_b32_e32 v24, v4
	v_mov_b32_e32 v25, v4
	v_mov_b32_e32 v26, v4
	v_mov_b32_e32 v27, v4
	v_mov_b32_e32 v36, v4
	v_mov_b32_e32 v37, v4
	v_mov_b32_e32 v38, v4
	v_mov_b32_e32 v39, v4
	v_mov_b32_e32 v40, v4
	v_mov_b32_e32 v41, v4
	v_mov_b32_e32 v42, v4
	v_mov_b32_e32 v43, v4
	v_mov_b32_e32 v52, v4
	v_mov_b32_e32 v53, v4
	v_mov_b32_e32 v54, v4
	v_mov_b32_e32 v55, v4
	v_mov_b32_e32 v56, v4
	v_mov_b32_e32 v57, v4
	v_mov_b32_e32 v58, v4
	v_mov_b32_e32 v59, v4
	v_mov_b32_e32 v12, v4
	v_mov_b32_e32 v13, v4
	v_mov_b32_e32 v14, v4
	v_mov_b32_e32 v15, v4
	v_mov_b32_e32 v16, v4
	v_mov_b32_e32 v17, v4
	v_mov_b32_e32 v18, v4
	v_mov_b32_e32 v19, v4
	v_mov_b32_e32 v28, v4
	v_mov_b32_e32 v29, v4
	v_mov_b32_e32 v30, v4
	v_mov_b32_e32 v31, v4
	v_mov_b32_e32 v32, v4
	v_mov_b32_e32 v33, v4
	v_mov_b32_e32 v34, v4
	v_mov_b32_e32 v35, v4
	v_mov_b32_e32 v44, v4
	v_mov_b32_e32 v45, v4
	v_mov_b32_e32 v46, v4
	v_mov_b32_e32 v47, v4
	v_mov_b32_e32 v48, v4
	v_mov_b32_e32 v49, v4
	v_mov_b32_e32 v50, v4
	v_mov_b32_e32 v51, v4
	v_mov_b32_e32 v60, v4
	v_mov_b32_e32 v61, v4
	v_mov_b32_e32 v62, v4
	v_mov_b32_e32 v63, v4
	v_mov_b32_e32 v64, v4
	v_mov_b32_e32 v65, v4
	v_mov_b32_e32 v66, v4
	v_mov_b32_e32 v67, v4
	v_mov_b32_e32 v68, v4
	v_mov_b32_e32 v69, v4
	v_mov_b32_e32 v70, v4
	v_mov_b32_e32 v71, v4
	v_mov_b32_e32 v72, v4
	v_mov_b32_e32 v73, v4
	v_mov_b32_e32 v74, v4
	v_mov_b32_e32 v75, v4
	v_mov_b32_e32 v84, v4
	v_mov_b32_e32 v85, v4
	v_mov_b32_e32 v86, v4
	v_mov_b32_e32 v87, v4
	v_mov_b32_e32 v88, v4
	v_mov_b32_e32 v89, v4
	v_mov_b32_e32 v90, v4
	v_mov_b32_e32 v91, v4
	v_mov_b32_e32 v100, v4
	v_mov_b32_e32 v101, v4
	v_mov_b32_e32 v102, v4
	v_mov_b32_e32 v103, v4
	v_mov_b32_e32 v104, v4
	v_mov_b32_e32 v105, v4
	v_mov_b32_e32 v106, v4
	v_mov_b32_e32 v107, v4
	v_mov_b32_e32 v116, v4
	v_mov_b32_e32 v117, v4
	v_mov_b32_e32 v118, v4
	v_mov_b32_e32 v119, v4
	v_mov_b32_e32 v120, v4
	v_mov_b32_e32 v121, v4
	v_mov_b32_e32 v122, v4
	v_mov_b32_e32 v123, v4
	v_mov_b32_e32 v76, v4
	v_mov_b32_e32 v77, v4
	v_mov_b32_e32 v78, v4
	v_mov_b32_e32 v79, v4
	v_mov_b32_e32 v80, v4
	v_mov_b32_e32 v81, v4
	v_mov_b32_e32 v82, v4
	v_mov_b32_e32 v83, v4
	v_mov_b32_e32 v92, v4
	v_mov_b32_e32 v93, v4
	v_mov_b32_e32 v94, v4
	v_mov_b32_e32 v95, v4
	v_mov_b32_e32 v96, v4
	v_mov_b32_e32 v97, v4
	v_mov_b32_e32 v98, v4
	v_mov_b32_e32 v99, v4
	v_mov_b32_e32 v108, v4
	v_mov_b32_e32 v109, v4
	v_mov_b32_e32 v110, v4
	v_mov_b32_e32 v111, v4
	v_mov_b32_e32 v112, v4
	v_mov_b32_e32 v113, v4
	v_mov_b32_e32 v114, v4
	v_mov_b32_e32 v115, v4
	v_mov_b32_e32 v124, v4
	v_mov_b32_e32 v125, v4
	v_mov_b32_e32 v126, v4
	v_mov_b32_e32 v127, v4
	v_mov_b32_e32 v128, v4
	v_mov_b32_e32 v129, v4
	v_mov_b32_e32 v130, v4
	v_mov_b32_e32 v131, v4
	s_cselect_b32 s99, 1, 0
	v_readfirstlane_b32 s98, v173
	s_nop 0
	s_cmpk_lt_u32 s98, 0x100
	s_cbranch_scc1 .Lprio_skip_LBB0332
	s_setprio 1

; #define PG8_STAGE(bufoff, gbase, voff) do { _Pragma("unroll") for (int _i = 0; _i < 2; ++_i) \
;         __builtin_amdgcn_global_load_lds((const unsigned*)((const char*)(gbase) + (voff)[_i]), (LAS unsigned*)(lds + (bufoff) + ldsw + _i * 8192), 16, 0, 0); } while (0)
; #define PG8_LDA(dst, b, h) do { _Pragma("unroll") for (int m = 0; m < 4; ++m) _Pragma("unroll") for (int k = 0; k < 2; ++k) dst[m][k] = *(const LAS bf16x8*)(lds + PG8_SA(b, h) + aoff + m * 2048 + k * 1024); } while (0)
; #define PG8_LDB(dst, b, h) do { _Pragma("unroll") for (int n = 0; n < 2; ++n) _Pragma("unroll") for (int k = 0; k < 2; ++k) dst[n][k] = *(const LAS bf16x8*)(lds + PG8_SB(b, h) + boff + n * 2048 + k * 1024); } while (0)
; #define PG8_MMA(ai, bj, At, Bt) do { __builtin_amdgcn_s_setprio(1); _Pragma("unroll") for (int m = 0; m < 4; ++m) _Pragma("unroll") for (int n = 0; n < 2; ++n) _Pragma("unroll") for (int k = 0; k < 2; ++k) \
;         acc[ai][bj][m][n] = __builtin_amdgcn_mfma_f32_16x16x32_bf16(Bt[n][k], At[m][k], acc[ai][bj][m][n], 0, 0, 0); __builtin_amdgcn_s_setprio(0); } while (0)
; #define PG8_WAIT_V(n) asm volatile("s_waitcnt vmcnt(" #n ")" ::: "memory")
; #define PG8_WAIT_L(n) asm volatile("s_waitcnt lgkmcnt(" #n ")" ::: "memory")
; #define PG8_BAR __builtin_amdgcn_s_barrier()
; #define PG8_SCHED __builtin_amdgcn_sched_barrier(0)
; template <class Epi, class Sched>
; __device__ __forceinline__ void gemm_phase(LAS unsigned char* lds, const Gemm g, const Sched& S, const Epi& E, const int tid) {
;     ...
;         for (int t = 0; t < nt; t += 2) {
;             const bool last = (t == nt - 2);
;             const char* a1 = cA + (size_t)(t + 1) * kstep;
;             const char* a2 = last ? nA : cA + (size_t)(t + 2) * kstep; const char* b2 = last ? nB : cB + (size_t)(t + 2) * kstep;
;             const char* a3 = a2 + kstep; const char* b3 = b2 + kstep;
;             PG8_LDB(B0, 0, 0); PG8_LDB(B1, 0, 1); PG8_SCHED; PG8_LDA(At, 0, 0); PG8_STAGE(PG8_SA(1, 1), a1 + hstepA, voffA);
;             PG8_WAIT_V(8); PG8_WAIT_L(0); PG8_BAR; PG8_MMA(0, 0, At, B0); PG8_MMA(0, 1, At, B1); PG8_BAR; PG8_SCHED;
;             PG8_LDA(At, 0, 1); PG8_STAGE(PG8_SB(0, 0), b2, voffB); PG8_STAGE(PG8_SB(0, 1), b2 + hstepB, voffB); PG8_STAGE(PG8_SA(0, 0), a2, voffA);
;             PG8_WAIT_V(8); PG8_WAIT_L(0); PG8_BAR; PG8_MMA(1, 0, At, B0); PG8_MMA(1, 1, At, B1); PG8_BAR; PG8_SCHED;
.LBB0_332:
	s_add_u32 s12, s54, 0xfffc0080
	s_addc_u32 s13, s55, -1
	s_add_i32 vcc_lo, 0, 0x10000
	s_cmp_eq_u32 s97, 12
	s_cselect_b32 s93, s16, s13
	s_cselect_b32 s92, s17, s12
	s_cselect_b32 s91, s31, s96
	s_cselect_b32 s90, s39, s47
	s_add_i32 vcc_hi, 0, 0x14000
	v_add_u32_e32 v144, vcc_lo, v178
	v_add_u32_e32 v176, vcc_hi, v178
	ds_read_b128 v[132:135], v144
	ds_read_b128 v[136:139], v144 offset:1024
	ds_read_b128 v[140:143], v144 offset:2048
	ds_read_b128 v[144:147], v144 offset:3072
	ds_read_b128 v[148:151], v176
	ds_read_b128 v[152:155], v176 offset:1024
	ds_read_b128 v[182:185], v176 offset:2048
	ds_read_b128 v[186:189], v176 offset:3072
	v_lshl_add_u64 v[176:177], s[54:55], 0, v[162:163]
	s_add_i32 m0, s79, 0xc000
	ds_read_b128 v[190:193], v180
	ds_read_b128 v[194:197], v180 offset:1024
	ds_read_b128 v[198:201], v180 offset:2048
	ds_read_b128 v[202:205], v180 offset:3072
	ds_read_b128 v[210:213], v180 offset:4096
	ds_read_b128 v[220:223], v180 offset:5120
	ds_read_b128 v[234:237], v180 offset:6144
	ds_read_b128 v[238:241], v180 offset:7168
	global_load_lds_dwordx4 v[176:177], off
	v_lshl_add_u64 v[176:177], s[54:55], 0, v[174:175]
	s_add_i32 m0, s79, 0xe000
	s_nop 0
	global_load_lds_dwordx4 v[176:177], off
	s_waitcnt vmcnt(8)
	s_waitcnt lgkmcnt(0)
	s_barrier
	s_waitcnt lgkmcnt(0)
	v_mfma_f32_16x16x32_bf16 v[128:131], v[132:135], v[190:193], v[128:131]
	v_mfma_f32_16x16x32_bf16 v[124:127], v[140:143], v[190:193], v[124:127]
	v_mfma_f32_16x16x32_bf16 v[112:115], v[132:135], v[198:201], v[112:115]
	v_mfma_f32_16x16x32_bf16 v[108:111], v[140:143], v[198:201], v[108:111]
	v_mfma_f32_16x16x32_bf16 v[96:99], v[132:135], v[210:213], v[96:99]
	v_mfma_f32_16x16x32_bf16 v[92:95], v[140:143], v[210:213], v[92:95]
	v_mfma_f32_16x16x32_bf16 v[80:83], v[132:135], v[234:237], v[80:83]
	v_mfma_f32_16x16x32_bf16 v[76:79], v[140:143], v[234:237], v[76:79]
	v_mfma_f32_16x16x32_bf16 v[128:131], v[136:139], v[194:197], v[128:131]
	v_mfma_f32_16x16x32_bf16 v[124:127], v[144:147], v[194:197], v[124:127]
	v_mfma_f32_16x16x32_bf16 v[112:115], v[136:139], v[202:205], v[112:115]
	v_mfma_f32_16x16x32_bf16 v[108:111], v[144:147], v[202:205], v[108:111]
	v_mfma_f32_16x16x32_bf16 v[96:99], v[136:139], v[220:223], v[96:99]
	v_mfma_f32_16x16x32_bf16 v[92:95], v[144:147], v[220:223], v[92:95]
	v_mfma_f32_16x16x32_bf16 v[80:83], v[136:139], v[238:241], v[80:83]
	v_mfma_f32_16x16x32_bf16 v[76:79], v[144:147], v[238:241], v[76:79]
	v_mfma_f32_16x16x32_bf16 v[120:123], v[148:151], v[190:193], v[120:123]
	v_mfma_f32_16x16x32_bf16 v[116:119], v[182:185], v[190:193], v[116:119]
	v_mfma_f32_16x16x32_bf16 v[104:107], v[148:151], v[198:201], v[104:107]
	v_mfma_f32_16x16x32_bf16 v[100:103], v[182:185], v[198:201], v[100:103]
	v_mfma_f32_16x16x32_bf16 v[88:91], v[148:151], v[210:213], v[88:91]
	v_mfma_f32_16x16x32_bf16 v[84:87], v[182:185], v[210:213], v[84:87]
	v_mfma_f32_16x16x32_bf16 v[72:75], v[148:151], v[234:237], v[72:75]
	v_mfma_f32_16x16x32_bf16 v[68:71], v[182:185], v[234:237], v[68:71]
	v_mfma_f32_16x16x32_bf16 v[120:123], v[152:155], v[194:197], v[120:123]
	v_mfma_f32_16x16x32_bf16 v[116:119], v[186:189], v[194:197], v[116:119]
	v_mfma_f32_16x16x32_bf16 v[104:107], v[152:155], v[202:205], v[104:107]
	v_mfma_f32_16x16x32_bf16 v[100:103], v[186:189], v[202:205], v[100:103]
	v_mfma_f32_16x16x32_bf16 v[88:91], v[152:155], v[220:223], v[88:91]
	v_mfma_f32_16x16x32_bf16 v[84:87], v[186:189], v[220:223], v[84:87]
	v_mfma_f32_16x16x32_bf16 v[72:75], v[152:155], v[238:241], v[72:75]
	v_mfma_f32_16x16x32_bf16 v[68:71], v[186:189], v[238:241], v[68:71]
	s_barrier
	s_add_i32 s12, vcc_lo, s59
	v_lshl_add_u64 v[176:177], s[90:91], 0, v[164:165]
	s_mov_b32 m0, s12
	ds_read_b128 v[190:193], v180 offset:16384
	ds_read_b128 v[194:197], v180 offset:17408
	ds_read_b128 v[198:201], v180 offset:18432
	ds_read_b128 v[202:205], v180 offset:19456
	ds_read_b128 v[210:213], v180 offset:20480
	ds_read_b128 v[220:223], v180 offset:21504
	ds_read_b128 v[234:237], v180 offset:22528
	ds_read_b128 v[238:241], v180 offset:23552
	global_load_lds_dwordx4 v[176:177], off
	s_add_i32 m0, s12, 0x2000
	s_add_u32 s12, s90, 0x40000
	v_lshl_add_u64 v[206:207], s[90:91], 0, v[160:161]
	s_addc_u32 s13, s91, 0
	s_add_i32 vcc_lo, vcc_hi, s59
	global_load_lds_dwordx4 v[206:207], off
	v_lshl_add_u64 v[224:225], s[12:13], 0, v[164:165]
	s_mov_b32 m0, vcc_lo
	v_lshl_add_u64 v[226:227], s[92:93], 0, v[158:159]
	global_load_lds_dwordx4 v[224:225], off
	v_lshl_add_u64 v[224:225], s[12:13], 0, v[160:161]
	s_add_i32 m0, vcc_lo, 0x2000
	s_nop 0
	global_load_lds_dwordx4 v[224:225], off
	v_lshl_add_u64 v[224:225], s[92:93], 0, v[156:157]
	s_mov_b32 m0, s79
	s_nop 0
	global_load_lds_dwordx4 v[224:225], off
	s_mov_b32 m0, s85
	s_nop 0
	global_load_lds_dwordx4 v[226:227], off
	s_waitcnt vmcnt(8)
	s_waitcnt lgkmcnt(0)
	s_barrier
; #define PG8_STAGE(bufoff, gbase, voff) do { _Pragma("unroll") for (int _i = 0; _i < 2; ++_i) \
;         __builtin_amdgcn_global_load_lds((const unsigned*)((const char*)(gbase) + (voff)[_i]), (LAS unsigned*)(lds + (bufoff) + ldsw + _i * 8192), 16, 0, 0); } while (0)
; #define PG8_LDA(dst, b, h) do { _Pragma("unroll") for (int m = 0; m < 4; ++m) _Pragma("unroll") for (int k = 0; k < 2; ++k) dst[m][k] = *(const LAS bf16x8*)(lds + PG8_SA(b, h) + aoff + m * 2048 + k * 1024); } while (0)
; #define PG8_LDB(dst, b, h) do { _Pragma("unroll") for (int n = 0; n < 2; ++n) _Pragma("unroll") for (int k = 0; k < 2; ++k) dst[n][k] = *(const LAS bf16x8*)(lds + PG8_SB(b, h) + boff + n * 2048 + k * 1024); } while (0)
; #define PG8_MMA(ai, bj, At, Bt) do { __builtin_amdgcn_s_setprio(1); _Pragma("unroll") for (int m = 0; m < 4; ++m) _Pragma("unroll") for (int n = 0; n < 2; ++n) _Pragma("unroll") for (int k = 0; k < 2; ++k) \
;         acc[ai][bj][m][n] = __builtin_amdgcn_mfma_f32_16x16x32_bf16(Bt[n][k], At[m][k], acc[ai][bj][m][n], 0, 0, 0); __builtin_amdgcn_s_setprio(0); } while (0)
; #define PG8_WAIT_V(n) asm volatile("s_waitcnt vmcnt(" #n ")" ::: "memory")
; #define PG8_WAIT_L(n) asm volatile("s_waitcnt lgkmcnt(" #n ")" ::: "memory")
; #define PG8_BAR __builtin_amdgcn_s_barrier()
; #define PG8_SCHED __builtin_amdgcn_sched_barrier(0)
; template <class Epi, class Sched>
; __device__ __forceinline__ void gemm_phase(LAS unsigned char* lds, const Gemm g, const Sched& S, const Epi& E, const int tid) {
;     ...
;             PG8_WAIT_V(8); PG8_WAIT_L(0); PG8_BAR; PG8_MMA(1, 0, At, B0); PG8_MMA(1, 1, At, B1); PG8_BAR; PG8_SCHED;
;             PG8_LDB(B0, 1, 0); PG8_LDB(B1, 1, 1); PG8_SCHED; PG8_LDA(At, 1, 0); PG8_STAGE(PG8_SA(0, 1), a2 + hstepA, voffA);
;             PG8_WAIT_V(8); PG8_WAIT_L(0); PG8_BAR; PG8_MMA(0, 0, At, B0); PG8_MMA(0, 1, At, B1); PG8_BAR; PG8_SCHED;
	s_waitcnt lgkmcnt(0)
	v_mfma_f32_16x16x32_bf16 v[64:67], v[132:135], v[190:193], v[64:67]
	v_mfma_f32_16x16x32_bf16 v[60:63], v[140:143], v[190:193], v[60:63]
	v_mfma_f32_16x16x32_bf16 v[48:51], v[132:135], v[198:201], v[48:51]
	v_mfma_f32_16x16x32_bf16 v[44:47], v[140:143], v[198:201], v[44:47]
	v_mfma_f32_16x16x32_bf16 v[32:35], v[132:135], v[210:213], v[32:35]
	v_mfma_f32_16x16x32_bf16 v[28:31], v[140:143], v[210:213], v[28:31]
	v_mfma_f32_16x16x32_bf16 v[16:19], v[132:135], v[234:237], v[16:19]
	v_mfma_f32_16x16x32_bf16 v[12:15], v[140:143], v[234:237], v[12:15]
	v_mfma_f32_16x16x32_bf16 v[64:67], v[136:139], v[194:197], v[64:67]
	v_mfma_f32_16x16x32_bf16 v[60:63], v[144:147], v[194:197], v[60:63]
	v_mfma_f32_16x16x32_bf16 v[48:51], v[136:139], v[202:205], v[48:51]
	v_mfma_f32_16x16x32_bf16 v[44:47], v[144:147], v[202:205], v[44:47]
	v_mfma_f32_16x16x32_bf16 v[32:35], v[136:139], v[220:223], v[32:35]
	v_mfma_f32_16x16x32_bf16 v[28:31], v[144:147], v[220:223], v[28:31]
	v_mfma_f32_16x16x32_bf16 v[16:19], v[136:139], v[238:241], v[16:19]
	v_mfma_f32_16x16x32_bf16 v[12:15], v[144:147], v[238:241], v[12:15]
	v_mfma_f32_16x16x32_bf16 v[56:59], v[148:151], v[190:193], v[56:59]
	v_mfma_f32_16x16x32_bf16 v[52:55], v[182:185], v[190:193], v[52:55]
	v_mfma_f32_16x16x32_bf16 v[40:43], v[148:151], v[198:201], v[40:43]
	v_mfma_f32_16x16x32_bf16 v[36:39], v[182:185], v[198:201], v[36:39]
	v_mfma_f32_16x16x32_bf16 v[24:27], v[148:151], v[210:213], v[24:27]
	v_mfma_f32_16x16x32_bf16 v[20:23], v[182:185], v[210:213], v[20:23]
	v_mfma_f32_16x16x32_bf16 v[8:11], v[148:151], v[234:237], v[8:11]
	v_mfma_f32_16x16x32_bf16 v[4:7], v[182:185], v[234:237], v[4:7]
	v_mfma_f32_16x16x32_bf16 v[56:59], v[152:155], v[194:197], v[56:59]
	v_mfma_f32_16x16x32_bf16 v[52:55], v[186:189], v[194:197], v[52:55]
	v_mfma_f32_16x16x32_bf16 v[40:43], v[152:155], v[202:205], v[40:43]
	v_mfma_f32_16x16x32_bf16 v[36:39], v[186:189], v[202:205], v[36:39]
	v_mfma_f32_16x16x32_bf16 v[24:27], v[152:155], v[220:223], v[24:27]
	v_mfma_f32_16x16x32_bf16 v[20:23], v[186:189], v[220:223], v[20:23]
	v_mfma_f32_16x16x32_bf16 v[8:11], v[152:155], v[238:241], v[8:11]
	v_mfma_f32_16x16x32_bf16 v[4:7], v[186:189], v[238:241], v[4:7]
	s_barrier
	s_add_i32 vcc_lo, 0, 0x18000
	s_add_i32 vcc_hi, 0, 0x1c000
	v_add_u32_e32 v144, vcc_lo, v178
	v_add_u32_e32 v181, vcc_hi, v178
	ds_read_b128 v[132:135], v144
	ds_read_b128 v[136:139], v144 offset:1024
	ds_read_b128 v[140:143], v144 offset:2048
	ds_read_b128 v[144:147], v144 offset:3072
	ds_read_b128 v[148:151], v181
	ds_read_b128 v[152:155], v181 offset:1024
	ds_read_b128 v[182:185], v181 offset:2048
	ds_read_b128 v[186:189], v181 offset:3072
	s_add_u32 s12, s92, 0x40000
	s_addc_u32 s13, s93, 0
	s_mov_b32 m0, s86
	v_lshl_add_u64 v[242:243], s[12:13], 0, v[156:157]
	ds_read_b128 v[190:193], v180 offset:32768
	ds_read_b128 v[194:197], v180 offset:33792
	ds_read_b128 v[198:201], v180 offset:34816
	ds_read_b128 v[202:205], v180 offset:35840
	ds_read_b128 v[210:213], v180 offset:36864
	ds_read_b128 v[220:223], v180 offset:37888
	ds_read_b128 v[234:237], v180 offset:38912
	ds_read_b128 v[238:241], v180 offset:39936
	global_load_lds_dwordx4 v[242:243], off
	v_lshl_add_u64 v[242:243], s[12:13], 0, v[158:159]
	s_mov_b32 m0, s87
	s_nop 0
	global_load_lds_dwordx4 v[242:243], off
	s_waitcnt vmcnt(8)
	s_waitcnt lgkmcnt(0)
	s_barrier
	s_waitcnt lgkmcnt(0)
	v_mfma_f32_16x16x32_bf16 v[128:131], v[132:135], v[190:193], v[128:131]
	v_mfma_f32_16x16x32_bf16 v[124:127], v[140:143], v[190:193], v[124:127]
	v_mfma_f32_16x16x32_bf16 v[112:115], v[132:135], v[198:201], v[112:115]
	v_mfma_f32_16x16x32_bf16 v[108:111], v[140:143], v[198:201], v[108:111]
	v_mfma_f32_16x16x32_bf16 v[96:99], v[132:135], v[210:213], v[96:99]
	v_mfma_f32_16x16x32_bf16 v[92:95], v[140:143], v[210:213], v[92:95]
	v_mfma_f32_16x16x32_bf16 v[80:83], v[132:135], v[234:237], v[80:83]
	v_mfma_f32_16x16x32_bf16 v[76:79], v[140:143], v[234:237], v[76:79]
	v_mfma_f32_16x16x32_bf16 v[128:131], v[136:139], v[194:197], v[128:131]
	v_mfma_f32_16x16x32_bf16 v[124:127], v[144:147], v[194:197], v[124:127]
	v_mfma_f32_16x16x32_bf16 v[112:115], v[136:139], v[202:205], v[112:115]
	v_mfma_f32_16x16x32_bf16 v[108:111], v[144:147], v[202:205], v[108:111]
	v_mfma_f32_16x16x32_bf16 v[96:99], v[136:139], v[220:223], v[96:99]
	v_mfma_f32_16x16x32_bf16 v[92:95], v[144:147], v[220:223], v[92:95]
	v_mfma_f32_16x16x32_bf16 v[80:83], v[136:139], v[238:241], v[80:83]
	v_mfma_f32_16x16x32_bf16 v[76:79], v[144:147], v[238:241], v[76:79]
	v_mfma_f32_16x16x32_bf16 v[120:123], v[148:151], v[190:193], v[120:123]
	v_mfma_f32_16x16x32_bf16 v[116:119], v[182:185], v[190:193], v[116:119]
	v_mfma_f32_16x16x32_bf16 v[104:107], v[148:151], v[198:201], v[104:107]
	v_mfma_f32_16x16x32_bf16 v[100:103], v[182:185], v[198:201], v[100:103]
	v_mfma_f32_16x16x32_bf16 v[88:91], v[148:151], v[210:213], v[88:91]
	v_mfma_f32_16x16x32_bf16 v[84:87], v[182:185], v[210:213], v[84:87]
	v_mfma_f32_16x16x32_bf16 v[72:75], v[148:151], v[234:237], v[72:75]
	v_mfma_f32_16x16x32_bf16 v[68:71], v[182:185], v[234:237], v[68:71]
	v_mfma_f32_16x16x32_bf16 v[120:123], v[152:155], v[194:197], v[120:123]
	v_mfma_f32_16x16x32_bf16 v[116:119], v[186:189], v[194:197], v[116:119]
	v_mfma_f32_16x16x32_bf16 v[104:107], v[152:155], v[202:205], v[104:107]
	v_mfma_f32_16x16x32_bf16 v[100:103], v[186:189], v[202:205], v[100:103]
	v_mfma_f32_16x16x32_bf16 v[88:91], v[152:155], v[220:223], v[88:91]
	v_mfma_f32_16x16x32_bf16 v[84:87], v[186:189], v[220:223], v[84:87]
	v_mfma_f32_16x16x32_bf16 v[72:75], v[152:155], v[238:241], v[72:75]
	v_mfma_f32_16x16x32_bf16 v[68:71], v[186:189], v[238:241], v[68:71]
	s_barrier
; #define PG8_STAGE(bufoff, gbase, voff) do { _Pragma("unroll") for (int _i = 0; _i < 2; ++_i) \
;         __builtin_amdgcn_global_load_lds((const unsigned*)((const char*)(gbase) + (voff)[_i]), (LAS unsigned*)(lds + (bufoff) + ldsw + _i * 8192), 16, 0, 0); } while (0)
; #define PG8_LDA(dst, b, h) do { _Pragma("unroll") for (int m = 0; m < 4; ++m) _Pragma("unroll") for (int k = 0; k < 2; ++k) dst[m][k] = *(const LAS bf16x8*)(lds + PG8_SA(b, h) + aoff + m * 2048 + k * 1024); } while (0)
; #define PG8_MMA(ai, bj, At, Bt) do { __builtin_amdgcn_s_setprio(1); _Pragma("unroll") for (int m = 0; m < 4; ++m) _Pragma("unroll") for (int n = 0; n < 2; ++n) _Pragma("unroll") for (int k = 0; k < 2; ++k) \
;         acc[ai][bj][m][n] = __builtin_amdgcn_mfma_f32_16x16x32_bf16(Bt[n][k], At[m][k], acc[ai][bj][m][n], 0, 0, 0); __builtin_amdgcn_s_setprio(0); } while (0)
; #define PG8_WAIT_V(n) asm volatile("s_waitcnt vmcnt(" #n ")" ::: "memory")
; #define PG8_WAIT_L(n) asm volatile("s_waitcnt lgkmcnt(" #n ")" ::: "memory")
; #define PG8_BAR __builtin_amdgcn_s_barrier()
; #define PG8_SCHED __builtin_amdgcn_sched_barrier(0)
; template <class Epi, class Sched>
; __device__ __forceinline__ void gemm_phase(LAS unsigned char* lds, const Gemm g, const Sched& S, const Epi& E, const int tid) {
;     ...
;             PG8_LDA(At, 1, 1); PG8_STAGE(PG8_SB(1, 0), b3, voffB); PG8_STAGE(PG8_SB(1, 1), b3 + hstepB, voffB); PG8_STAGE(PG8_SA(1, 0), a3, voffA);
;             PG8_WAIT_V(8); PG8_WAIT_L(0); PG8_BAR; PG8_MMA(1, 0, At, B0); PG8_MMA(1, 1, At, B1); PG8_BAR; PG8_SCHED;
;         }
;         if (wr == 0) PG8_BAR;
	s_add_i32 s12, vcc_lo, s59
	v_lshl_add_u64 v[176:177], v[176:177], 0, s[28:29]
	s_mov_b32 m0, s12
	ds_read_b128 v[190:193], v180 offset:49152
	ds_read_b128 v[194:197], v180 offset:50176
	ds_read_b128 v[198:201], v180 offset:51200
	ds_read_b128 v[202:205], v180 offset:52224
	ds_read_b128 v[210:213], v180 offset:53248
	ds_read_b128 v[220:223], v180 offset:54272
	ds_read_b128 v[234:237], v180 offset:55296
	ds_read_b128 v[238:241], v180 offset:56320
	global_load_lds_dwordx4 v[176:177], off
	s_add_i32 m0, s12, 0x2000
	s_add_u32 s12, s90, 0x40080
	v_lshl_add_u64 v[176:177], v[206:207], 0, s[28:29]
	s_addc_u32 s13, s91, 0
	s_add_i32 s90, vcc_hi, s59
	global_load_lds_dwordx4 v[176:177], off
	v_lshl_add_u64 v[176:177], s[12:13], 0, v[164:165]
	s_mov_b32 m0, s90
	s_nop 0
	global_load_lds_dwordx4 v[176:177], off
	v_lshl_add_u64 v[176:177], s[12:13], 0, v[160:161]
	s_add_i32 m0, s90, 0x2000
	s_nop 0
	global_load_lds_dwordx4 v[176:177], off
	v_lshl_add_u64 v[176:177], v[224:225], 0, s[28:29]
	s_mov_b32 m0, s88
	s_nop 0
	global_load_lds_dwordx4 v[176:177], off
	v_lshl_add_u64 v[176:177], v[226:227], 0, s[28:29]
	s_mov_b32 m0, s89
	s_nop 0
	global_load_lds_dwordx4 v[176:177], off
	s_waitcnt vmcnt(8)
	s_waitcnt lgkmcnt(0)
	s_barrier
	s_waitcnt lgkmcnt(0)
	v_mfma_f32_16x16x32_bf16 v[64:67], v[132:135], v[190:193], v[64:67]
	v_mfma_f32_16x16x32_bf16 v[60:63], v[140:143], v[190:193], v[60:63]
	v_mfma_f32_16x16x32_bf16 v[48:51], v[132:135], v[198:201], v[48:51]
	v_mfma_f32_16x16x32_bf16 v[44:47], v[140:143], v[198:201], v[44:47]
	v_mfma_f32_16x16x32_bf16 v[32:35], v[132:135], v[210:213], v[32:35]
	v_mfma_f32_16x16x32_bf16 v[28:31], v[140:143], v[210:213], v[28:31]
	v_mfma_f32_16x16x32_bf16 v[16:19], v[132:135], v[234:237], v[16:19]
	v_mfma_f32_16x16x32_bf16 v[12:15], v[140:143], v[234:237], v[12:15]
	v_mfma_f32_16x16x32_bf16 v[64:67], v[136:139], v[194:197], v[64:67]
	v_mfma_f32_16x16x32_bf16 v[60:63], v[144:147], v[194:197], v[60:63]
	v_mfma_f32_16x16x32_bf16 v[48:51], v[136:139], v[202:205], v[48:51]
	v_mfma_f32_16x16x32_bf16 v[44:47], v[144:147], v[202:205], v[44:47]
	v_mfma_f32_16x16x32_bf16 v[32:35], v[136:139], v[220:223], v[32:35]
	v_mfma_f32_16x16x32_bf16 v[28:31], v[144:147], v[220:223], v[28:31]
	v_mfma_f32_16x16x32_bf16 v[16:19], v[136:139], v[238:241], v[16:19]
	v_mfma_f32_16x16x32_bf16 v[12:15], v[144:147], v[238:241], v[12:15]
	v_mfma_f32_16x16x32_bf16 v[56:59], v[148:151], v[190:193], v[56:59]
	v_mfma_f32_16x16x32_bf16 v[52:55], v[182:185], v[190:193], v[52:55]
	v_mfma_f32_16x16x32_bf16 v[40:43], v[148:151], v[198:201], v[40:43]
	v_mfma_f32_16x16x32_bf16 v[36:39], v[182:185], v[198:201], v[36:39]
	v_mfma_f32_16x16x32_bf16 v[24:27], v[148:151], v[210:213], v[24:27]
	v_mfma_f32_16x16x32_bf16 v[20:23], v[182:185], v[210:213], v[20:23]
	v_mfma_f32_16x16x32_bf16 v[8:11], v[148:151], v[234:237], v[8:11]
	v_mfma_f32_16x16x32_bf16 v[4:7], v[182:185], v[234:237], v[4:7]
	v_mfma_f32_16x16x32_bf16 v[56:59], v[152:155], v[194:197], v[56:59]
	v_mfma_f32_16x16x32_bf16 v[52:55], v[186:189], v[194:197], v[52:55]
	v_mfma_f32_16x16x32_bf16 v[40:43], v[152:155], v[202:205], v[40:43]
	v_mfma_f32_16x16x32_bf16 v[36:39], v[186:189], v[202:205], v[36:39]
	v_mfma_f32_16x16x32_bf16 v[24:27], v[152:155], v[220:223], v[24:27]
	v_mfma_f32_16x16x32_bf16 v[20:23], v[186:189], v[220:223], v[20:23]
	v_mfma_f32_16x16x32_bf16 v[8:11], v[152:155], v[238:241], v[8:11]
	v_mfma_f32_16x16x32_bf16 v[4:7], v[186:189], v[238:241], v[4:7]
	s_barrier
	s_add_i32 s97, s97, 2
	s_add_u32 s54, s54, 0x100
	s_addc_u32 s55, s55, 0
	s_add_u32 s47, s47, 0x100
	s_addc_u32 s96, s96, 0
	s_cmp_gt_u32 s97, 13
	s_cbranch_scc0 .LBB0_332
	s_setprio 0
	s_and_b64 vcc, exec, s[20:21]
	s_cbranch_vccz .LBB0_335
	s_barrier

; template <class Epi, class Sched>
; __device__ __forceinline__ void gemm_phase(LAS unsigned char* lds, const Gemm g, const Sched& S, const Epi& E, const int tid) {
;     ...
;     for (;;) {
;         const bool has_next = S.next(ui + 1, nxt);
;         const char* nA = has_next ? (const char*)g.A + (size_t)nxt.pm * tstepA : cA; const char* nB = has_next ? (const char*)g.Bt + (size_t)nxt.pn * tstepB : cB;
;         for (int t = 0; t < nt; t += 2) {
;     ...
; #pragma unroll
;         for (int a = 0; a < 2; ++a)
; #pragma unroll
;             for (int b = 0; b < 2; ++b)
; #pragma unroll
;                 for (int m = 0; m < 4; ++m)
; #pragma unroll
;                     for (int n = 0; n < 2; ++n) acc[a][b][m][n] = (f32x4){0.f, 0.f, 0.f, 0.f};
.LBB0_588:
	s_ashr_i32 s39, s38, 31
	s_lshl_b64 s[42:43], s[38:39], 20
	v_readlane_b32 s0, v255, 26
	s_add_u32 s42, s0, s42
	s_addc_u32 s43, s75, s43
	s_and_b64 s[44:45], s[6:7], exec
	s_cselect_b32 s0, s43, s47
	s_cselect_b32 s9, s42, s46
	s_ashr_i32 s31, s30, 31
	s_lshl_b64 s[44:45], s[30:31], 20
	s_add_u32 s44, s80, s44
	s_addc_u32 s45, s81, s45
	s_and_b64 s[84:85], s[6:7], exec
	s_cselect_b32 s11, s45, s55
	s_cselect_b32 s31, s44, s54
	s_add_u32 s46, s46, 0x80080
	s_addc_u32 s47, s47, 0
	s_add_u32 s39, s54, 0x100
	v_mov_b32_e32 v4, 0
	s_addc_u32 s86, s55, 0
	s_mov_b32 s87, -2
	v_mov_b32_e32 v5, v4
	v_mov_b32_e32 v6, v4
	v_mov_b32_e32 v7, v4
	v_mov_b32_e32 v8, v4
	v_mov_b32_e32 v9, v4
	v_mov_b32_e32 v10, v4
	v_mov_b32_e32 v11, v4
	v_mov_b32_e32 v12, v4
	v_mov_b32_e32 v13, v4
	v_mov_b32_e32 v14, v4
	v_mov_b32_e32 v15, v4
	v_mov_b32_e32 v16, v4
	v_mov_b32_e32 v17, v4
	v_mov_b32_e32 v18, v4
	v_mov_b32_e32 v19, v4
	v_mov_b32_e32 v20, v4
	v_mov_b32_e32 v21, v4
	v_mov_b32_e32 v22, v4
	v_mov_b32_e32 v23, v4
	v_mov_b32_e32 v24, v4
	v_mov_b32_e32 v25, v4
	v_mov_b32_e32 v26, v4
	v_mov_b32_e32 v27, v4
	v_mov_b32_e32 v28, v4
	v_mov_b32_e32 v29, v4
	v_mov_b32_e32 v30, v4
	v_mov_b32_e32 v31, v4
	v_mov_b32_e32 v32, v4
	v_mov_b32_e32 v33, v4
	v_mov_b32_e32 v34, v4
	v_mov_b32_e32 v35, v4
	v_mov_b32_e32 v68, v4
	v_mov_b32_e32 v69, v4
	v_mov_b32_e32 v70, v4
	v_mov_b32_e32 v71, v4
	v_mov_b32_e32 v72, v4
	v_mov_b32_e32 v73, v4
	v_mov_b32_e32 v74, v4
	v_mov_b32_e32 v75, v4
	v_mov_b32_e32 v76, v4
	v_mov_b32_e32 v77, v4
	v_mov_b32_e32 v78, v4
	v_mov_b32_e32 v79, v4
	v_mov_b32_e32 v80, v4
	v_mov_b32_e32 v81, v4
	v_mov_b32_e32 v82, v4
	v_mov_b32_e32 v83, v4
	v_mov_b32_e32 v84, v4
	v_mov_b32_e32 v85, v4
	v_mov_b32_e32 v86, v4
	v_mov_b32_e32 v87, v4
	v_mov_b32_e32 v88, v4
	v_mov_b32_e32 v89, v4
	v_mov_b32_e32 v90, v4
	v_mov_b32_e32 v91, v4
	v_mov_b32_e32 v92, v4
	v_mov_b32_e32 v93, v4
	v_mov_b32_e32 v94, v4
	v_mov_b32_e32 v95, v4
	v_mov_b32_e32 v96, v4
	v_mov_b32_e32 v97, v4
	v_mov_b32_e32 v98, v4
	v_mov_b32_e32 v99, v4
	v_mov_b32_e32 v36, v4
	v_mov_b32_e32 v37, v4
	v_mov_b32_e32 v38, v4
	v_mov_b32_e32 v39, v4
	v_mov_b32_e32 v40, v4
	v_mov_b32_e32 v41, v4
	v_mov_b32_e32 v42, v4
	v_mov_b32_e32 v43, v4
	v_mov_b32_e32 v44, v4
	v_mov_b32_e32 v45, v4
	v_mov_b32_e32 v46, v4
	v_mov_b32_e32 v47, v4
	v_mov_b32_e32 v48, v4
	v_mov_b32_e32 v49, v4
	v_mov_b32_e32 v50, v4
	v_mov_b32_e32 v51, v4
	v_mov_b32_e32 v52, v4
	v_mov_b32_e32 v53, v4
	v_mov_b32_e32 v54, v4
	v_mov_b32_e32 v55, v4
	v_mov_b32_e32 v56, v4
	v_mov_b32_e32 v57, v4
	v_mov_b32_e32 v58, v4
	v_mov_b32_e32 v59, v4
	v_mov_b32_e32 v60, v4
	v_mov_b32_e32 v61, v4
	v_mov_b32_e32 v62, v4
	v_mov_b32_e32 v63, v4
	v_mov_b32_e32 v64, v4
	v_mov_b32_e32 v65, v4
	v_mov_b32_e32 v66, v4
	v_mov_b32_e32 v67, v4
	v_mov_b32_e32 v108, v4
	v_mov_b32_e32 v109, v4
	v_mov_b32_e32 v110, v4
	v_mov_b32_e32 v111, v4
	v_mov_b32_e32 v112, v4
	v_mov_b32_e32 v113, v4
	v_mov_b32_e32 v114, v4
	v_mov_b32_e32 v115, v4
	v_mov_b32_e32 v116, v4
	v_mov_b32_e32 v117, v4
	v_mov_b32_e32 v118, v4
	v_mov_b32_e32 v119, v4
	v_mov_b32_e32 v120, v4
	v_mov_b32_e32 v121, v4
	v_mov_b32_e32 v122, v4
	v_mov_b32_e32 v123, v4
	v_mov_b32_e32 v124, v4
	v_mov_b32_e32 v125, v4
	v_mov_b32_e32 v126, v4
	v_mov_b32_e32 v127, v4
	v_mov_b32_e32 v128, v4
	v_mov_b32_e32 v129, v4
	v_mov_b32_e32 v130, v4
	v_mov_b32_e32 v131, v4
	v_mov_b32_e32 v132, v4
	v_mov_b32_e32 v133, v4
	v_mov_b32_e32 v134, v4
	v_mov_b32_e32 v135, v4
	v_mov_b32_e32 v136, v4
	v_mov_b32_e32 v137, v4
	v_mov_b32_e32 v138, v4
	v_mov_b32_e32 v139, v4
	s_cselect_b32 s99, 1, 0
	v_readfirstlane_b32 s98, v173
	s_nop 0
	s_cmpk_lt_u32 s98, 0x100
	s_cbranch_scc1 .Lprio_skip_LBB0589
	s_setprio 1

; #define PG8_STAGE(bufoff, gbase, voff) do { _Pragma("unroll") for (int _i = 0; _i < 2; ++_i) \
;         __builtin_amdgcn_global_load_lds((const unsigned*)((const char*)(gbase) + (voff)[_i]), (LAS unsigned*)(lds + (bufoff) + ldsw + _i * 8192), 16, 0, 0); } while (0)
; #define PG8_LDA(dst, b, h) do { _Pragma("unroll") for (int m = 0; m < 4; ++m) _Pragma("unroll") for (int k = 0; k < 2; ++k) dst[m][k] = *(const LAS bf16x8*)(lds + PG8_SA(b, h) + aoff + m * 2048 + k * 1024); } while (0)
; #define PG8_LDB(dst, b, h) do { _Pragma("unroll") for (int n = 0; n < 2; ++n) _Pragma("unroll") for (int k = 0; k < 2; ++k) dst[n][k] = *(const LAS bf16x8*)(lds + PG8_SB(b, h) + boff + n * 2048 + k * 1024); } while (0)
; #define PG8_MMA(ai, bj, At, Bt) do { __builtin_amdgcn_s_setprio(1); _Pragma("unroll") for (int m = 0; m < 4; ++m) _Pragma("unroll") for (int n = 0; n < 2; ++n) _Pragma("unroll") for (int k = 0; k < 2; ++k) \
;         acc[ai][bj][m][n] = __builtin_amdgcn_mfma_f32_16x16x32_bf16(Bt[n][k], At[m][k], acc[ai][bj][m][n], 0, 0, 0); __builtin_amdgcn_s_setprio(0); } while (0)
; #define PG8_WAIT_V(n) asm volatile("s_waitcnt vmcnt(" #n ")" ::: "memory")
; #define PG8_WAIT_L(n) asm volatile("s_waitcnt lgkmcnt(" #n ")" ::: "memory")
; #define PG8_BAR __builtin_amdgcn_s_barrier()
; #define PG8_SCHED __builtin_amdgcn_sched_barrier(0)
; template <class Epi, class Sched>
; __device__ __forceinline__ void gemm_phase(LAS unsigned char* lds, const Gemm g, const Sched& S, const Epi& E, const int tid) {
;     ...
;         for (int t = 0; t < nt; t += 2) {
;             const bool last = (t == nt - 2);
;             const char* a1 = cA + (size_t)(t + 1) * kstep;
;             const char* a2 = last ? nA : cA + (size_t)(t + 2) * kstep; const char* b2 = last ? nB : cB + (size_t)(t + 2) * kstep;
;             const char* a3 = a2 + kstep; const char* b3 = b2 + kstep;
;             PG8_LDB(B0, 0, 0); PG8_LDB(B1, 0, 1); PG8_SCHED; PG8_LDA(At, 0, 0); PG8_STAGE(PG8_SA(1, 1), a1 + hstepA, voffA);
;             PG8_WAIT_V(8); PG8_WAIT_L(0); PG8_BAR; PG8_MMA(0, 0, At, B0); PG8_MMA(0, 1, At, B1); PG8_BAR; PG8_SCHED;
;             PG8_LDA(At, 0, 1); PG8_STAGE(PG8_SB(0, 0), b2, voffB); PG8_STAGE(PG8_SB(0, 1), b2 + hstepB, voffB); PG8_STAGE(PG8_SA(0, 0), a2, voffA);
;             PG8_WAIT_V(8); PG8_WAIT_L(0); PG8_BAR; PG8_MMA(1, 0, At, B0); PG8_MMA(1, 1, At, B1); PG8_BAR; PG8_SCHED;
.LBB0_589:
	s_add_u32 s54, s46, 0xfff80080
	s_addc_u32 s55, s47, -1
	s_add_i32 s88, 0, 0x10000
	s_cmp_eq_u32 s87, 28
	s_cselect_b32 s85, s0, s55
	s_cselect_b32 s84, s9, s54
	s_cselect_b32 s55, s11, s86
	s_cselect_b32 s54, s31, s39
	s_add_i32 s90, 0, 0x14000
	v_add_u32_e32 v154, s88, v163
	v_add_u32_e32 v175, s90, v163
	ds_read_b128 v[100:103], v154
	ds_read_b128 v[104:107], v154 offset:1024
	ds_read_b128 v[150:153], v154 offset:2048
	ds_read_b128 v[154:157], v154 offset:3072
	ds_read_b128 v[158:161], v175
	ds_read_b128 v[176:179], v175 offset:1024
	ds_read_b128 v[180:183], v175 offset:2048
	ds_read_b128 v[184:187], v175 offset:3072
	v_lshl_add_u64 v[210:211], s[46:47], 0, v[146:147]
	s_add_i32 m0, s5, 0xc000
	ds_read_b128 v[188:191], v174
	ds_read_b128 v[192:195], v174 offset:1024
	ds_read_b128 v[196:199], v174 offset:2048
	ds_read_b128 v[200:203], v174 offset:3072
	ds_read_b128 v[204:207], v174 offset:4096
	ds_read_b128 v[234:237], v174 offset:5120
	ds_read_b128 v[238:241], v174 offset:6144
	ds_read_b128 v[242:245], v174 offset:7168
	global_load_lds_dwordx4 v[210:211], off
	v_lshl_add_u64 v[210:211], s[46:47], 0, v[148:149]
	s_add_i32 m0, s5, 0xe000
	s_nop 0
	global_load_lds_dwordx4 v[210:211], off
	s_waitcnt vmcnt(8)
	s_waitcnt lgkmcnt(0)
	s_barrier
	s_waitcnt lgkmcnt(0)
	v_mfma_f32_16x16x32_bf16 v[136:139], v[100:103], v[188:191], v[136:139]
	v_mfma_f32_16x16x32_bf16 v[132:135], v[150:153], v[188:191], v[132:135]
	v_mfma_f32_16x16x32_bf16 v[128:131], v[100:103], v[196:199], v[128:131]
	v_mfma_f32_16x16x32_bf16 v[124:127], v[150:153], v[196:199], v[124:127]
	v_mfma_f32_16x16x32_bf16 v[120:123], v[100:103], v[204:207], v[120:123]
	v_mfma_f32_16x16x32_bf16 v[116:119], v[150:153], v[204:207], v[116:119]
	v_mfma_f32_16x16x32_bf16 v[112:115], v[100:103], v[238:241], v[112:115]
	v_mfma_f32_16x16x32_bf16 v[108:111], v[150:153], v[238:241], v[108:111]
	v_mfma_f32_16x16x32_bf16 v[136:139], v[104:107], v[192:195], v[136:139]
	v_mfma_f32_16x16x32_bf16 v[132:135], v[154:157], v[192:195], v[132:135]
	v_mfma_f32_16x16x32_bf16 v[128:131], v[104:107], v[200:203], v[128:131]
	v_mfma_f32_16x16x32_bf16 v[124:127], v[154:157], v[200:203], v[124:127]
	v_mfma_f32_16x16x32_bf16 v[120:123], v[104:107], v[234:237], v[120:123]
	v_mfma_f32_16x16x32_bf16 v[116:119], v[154:157], v[234:237], v[116:119]
	v_mfma_f32_16x16x32_bf16 v[112:115], v[104:107], v[242:245], v[112:115]
	v_mfma_f32_16x16x32_bf16 v[108:111], v[154:157], v[242:245], v[108:111]
	v_mfma_f32_16x16x32_bf16 v[64:67], v[158:161], v[188:191], v[64:67]
	v_mfma_f32_16x16x32_bf16 v[60:63], v[180:183], v[188:191], v[60:63]
	v_mfma_f32_16x16x32_bf16 v[56:59], v[158:161], v[196:199], v[56:59]
	v_mfma_f32_16x16x32_bf16 v[52:55], v[180:183], v[196:199], v[52:55]
	v_mfma_f32_16x16x32_bf16 v[48:51], v[158:161], v[204:207], v[48:51]
	v_mfma_f32_16x16x32_bf16 v[44:47], v[180:183], v[204:207], v[44:47]
	v_mfma_f32_16x16x32_bf16 v[40:43], v[158:161], v[238:241], v[40:43]
	v_mfma_f32_16x16x32_bf16 v[36:39], v[180:183], v[238:241], v[36:39]
	v_mfma_f32_16x16x32_bf16 v[64:67], v[176:179], v[192:195], v[64:67]
	v_mfma_f32_16x16x32_bf16 v[60:63], v[184:187], v[192:195], v[60:63]
	v_mfma_f32_16x16x32_bf16 v[56:59], v[176:179], v[200:203], v[56:59]
	v_mfma_f32_16x16x32_bf16 v[52:55], v[184:187], v[200:203], v[52:55]
	v_mfma_f32_16x16x32_bf16 v[48:51], v[176:179], v[234:237], v[48:51]
	v_mfma_f32_16x16x32_bf16 v[44:47], v[184:187], v[234:237], v[44:47]
	v_mfma_f32_16x16x32_bf16 v[40:43], v[176:179], v[242:245], v[40:43]
	v_mfma_f32_16x16x32_bf16 v[36:39], v[184:187], v[242:245], v[36:39]
	s_barrier
	s_add_i32 s88, s88, s1
	v_lshl_add_u64 v[210:211], s[54:55], 0, v[164:165]
	s_mov_b32 m0, s88
	ds_read_b128 v[188:191], v174 offset:16384
	ds_read_b128 v[192:195], v174 offset:17408
	ds_read_b128 v[196:199], v174 offset:18432
	ds_read_b128 v[200:203], v174 offset:19456
	ds_read_b128 v[204:207], v174 offset:20480
	ds_read_b128 v[234:237], v174 offset:21504
	ds_read_b128 v[238:241], v174 offset:22528
	ds_read_b128 v[242:245], v174 offset:23552
	global_load_lds_dwordx4 v[210:211], off
	s_add_i32 m0, s88, 0x2000
	s_add_u32 s88, s54, 0x80000
	v_lshl_add_u64 v[212:213], s[54:55], 0, v[144:145]
	s_addc_u32 s89, s55, 0
	s_add_i32 s90, s90, s1
	global_load_lds_dwordx4 v[212:213], off
	v_lshl_add_u64 v[220:221], s[88:89], 0, v[164:165]
	s_mov_b32 m0, s90
	v_lshl_add_u64 v[222:223], s[84:85], 0, v[142:143]
	global_load_lds_dwordx4 v[220:221], off
	v_lshl_add_u64 v[220:221], s[88:89], 0, v[144:145]
	s_add_i32 m0, s90, 0x2000
	s_nop 0
	global_load_lds_dwordx4 v[220:221], off
	v_lshl_add_u64 v[220:221], s[84:85], 0, v[140:141]
	s_mov_b32 m0, s5
	s_nop 0
	global_load_lds_dwordx4 v[220:221], off
	s_mov_b32 m0, s26
	s_nop 0
	global_load_lds_dwordx4 v[222:223], off
	s_waitcnt vmcnt(8)
	s_waitcnt lgkmcnt(0)
	s_barrier
; #define PG8_STAGE(bufoff, gbase, voff) do { _Pragma("unroll") for (int _i = 0; _i < 2; ++_i) \
;         __builtin_amdgcn_global_load_lds((const unsigned*)((const char*)(gbase) + (voff)[_i]), (LAS unsigned*)(lds + (bufoff) + ldsw + _i * 8192), 16, 0, 0); } while (0)
; #define PG8_LDA(dst, b, h) do { _Pragma("unroll") for (int m = 0; m < 4; ++m) _Pragma("unroll") for (int k = 0; k < 2; ++k) dst[m][k] = *(const LAS bf16x8*)(lds + PG8_SA(b, h) + aoff + m * 2048 + k * 1024); } while (0)
; #define PG8_LDB(dst, b, h) do { _Pragma("unroll") for (int n = 0; n < 2; ++n) _Pragma("unroll") for (int k = 0; k < 2; ++k) dst[n][k] = *(const LAS bf16x8*)(lds + PG8_SB(b, h) + boff + n * 2048 + k * 1024); } while (0)
; #define PG8_MMA(ai, bj, At, Bt) do { __builtin_amdgcn_s_setprio(1); _Pragma("unroll") for (int m = 0; m < 4; ++m) _Pragma("unroll") for (int n = 0; n < 2; ++n) _Pragma("unroll") for (int k = 0; k < 2; ++k) \
;         acc[ai][bj][m][n] = __builtin_amdgcn_mfma_f32_16x16x32_bf16(Bt[n][k], At[m][k], acc[ai][bj][m][n], 0, 0, 0); __builtin_amdgcn_s_setprio(0); } while (0)
; #define PG8_WAIT_V(n) asm volatile("s_waitcnt vmcnt(" #n ")" ::: "memory")
; #define PG8_WAIT_L(n) asm volatile("s_waitcnt lgkmcnt(" #n ")" ::: "memory")
; #define PG8_BAR __builtin_amdgcn_s_barrier()
; #define PG8_SCHED __builtin_amdgcn_sched_barrier(0)
; template <class Epi, class Sched>
; __device__ __forceinline__ void gemm_phase(LAS unsigned char* lds, const Gemm g, const Sched& S, const Epi& E, const int tid) {
;     ...
;             PG8_WAIT_V(8); PG8_WAIT_L(0); PG8_BAR; PG8_MMA(1, 0, At, B0); PG8_MMA(1, 1, At, B1); PG8_BAR; PG8_SCHED;
;             PG8_LDB(B0, 1, 0); PG8_LDB(B1, 1, 1); PG8_SCHED; PG8_LDA(At, 1, 0); PG8_STAGE(PG8_SA(0, 1), a2 + hstepA, voffA);
;             PG8_WAIT_V(8); PG8_WAIT_L(0); PG8_BAR; PG8_MMA(0, 0, At, B0); PG8_MMA(0, 1, At, B1); PG8_BAR; PG8_SCHED;
	s_waitcnt lgkmcnt(0)
	v_mfma_f32_16x16x32_bf16 v[96:99], v[100:103], v[188:191], v[96:99]
	v_mfma_f32_16x16x32_bf16 v[92:95], v[150:153], v[188:191], v[92:95]
	v_mfma_f32_16x16x32_bf16 v[88:91], v[100:103], v[196:199], v[88:91]
	v_mfma_f32_16x16x32_bf16 v[84:87], v[150:153], v[196:199], v[84:87]
	v_mfma_f32_16x16x32_bf16 v[80:83], v[100:103], v[204:207], v[80:83]
	v_mfma_f32_16x16x32_bf16 v[76:79], v[150:153], v[204:207], v[76:79]
	v_mfma_f32_16x16x32_bf16 v[72:75], v[100:103], v[238:241], v[72:75]
	v_mfma_f32_16x16x32_bf16 v[68:71], v[150:153], v[238:241], v[68:71]
	v_mfma_f32_16x16x32_bf16 v[96:99], v[104:107], v[192:195], v[96:99]
	v_mfma_f32_16x16x32_bf16 v[92:95], v[154:157], v[192:195], v[92:95]
	v_mfma_f32_16x16x32_bf16 v[88:91], v[104:107], v[200:203], v[88:91]
	v_mfma_f32_16x16x32_bf16 v[84:87], v[154:157], v[200:203], v[84:87]
	v_mfma_f32_16x16x32_bf16 v[80:83], v[104:107], v[234:237], v[80:83]
	v_mfma_f32_16x16x32_bf16 v[76:79], v[154:157], v[234:237], v[76:79]
	v_mfma_f32_16x16x32_bf16 v[72:75], v[104:107], v[242:245], v[72:75]
	v_mfma_f32_16x16x32_bf16 v[68:71], v[154:157], v[242:245], v[68:71]
	v_mfma_f32_16x16x32_bf16 v[32:35], v[158:161], v[188:191], v[32:35]
	v_mfma_f32_16x16x32_bf16 v[28:31], v[180:183], v[188:191], v[28:31]
	v_mfma_f32_16x16x32_bf16 v[24:27], v[158:161], v[196:199], v[24:27]
	v_mfma_f32_16x16x32_bf16 v[20:23], v[180:183], v[196:199], v[20:23]
	v_mfma_f32_16x16x32_bf16 v[16:19], v[158:161], v[204:207], v[16:19]
	v_mfma_f32_16x16x32_bf16 v[12:15], v[180:183], v[204:207], v[12:15]
	v_mfma_f32_16x16x32_bf16 v[8:11], v[158:161], v[238:241], v[8:11]
	v_mfma_f32_16x16x32_bf16 v[4:7], v[180:183], v[238:241], v[4:7]
	v_mfma_f32_16x16x32_bf16 v[32:35], v[176:179], v[192:195], v[32:35]
	v_mfma_f32_16x16x32_bf16 v[28:31], v[184:187], v[192:195], v[28:31]
	v_mfma_f32_16x16x32_bf16 v[24:27], v[176:179], v[200:203], v[24:27]
	v_mfma_f32_16x16x32_bf16 v[20:23], v[184:187], v[200:203], v[20:23]
	v_mfma_f32_16x16x32_bf16 v[16:19], v[176:179], v[234:237], v[16:19]
	v_mfma_f32_16x16x32_bf16 v[12:15], v[184:187], v[234:237], v[12:15]
	v_mfma_f32_16x16x32_bf16 v[8:11], v[176:179], v[242:245], v[8:11]
	v_mfma_f32_16x16x32_bf16 v[4:7], v[184:187], v[242:245], v[4:7]
	s_barrier
	s_add_i32 s88, 0, 0x18000
	s_add_i32 s89, 0, 0x1c000
	v_add_u32_e32 v154, s88, v163
	v_add_u32_e32 v175, s89, v163
	ds_read_b128 v[100:103], v154
	ds_read_b128 v[104:107], v154 offset:1024
	ds_read_b128 v[150:153], v154 offset:2048
	ds_read_b128 v[154:157], v154 offset:3072
	ds_read_b128 v[158:161], v175
	ds_read_b128 v[176:179], v175 offset:1024
	ds_read_b128 v[180:183], v175 offset:2048
	ds_read_b128 v[184:187], v175 offset:3072
	s_add_u32 s84, s84, 0x80000
	s_addc_u32 s85, s85, 0
	s_mov_b32 m0, s56
	v_lshl_add_u64 v[246:247], s[84:85], 0, v[140:141]
	ds_read_b128 v[188:191], v174 offset:32768
	ds_read_b128 v[192:195], v174 offset:33792
	ds_read_b128 v[196:199], v174 offset:34816
	ds_read_b128 v[200:203], v174 offset:35840
	ds_read_b128 v[204:207], v174 offset:36864
	ds_read_b128 v[234:237], v174 offset:37888
	ds_read_b128 v[238:241], v174 offset:38912
	ds_read_b128 v[242:245], v174 offset:39936
	global_load_lds_dwordx4 v[246:247], off
	v_lshl_add_u64 v[246:247], s[84:85], 0, v[142:143]
	s_mov_b32 m0, s57
	s_nop 0
	global_load_lds_dwordx4 v[246:247], off
	s_waitcnt vmcnt(8)
	s_waitcnt lgkmcnt(0)
	s_barrier
	s_waitcnt lgkmcnt(0)
	v_mfma_f32_16x16x32_bf16 v[136:139], v[100:103], v[188:191], v[136:139]
	v_mfma_f32_16x16x32_bf16 v[132:135], v[150:153], v[188:191], v[132:135]
	v_mfma_f32_16x16x32_bf16 v[128:131], v[100:103], v[196:199], v[128:131]
	v_mfma_f32_16x16x32_bf16 v[124:127], v[150:153], v[196:199], v[124:127]
	v_mfma_f32_16x16x32_bf16 v[120:123], v[100:103], v[204:207], v[120:123]
	v_mfma_f32_16x16x32_bf16 v[116:119], v[150:153], v[204:207], v[116:119]
	v_mfma_f32_16x16x32_bf16 v[112:115], v[100:103], v[238:241], v[112:115]
	v_mfma_f32_16x16x32_bf16 v[108:111], v[150:153], v[238:241], v[108:111]
	v_mfma_f32_16x16x32_bf16 v[136:139], v[104:107], v[192:195], v[136:139]
	v_mfma_f32_16x16x32_bf16 v[132:135], v[154:157], v[192:195], v[132:135]
	v_mfma_f32_16x16x32_bf16 v[128:131], v[104:107], v[200:203], v[128:131]
	v_mfma_f32_16x16x32_bf16 v[124:127], v[154:157], v[200:203], v[124:127]
	v_mfma_f32_16x16x32_bf16 v[120:123], v[104:107], v[234:237], v[120:123]
	v_mfma_f32_16x16x32_bf16 v[116:119], v[154:157], v[234:237], v[116:119]
	v_mfma_f32_16x16x32_bf16 v[112:115], v[104:107], v[242:245], v[112:115]
	v_mfma_f32_16x16x32_bf16 v[108:111], v[154:157], v[242:245], v[108:111]
	v_mfma_f32_16x16x32_bf16 v[64:67], v[158:161], v[188:191], v[64:67]
	v_mfma_f32_16x16x32_bf16 v[60:63], v[180:183], v[188:191], v[60:63]
	v_mfma_f32_16x16x32_bf16 v[56:59], v[158:161], v[196:199], v[56:59]
	v_mfma_f32_16x16x32_bf16 v[52:55], v[180:183], v[196:199], v[52:55]
	v_mfma_f32_16x16x32_bf16 v[48:51], v[158:161], v[204:207], v[48:51]
	v_mfma_f32_16x16x32_bf16 v[44:47], v[180:183], v[204:207], v[44:47]
	v_mfma_f32_16x16x32_bf16 v[40:43], v[158:161], v[238:241], v[40:43]
	v_mfma_f32_16x16x32_bf16 v[36:39], v[180:183], v[238:241], v[36:39]
	v_mfma_f32_16x16x32_bf16 v[64:67], v[176:179], v[192:195], v[64:67]
	v_mfma_f32_16x16x32_bf16 v[60:63], v[184:187], v[192:195], v[60:63]
	v_mfma_f32_16x16x32_bf16 v[56:59], v[176:179], v[200:203], v[56:59]
	v_mfma_f32_16x16x32_bf16 v[52:55], v[184:187], v[200:203], v[52:55]
	v_mfma_f32_16x16x32_bf16 v[48:51], v[176:179], v[234:237], v[48:51]
	v_mfma_f32_16x16x32_bf16 v[44:47], v[184:187], v[234:237], v[44:47]
	v_mfma_f32_16x16x32_bf16 v[40:43], v[176:179], v[242:245], v[40:43]
	v_mfma_f32_16x16x32_bf16 v[36:39], v[184:187], v[242:245], v[36:39]
	s_barrier
; #define PG8_STAGE(bufoff, gbase, voff) do { _Pragma("unroll") for (int _i = 0; _i < 2; ++_i) \
;         __builtin_amdgcn_global_load_lds((const unsigned*)((const char*)(gbase) + (voff)[_i]), (LAS unsigned*)(lds + (bufoff) + ldsw + _i * 8192), 16, 0, 0); } while (0)
; #define PG8_LDA(dst, b, h) do { _Pragma("unroll") for (int m = 0; m < 4; ++m) _Pragma("unroll") for (int k = 0; k < 2; ++k) dst[m][k] = *(const LAS bf16x8*)(lds + PG8_SA(b, h) + aoff + m * 2048 + k * 1024); } while (0)
; #define PG8_MMA(ai, bj, At, Bt) do { __builtin_amdgcn_s_setprio(1); _Pragma("unroll") for (int m = 0; m < 4; ++m) _Pragma("unroll") for (int n = 0; n < 2; ++n) _Pragma("unroll") for (int k = 0; k < 2; ++k) \
;         acc[ai][bj][m][n] = __builtin_amdgcn_mfma_f32_16x16x32_bf16(Bt[n][k], At[m][k], acc[ai][bj][m][n], 0, 0, 0); __builtin_amdgcn_s_setprio(0); } while (0)
; #define PG8_WAIT_V(n) asm volatile("s_waitcnt vmcnt(" #n ")" ::: "memory")
; #define PG8_WAIT_L(n) asm volatile("s_waitcnt lgkmcnt(" #n ")" ::: "memory")
; #define PG8_BAR __builtin_amdgcn_s_barrier()
; #define PG8_SCHED __builtin_amdgcn_sched_barrier(0)
; template <class Epi, class Sched>
; __device__ __forceinline__ void gemm_phase(LAS unsigned char* lds, const Gemm g, const Sched& S, const Epi& E, const int tid) {
;     ...
;             PG8_LDA(At, 1, 1); PG8_STAGE(PG8_SB(1, 0), b3, voffB); PG8_STAGE(PG8_SB(1, 1), b3 + hstepB, voffB); PG8_STAGE(PG8_SA(1, 0), a3, voffA);
;             PG8_WAIT_V(8); PG8_WAIT_L(0); PG8_BAR; PG8_MMA(1, 0, At, B0); PG8_MMA(1, 1, At, B1); PG8_BAR; PG8_SCHED;
;         }
;         if (wr == 0) PG8_BAR;
	s_add_i32 s84, s88, s1
	v_lshl_add_u64 v[210:211], v[210:211], 0, s[28:29]
	s_mov_b32 m0, s84
	ds_read_b128 v[188:191], v174 offset:49152
	ds_read_b128 v[192:195], v174 offset:50176
	ds_read_b128 v[196:199], v174 offset:51200
	ds_read_b128 v[200:203], v174 offset:52224
	ds_read_b128 v[204:207], v174 offset:53248
	ds_read_b128 v[234:237], v174 offset:54272
	ds_read_b128 v[238:241], v174 offset:55296
	ds_read_b128 v[242:245], v174 offset:56320
	global_load_lds_dwordx4 v[210:211], off
	s_add_i32 m0, s84, 0x2000
	s_add_u32 s54, s54, 0x80080
	v_lshl_add_u64 v[210:211], v[212:213], 0, s[28:29]
	s_addc_u32 s55, s55, 0
	s_add_i32 s84, s89, s1
	global_load_lds_dwordx4 v[210:211], off
	v_lshl_add_u64 v[210:211], s[54:55], 0, v[164:165]
	s_mov_b32 m0, s84
	s_nop 0
	global_load_lds_dwordx4 v[210:211], off
	v_lshl_add_u64 v[210:211], s[54:55], 0, v[144:145]
	s_add_i32 m0, s84, 0x2000
	s_nop 0
	global_load_lds_dwordx4 v[210:211], off
	v_lshl_add_u64 v[210:211], v[220:221], 0, s[28:29]
	s_mov_b32 m0, s58
	s_nop 0
	global_load_lds_dwordx4 v[210:211], off
	v_lshl_add_u64 v[210:211], v[222:223], 0, s[28:29]
	s_mov_b32 m0, s59
	s_nop 0
	global_load_lds_dwordx4 v[210:211], off
	s_waitcnt vmcnt(8)
	s_waitcnt lgkmcnt(0)
	s_barrier
	s_waitcnt lgkmcnt(0)
	v_mfma_f32_16x16x32_bf16 v[96:99], v[100:103], v[188:191], v[96:99]
	v_mfma_f32_16x16x32_bf16 v[92:95], v[150:153], v[188:191], v[92:95]
	v_mfma_f32_16x16x32_bf16 v[88:91], v[100:103], v[196:199], v[88:91]
	v_mfma_f32_16x16x32_bf16 v[84:87], v[150:153], v[196:199], v[84:87]
	v_mfma_f32_16x16x32_bf16 v[80:83], v[100:103], v[204:207], v[80:83]
	v_mfma_f32_16x16x32_bf16 v[76:79], v[150:153], v[204:207], v[76:79]
	v_mfma_f32_16x16x32_bf16 v[72:75], v[100:103], v[238:241], v[72:75]
	v_mfma_f32_16x16x32_bf16 v[68:71], v[150:153], v[238:241], v[68:71]
	v_mfma_f32_16x16x32_bf16 v[96:99], v[104:107], v[192:195], v[96:99]
	v_mfma_f32_16x16x32_bf16 v[92:95], v[154:157], v[192:195], v[92:95]
	v_mfma_f32_16x16x32_bf16 v[88:91], v[104:107], v[200:203], v[88:91]
	v_mfma_f32_16x16x32_bf16 v[84:87], v[154:157], v[200:203], v[84:87]
	v_mfma_f32_16x16x32_bf16 v[80:83], v[104:107], v[234:237], v[80:83]
	v_mfma_f32_16x16x32_bf16 v[76:79], v[154:157], v[234:237], v[76:79]
	v_mfma_f32_16x16x32_bf16 v[72:75], v[104:107], v[242:245], v[72:75]
	v_mfma_f32_16x16x32_bf16 v[68:71], v[154:157], v[242:245], v[68:71]
	v_mfma_f32_16x16x32_bf16 v[32:35], v[158:161], v[188:191], v[32:35]
	v_mfma_f32_16x16x32_bf16 v[28:31], v[180:183], v[188:191], v[28:31]
	v_mfma_f32_16x16x32_bf16 v[24:27], v[158:161], v[196:199], v[24:27]
	v_mfma_f32_16x16x32_bf16 v[20:23], v[180:183], v[196:199], v[20:23]
	v_mfma_f32_16x16x32_bf16 v[16:19], v[158:161], v[204:207], v[16:19]
	v_mfma_f32_16x16x32_bf16 v[12:15], v[180:183], v[204:207], v[12:15]
	v_mfma_f32_16x16x32_bf16 v[8:11], v[158:161], v[238:241], v[8:11]
	v_mfma_f32_16x16x32_bf16 v[4:7], v[180:183], v[238:241], v[4:7]
	v_mfma_f32_16x16x32_bf16 v[32:35], v[176:179], v[192:195], v[32:35]
	v_mfma_f32_16x16x32_bf16 v[28:31], v[184:187], v[192:195], v[28:31]
	v_mfma_f32_16x16x32_bf16 v[24:27], v[176:179], v[200:203], v[24:27]
	v_mfma_f32_16x16x32_bf16 v[20:23], v[184:187], v[200:203], v[20:23]
	v_mfma_f32_16x16x32_bf16 v[16:19], v[176:179], v[234:237], v[16:19]
	v_mfma_f32_16x16x32_bf16 v[12:15], v[184:187], v[234:237], v[12:15]
	v_mfma_f32_16x16x32_bf16 v[8:11], v[176:179], v[242:245], v[8:11]
	v_mfma_f32_16x16x32_bf16 v[4:7], v[184:187], v[242:245], v[4:7]
	s_barrier
	s_add_i32 s87, s87, 2
	s_add_u32 s46, s46, 0x100
	s_addc_u32 s47, s47, 0
	s_add_u32 s39, s39, 0x100
	s_addc_u32 s86, s86, 0
	s_cmp_gt_u32 s87, 29
	s_cbranch_scc0 .LBB0_589
	s_setprio 0
	s_and_b64 vcc, exec, s[16:17]
	s_cbranch_vccz .LBB0_592
	s_barrier
